# K-loop barrier hand-off: s_setprio 0 moved after the post-MFMA barrier, s_setprio 1 moved before the pre-MFMA barrier and the redundant lgkmcnt(0) dropped, so the barrier is signalled right after the
# speedup vs baseline: 1.0074x; 1.0074x over previous
; #define PG8_STAGE(bufoff, gbase, voff) do { _Pragma("unroll") for (int _i = 0; _i < 2; ++_i) \
;         __builtin_amdgcn_global_load_lds((const unsigned*)((const char*)(gbase) + (voff)[_i]), (LAS unsigned*)(lds + (bufoff) + ldsw + _i * 8192), 16, 0, 0); } while (0)
; #define PG8_LDA(dst, b, h) do { _Pragma("unroll") for (int m = 0; m < 4; ++m) _Pragma("unroll") for (int k = 0; k < 2; ++k) dst[m][k] = *(const LAS bf16x8*)(lds + PG8_SA(b, h) + aoff + m * 2048 + k * 1024); } while (0)
; #define PG8_LDB(dst, b, h) do { _Pragma("unroll") for (int n = 0; n < 2; ++n) _Pragma("unroll") for (int k = 0; k < 2; ++k) dst[n][k] = *(const LAS bf16x8*)(lds + PG8_SB(b, h) + boff + n * 2048 + k * 1024); } while (0)
; #define PG8_MMA(ai, bj, At, Bt) do { __builtin_amdgcn_s_setprio(1); _Pragma("unroll") for (int m = 0; m < 4; ++m) _Pragma("unroll") for (int n = 0; n < 2; ++n) _Pragma("unroll") for (int k = 0; k < 2; ++k) \
;         acc[ai][bj][m][n] = __builtin_amdgcn_mfma_f32_16x16x32_bf16(Bt[n][k], At[m][k], acc[ai][bj][m][n], 0, 0, 0); __builtin_amdgcn_s_setprio(0); } while (0)
; #define PG8_WAIT_V(n) asm volatile("s_waitcnt vmcnt(" #n ")" ::: "memory")
; #define PG8_WAIT_L(n) asm volatile("s_waitcnt lgkmcnt(" #n ")" ::: "memory")
; #define PG8_BAR __builtin_amdgcn_s_barrier()
; #define PG8_SCHED __builtin_amdgcn_sched_barrier(0)
; template <class Epi>
; __device__ __forceinline__ void gemm_phase(LAS unsigned char* lds, const GemmD g, const Epi& E, int G, int c) {
;     ...
;         for (int t = 0; t < nt; t += 2) {
;             const bool last = (t == nt - 2);
;             const char* a1 = cA + (size_t)(t + 1) * kstep;
;             const char* a2 = last ? nA : cA + (size_t)(t + 2) * kstep; const char* b2 = last ? nB : cB + (size_t)(t + 2) * kstep;
;             const char* a3 = a2 + kstep; const char* b3 = b2 + kstep;
;             PG8_LDB(B0, 0, 0); PG8_LDB(B1, 0, 1); PG8_SCHED; PG8_LDA(At, 0, 0); PG8_STAGE(PG8_SA(1, 1), a1 + hstepA, voffA);
;             PG8_WAIT_V(8); PG8_WAIT_L(0); PG8_BAR; PG8_MMA(0, 0, At, B0); PG8_MMA(0, 1, At, B1); PG8_BAR; PG8_SCHED;
;             PG8_LDA(At, 0, 1); PG8_STAGE(PG8_SB(0, 0), b2, voffB); PG8_STAGE(PG8_SB(0, 1), b2 + hstepB, voffB); PG8_STAGE(PG8_SA(0, 0), a2, voffA);
;             PG8_WAIT_V(8); PG8_WAIT_L(0); PG8_BAR; PG8_MMA(1, 0, At, B0); PG8_MMA(1, 1, At, B1); PG8_BAR; PG8_SCHED;
.LBB0_106:
	s_add_u32 s88, s46, 0x100
	s_addc_u32 s89, s47, 0
	s_add_i32 s31, 0, 0x10000
	s_cmpk_eq_i32 s30, 0x54
	s_cselect_b32 s5, s85, s89
	s_cselect_b32 s4, s84, s88
	v_add_u32_e32 v153, s31, v149
	s_cselect_b32 s91, s87, s29
	s_cselect_b32 s90, s86, s28
	s_add_i32 s33, 0, 0x14000
	ds_read_b128 v[140:143], v153
	ds_read_b128 v[144:147], v153 offset:1024
	ds_read_b128 v[154:157], v153 offset:2048
	ds_read_b128 v[158:161], v153 offset:3072
	v_add_u32_e32 v153, s33, v149
	ds_read_b128 v[162:165], v153
	ds_read_b128 v[166:169], v153 offset:1024
	ds_read_b128 v[170:173], v153 offset:2048
	ds_read_b128 v[180:183], v153 offset:3072
	v_lshl_add_u64 v[174:175], s[46:47], 0, v[136:137]
	s_add_i32 m0, s6, 0xc000
	ds_read_b128 v[184:187], v151
	ds_read_b128 v[188:191], v151 offset:1024
	ds_read_b128 v[192:195], v151 offset:2048
	ds_read_b128 v[210:213], v151 offset:3072
	ds_read_b128 v[214:217], v151 offset:4096
	ds_read_b128 v[218:221], v151 offset:5120
	ds_read_b128 v[222:225], v151 offset:6144
	ds_read_b128 v[226:229], v151 offset:7168
	global_load_lds_dwordx4 v[174:175], off
	v_lshl_add_u64 v[174:175], s[46:47], 0, v[138:139]
	s_add_i32 m0, s6, 0xe000
	s_nop 0
	global_load_lds_dwordx4 v[174:175], off
	s_waitcnt vmcnt(8)
	s_waitcnt lgkmcnt(0)
	s_setprio 1
	s_barrier
	v_mfma_f32_16x16x32_bf16 v[124:127], v[140:143], v[184:187], v[124:127]
	v_mfma_f32_16x16x32_bf16 v[116:119], v[154:157], v[184:187], v[116:119]
	v_mfma_f32_16x16x32_bf16 v[104:107], v[140:143], v[192:195], v[104:107]
	v_mfma_f32_16x16x32_bf16 v[96:99], v[154:157], v[192:195], v[96:99]
	v_mfma_f32_16x16x32_bf16 v[88:91], v[140:143], v[214:217], v[88:91]
	v_mfma_f32_16x16x32_bf16 v[80:83], v[154:157], v[214:217], v[80:83]
	v_mfma_f32_16x16x32_bf16 v[72:75], v[140:143], v[222:225], v[72:75]
	v_mfma_f32_16x16x32_bf16 v[64:67], v[154:157], v[222:225], v[64:67]
	v_mfma_f32_16x16x32_bf16 v[124:127], v[144:147], v[188:191], v[124:127]
	v_mfma_f32_16x16x32_bf16 v[116:119], v[158:161], v[188:191], v[116:119]
	v_mfma_f32_16x16x32_bf16 v[104:107], v[144:147], v[210:213], v[104:107]
	v_mfma_f32_16x16x32_bf16 v[96:99], v[158:161], v[210:213], v[96:99]
	v_mfma_f32_16x16x32_bf16 v[88:91], v[144:147], v[218:221], v[88:91]
	v_mfma_f32_16x16x32_bf16 v[80:83], v[158:161], v[218:221], v[80:83]
	v_mfma_f32_16x16x32_bf16 v[72:75], v[144:147], v[226:229], v[72:75]
	v_mfma_f32_16x16x32_bf16 v[64:67], v[158:161], v[226:229], v[64:67]
	s_setprio 0
	s_setprio 1
	v_mfma_f32_16x16x32_bf16 v[120:123], v[162:165], v[184:187], v[120:123]
	v_mfma_f32_16x16x32_bf16 v[112:115], v[170:173], v[184:187], v[112:115]
	v_mfma_f32_16x16x32_bf16 v[108:111], v[162:165], v[192:195], v[108:111]
	v_mfma_f32_16x16x32_bf16 v[100:103], v[170:173], v[192:195], v[100:103]
	v_mfma_f32_16x16x32_bf16 v[92:95], v[162:165], v[214:217], v[92:95]
	v_mfma_f32_16x16x32_bf16 v[84:87], v[170:173], v[214:217], v[84:87]
	v_mfma_f32_16x16x32_bf16 v[76:79], v[162:165], v[222:225], v[76:79]
	v_mfma_f32_16x16x32_bf16 v[68:71], v[170:173], v[222:225], v[68:71]
	v_mfma_f32_16x16x32_bf16 v[120:123], v[166:169], v[188:191], v[120:123]
	v_mfma_f32_16x16x32_bf16 v[112:115], v[180:183], v[188:191], v[112:115]
	v_mfma_f32_16x16x32_bf16 v[108:111], v[166:169], v[210:213], v[108:111]
	v_mfma_f32_16x16x32_bf16 v[100:103], v[180:183], v[210:213], v[100:103]
	v_mfma_f32_16x16x32_bf16 v[92:95], v[166:169], v[218:221], v[92:95]
	v_mfma_f32_16x16x32_bf16 v[84:87], v[180:183], v[218:221], v[84:87]
	v_mfma_f32_16x16x32_bf16 v[76:79], v[166:169], v[226:229], v[76:79]
	v_mfma_f32_16x16x32_bf16 v[68:71], v[180:183], v[226:229], v[68:71]
	s_barrier
	s_setprio 0
	s_add_i32 s31, s31, s2
	v_lshl_add_u64 v[174:175], s[90:91], 0, v[178:179]
	s_mov_b32 m0, s31
	ds_read_b128 v[184:187], v151 offset:16384
	ds_read_b128 v[188:191], v151 offset:17408
	ds_read_b128 v[192:195], v151 offset:18432
	ds_read_b128 v[210:213], v151 offset:19456
	ds_read_b128 v[214:217], v151 offset:20480
	ds_read_b128 v[218:221], v151 offset:21504
	ds_read_b128 v[222:225], v151 offset:22528
	ds_read_b128 v[226:229], v151 offset:23552
	global_load_lds_dwordx4 v[174:175], off
	s_add_i32 m0, s31, 0x2000
	s_add_u32 s38, s90, 0x160000
	v_lshl_add_u64 v[198:199], s[90:91], 0, v[128:129]
	s_addc_u32 s39, s91, 0
	s_add_i32 s31, s33, s2
	global_load_lds_dwordx4 v[198:199], off
	v_lshl_add_u64 v[230:231], s[38:39], 0, v[178:179]
	s_mov_b32 m0, s31
	v_lshl_add_u64 v[232:233], s[4:5], 0, v[130:131]
	global_load_lds_dwordx4 v[230:231], off
	v_lshl_add_u64 v[230:231], s[38:39], 0, v[128:129]
	s_add_i32 m0, s31, 0x2000
	s_nop 0
	global_load_lds_dwordx4 v[230:231], off
	v_lshl_add_u64 v[230:231], s[4:5], 0, v[132:133]
	s_mov_b32 m0, s6
	s_nop 0
	global_load_lds_dwordx4 v[230:231], off
	s_mov_b32 m0, s9
	s_nop 0
	global_load_lds_dwordx4 v[232:233], off
	s_waitcnt vmcnt(8)
	s_waitcnt lgkmcnt(0)
	s_setprio 1
	s_barrier
; #define PG8_STAGE(bufoff, gbase, voff) do { _Pragma("unroll") for (int _i = 0; _i < 2; ++_i) \
;         __builtin_amdgcn_global_load_lds((const unsigned*)((const char*)(gbase) + (voff)[_i]), (LAS unsigned*)(lds + (bufoff) + ldsw + _i * 8192), 16, 0, 0); } while (0)
; #define PG8_LDA(dst, b, h) do { _Pragma("unroll") for (int m = 0; m < 4; ++m) _Pragma("unroll") for (int k = 0; k < 2; ++k) dst[m][k] = *(const LAS bf16x8*)(lds + PG8_SA(b, h) + aoff + m * 2048 + k * 1024); } while (0)
; #define PG8_LDB(dst, b, h) do { _Pragma("unroll") for (int n = 0; n < 2; ++n) _Pragma("unroll") for (int k = 0; k < 2; ++k) dst[n][k] = *(const LAS bf16x8*)(lds + PG8_SB(b, h) + boff + n * 2048 + k * 1024); } while (0)
; #define PG8_MMA(ai, bj, At, Bt) do { __builtin_amdgcn_s_setprio(1); _Pragma("unroll") for (int m = 0; m < 4; ++m) _Pragma("unroll") for (int n = 0; n < 2; ++n) _Pragma("unroll") for (int k = 0; k < 2; ++k) \
;         acc[ai][bj][m][n] = __builtin_amdgcn_mfma_f32_16x16x32_bf16(Bt[n][k], At[m][k], acc[ai][bj][m][n], 0, 0, 0); __builtin_amdgcn_s_setprio(0); } while (0)
; #define PG8_WAIT_V(n) asm volatile("s_waitcnt vmcnt(" #n ")" ::: "memory")
; #define PG8_WAIT_L(n) asm volatile("s_waitcnt lgkmcnt(" #n ")" ::: "memory")
; #define PG8_BAR __builtin_amdgcn_s_barrier()
; #define PG8_SCHED __builtin_amdgcn_sched_barrier(0)
; template <class Epi>
; __device__ __forceinline__ void gemm_phase(LAS unsigned char* lds, const GemmD g, const Epi& E, int G, int c) {
;     ...
;             PG8_WAIT_V(8); PG8_WAIT_L(0); PG8_BAR; PG8_MMA(1, 0, At, B0); PG8_MMA(1, 1, At, B1); PG8_BAR; PG8_SCHED;
;             PG8_LDB(B0, 1, 0); PG8_LDB(B1, 1, 1); PG8_SCHED; PG8_LDA(At, 1, 0); PG8_STAGE(PG8_SA(0, 1), a2 + hstepA, voffA);
;             PG8_WAIT_V(8); PG8_WAIT_L(0); PG8_BAR; PG8_MMA(0, 0, At, B0); PG8_MMA(0, 1, At, B1); PG8_BAR; PG8_SCHED;
	v_mfma_f32_16x16x32_bf16 v[52:55], v[140:143], v[184:187], v[52:55]
	v_mfma_f32_16x16x32_bf16 v[56:59], v[154:157], v[184:187], v[56:59]
	v_mfma_f32_16x16x32_bf16 v[40:43], v[140:143], v[192:195], v[40:43]
	v_mfma_f32_16x16x32_bf16 v[32:35], v[154:157], v[192:195], v[32:35]
	v_mfma_f32_16x16x32_bf16 v[20:23], v[140:143], v[214:217], v[20:23]
	v_mfma_f32_16x16x32_bf16 v[16:19], v[154:157], v[214:217], v[16:19]
	v_mfma_f32_16x16x32_bf16 v[4:7], v[140:143], v[222:225], v[4:7]
	v_mfma_f32_16x16x32_bf16 v[0:3], v[154:157], v[222:225], v[0:3]
	v_mfma_f32_16x16x32_bf16 v[52:55], v[144:147], v[188:191], v[52:55]
	v_mfma_f32_16x16x32_bf16 v[56:59], v[158:161], v[188:191], v[56:59]
	v_mfma_f32_16x16x32_bf16 v[40:43], v[144:147], v[210:213], v[40:43]
	v_mfma_f32_16x16x32_bf16 v[32:35], v[158:161], v[210:213], v[32:35]
	v_mfma_f32_16x16x32_bf16 v[20:23], v[144:147], v[218:221], v[20:23]
	v_mfma_f32_16x16x32_bf16 v[16:19], v[158:161], v[218:221], v[16:19]
	v_mfma_f32_16x16x32_bf16 v[4:7], v[144:147], v[226:229], v[4:7]
	v_mfma_f32_16x16x32_bf16 v[0:3], v[158:161], v[226:229], v[0:3]
	s_setprio 0
	s_setprio 1
	v_mfma_f32_16x16x32_bf16 v[60:63], v[162:165], v[184:187], v[60:63]
	v_mfma_f32_16x16x32_bf16 v[48:51], v[170:173], v[184:187], v[48:51]
	v_mfma_f32_16x16x32_bf16 v[44:47], v[162:165], v[192:195], v[44:47]
	v_mfma_f32_16x16x32_bf16 v[36:39], v[170:173], v[192:195], v[36:39]
	v_mfma_f32_16x16x32_bf16 v[28:31], v[162:165], v[214:217], v[28:31]
	v_mfma_f32_16x16x32_bf16 v[24:27], v[170:173], v[214:217], v[24:27]
	v_mfma_f32_16x16x32_bf16 v[12:15], v[162:165], v[222:225], v[12:15]
	v_mfma_f32_16x16x32_bf16 v[8:11], v[170:173], v[222:225], v[8:11]
	v_mfma_f32_16x16x32_bf16 v[60:63], v[166:169], v[188:191], v[60:63]
	v_mfma_f32_16x16x32_bf16 v[48:51], v[180:183], v[188:191], v[48:51]
	v_mfma_f32_16x16x32_bf16 v[44:47], v[166:169], v[210:213], v[44:47]
	v_mfma_f32_16x16x32_bf16 v[36:39], v[180:183], v[210:213], v[36:39]
	v_mfma_f32_16x16x32_bf16 v[28:31], v[166:169], v[218:221], v[28:31]
	v_mfma_f32_16x16x32_bf16 v[24:27], v[180:183], v[218:221], v[24:27]
	v_mfma_f32_16x16x32_bf16 v[12:15], v[166:169], v[226:229], v[12:15]
	v_mfma_f32_16x16x32_bf16 v[8:11], v[180:183], v[226:229], v[8:11]
	s_barrier
	s_setprio 0
	s_add_i32 s31, 0, 0x18000
	v_add_u32_e32 v153, s31, v149
	s_add_i32 s33, 0, 0x1c000
	ds_read_b128 v[140:143], v153
	ds_read_b128 v[144:147], v153 offset:1024
	ds_read_b128 v[154:157], v153 offset:2048
	ds_read_b128 v[158:161], v153 offset:3072
	v_add_u32_e32 v153, s33, v149
	ds_read_b128 v[162:165], v153
	ds_read_b128 v[166:169], v153 offset:1024
	ds_read_b128 v[170:173], v153 offset:2048
	ds_read_b128 v[180:183], v153 offset:3072
	s_add_u32 s4, s4, 0x160000
	s_addc_u32 s5, s5, 0
	s_mov_b32 m0, s10
	v_lshl_add_u64 v[234:235], s[4:5], 0, v[132:133]
	ds_read_b128 v[184:187], v151 offset:32768
	ds_read_b128 v[188:191], v151 offset:33792
	ds_read_b128 v[192:195], v151 offset:34816
	ds_read_b128 v[210:213], v151 offset:35840
	ds_read_b128 v[214:217], v151 offset:36864
	ds_read_b128 v[218:221], v151 offset:37888
	ds_read_b128 v[222:225], v151 offset:38912
	ds_read_b128 v[226:229], v151 offset:39936
	global_load_lds_dwordx4 v[234:235], off
	v_lshl_add_u64 v[234:235], s[4:5], 0, v[130:131]
	s_mov_b32 m0, s11
	s_nop 0
	global_load_lds_dwordx4 v[234:235], off
	s_waitcnt vmcnt(8)
	s_waitcnt lgkmcnt(0)
	s_setprio 1
	s_barrier
	v_mfma_f32_16x16x32_bf16 v[124:127], v[140:143], v[184:187], v[124:127]
	v_mfma_f32_16x16x32_bf16 v[116:119], v[154:157], v[184:187], v[116:119]
	v_mfma_f32_16x16x32_bf16 v[104:107], v[140:143], v[192:195], v[104:107]
	v_mfma_f32_16x16x32_bf16 v[96:99], v[154:157], v[192:195], v[96:99]
	v_mfma_f32_16x16x32_bf16 v[88:91], v[140:143], v[214:217], v[88:91]
	v_mfma_f32_16x16x32_bf16 v[80:83], v[154:157], v[214:217], v[80:83]
	v_mfma_f32_16x16x32_bf16 v[72:75], v[140:143], v[222:225], v[72:75]
	v_mfma_f32_16x16x32_bf16 v[64:67], v[154:157], v[222:225], v[64:67]
	v_mfma_f32_16x16x32_bf16 v[124:127], v[144:147], v[188:191], v[124:127]
	v_mfma_f32_16x16x32_bf16 v[116:119], v[158:161], v[188:191], v[116:119]
	v_mfma_f32_16x16x32_bf16 v[104:107], v[144:147], v[210:213], v[104:107]
	v_mfma_f32_16x16x32_bf16 v[96:99], v[158:161], v[210:213], v[96:99]
	v_mfma_f32_16x16x32_bf16 v[88:91], v[144:147], v[218:221], v[88:91]
	v_mfma_f32_16x16x32_bf16 v[80:83], v[158:161], v[218:221], v[80:83]
	v_mfma_f32_16x16x32_bf16 v[72:75], v[144:147], v[226:229], v[72:75]
	v_mfma_f32_16x16x32_bf16 v[64:67], v[158:161], v[226:229], v[64:67]
	s_setprio 0
	s_setprio 1
	v_mfma_f32_16x16x32_bf16 v[120:123], v[162:165], v[184:187], v[120:123]
	v_mfma_f32_16x16x32_bf16 v[112:115], v[170:173], v[184:187], v[112:115]
	v_mfma_f32_16x16x32_bf16 v[108:111], v[162:165], v[192:195], v[108:111]
	v_mfma_f32_16x16x32_bf16 v[100:103], v[170:173], v[192:195], v[100:103]
	v_mfma_f32_16x16x32_bf16 v[92:95], v[162:165], v[214:217], v[92:95]
	v_mfma_f32_16x16x32_bf16 v[84:87], v[170:173], v[214:217], v[84:87]
	v_mfma_f32_16x16x32_bf16 v[76:79], v[162:165], v[222:225], v[76:79]
	v_mfma_f32_16x16x32_bf16 v[68:71], v[170:173], v[222:225], v[68:71]
	v_mfma_f32_16x16x32_bf16 v[120:123], v[166:169], v[188:191], v[120:123]
	v_mfma_f32_16x16x32_bf16 v[112:115], v[180:183], v[188:191], v[112:115]
	v_mfma_f32_16x16x32_bf16 v[108:111], v[166:169], v[210:213], v[108:111]
	v_mfma_f32_16x16x32_bf16 v[100:103], v[180:183], v[210:213], v[100:103]
	v_mfma_f32_16x16x32_bf16 v[92:95], v[166:169], v[218:221], v[92:95]
	v_mfma_f32_16x16x32_bf16 v[84:87], v[180:183], v[218:221], v[84:87]
	v_mfma_f32_16x16x32_bf16 v[76:79], v[166:169], v[226:229], v[76:79]
	v_mfma_f32_16x16x32_bf16 v[68:71], v[180:183], v[226:229], v[68:71]
	s_barrier
; #define PG8_STAGE(bufoff, gbase, voff) do { _Pragma("unroll") for (int _i = 0; _i < 2; ++_i) \
;         __builtin_amdgcn_global_load_lds((const unsigned*)((const char*)(gbase) + (voff)[_i]), (LAS unsigned*)(lds + (bufoff) + ldsw + _i * 8192), 16, 0, 0); } while (0)
; #define PG8_LDA(dst, b, h) do { _Pragma("unroll") for (int m = 0; m < 4; ++m) _Pragma("unroll") for (int k = 0; k < 2; ++k) dst[m][k] = *(const LAS bf16x8*)(lds + PG8_SA(b, h) + aoff + m * 2048 + k * 1024); } while (0)
; #define PG8_MMA(ai, bj, At, Bt) do { __builtin_amdgcn_s_setprio(1); _Pragma("unroll") for (int m = 0; m < 4; ++m) _Pragma("unroll") for (int n = 0; n < 2; ++n) _Pragma("unroll") for (int k = 0; k < 2; ++k) \
;         acc[ai][bj][m][n] = __builtin_amdgcn_mfma_f32_16x16x32_bf16(Bt[n][k], At[m][k], acc[ai][bj][m][n], 0, 0, 0); __builtin_amdgcn_s_setprio(0); } while (0)
; #define PG8_WAIT_V(n) asm volatile("s_waitcnt vmcnt(" #n ")" ::: "memory")
; #define PG8_WAIT_L(n) asm volatile("s_waitcnt lgkmcnt(" #n ")" ::: "memory")
; #define PG8_BAR __builtin_amdgcn_s_barrier()
; #define PG8_SCHED __builtin_amdgcn_sched_barrier(0)
; template <class Epi>
; __device__ __forceinline__ void gemm_phase(LAS unsigned char* lds, const GemmD g, const Epi& E, int G, int c) {
;     ...
;             PG8_LDA(At, 1, 1); PG8_STAGE(PG8_SB(1, 0), b3, voffB); PG8_STAGE(PG8_SB(1, 1), b3 + hstepB, voffB); PG8_STAGE(PG8_SA(1, 0), a3, voffA);
;             PG8_WAIT_V(8); PG8_WAIT_L(0); PG8_BAR; PG8_MMA(1, 0, At, B0); PG8_MMA(1, 1, At, B1); PG8_BAR; PG8_SCHED;
;         }
;         if (wr == 0) PG8_BAR;
	s_setprio 0
	s_add_i32 s4, s31, s2
	v_lshl_add_u64 v[174:175], v[174:175], 0, s[48:49]
	s_mov_b32 m0, s4
	ds_read_b128 v[184:187], v151 offset:49152
	ds_read_b128 v[188:191], v151 offset:50176
	ds_read_b128 v[192:195], v151 offset:51200
	ds_read_b128 v[210:213], v151 offset:52224
	ds_read_b128 v[214:217], v151 offset:53248
	ds_read_b128 v[218:221], v151 offset:54272
	ds_read_b128 v[222:225], v151 offset:55296
	ds_read_b128 v[226:229], v151 offset:56320
	global_load_lds_dwordx4 v[174:175], off
	s_add_i32 m0, s4, 0x2000
	s_add_u32 s4, s90, 0x160080
	v_lshl_add_u64 v[174:175], v[198:199], 0, s[48:49]
	s_addc_u32 s5, s91, 0
	s_add_i32 s31, s33, s2
	global_load_lds_dwordx4 v[174:175], off
	v_lshl_add_u64 v[174:175], s[4:5], 0, v[178:179]
	s_mov_b32 m0, s31
	s_nop 0
	global_load_lds_dwordx4 v[174:175], off
	v_lshl_add_u64 v[174:175], s[4:5], 0, v[128:129]
	s_add_i32 m0, s31, 0x2000
	s_nop 0
	global_load_lds_dwordx4 v[174:175], off
	v_lshl_add_u64 v[174:175], v[230:231], 0, s[48:49]
	s_mov_b32 m0, s16
	s_nop 0
	global_load_lds_dwordx4 v[174:175], off
	v_lshl_add_u64 v[174:175], v[232:233], 0, s[48:49]
	s_mov_b32 m0, s17
	s_nop 0
	global_load_lds_dwordx4 v[174:175], off
	s_waitcnt vmcnt(8)
	s_waitcnt lgkmcnt(0)
	s_setprio 1
	s_barrier
	v_mfma_f32_16x16x32_bf16 v[52:55], v[140:143], v[184:187], v[52:55]
	v_mfma_f32_16x16x32_bf16 v[56:59], v[154:157], v[184:187], v[56:59]
	v_mfma_f32_16x16x32_bf16 v[40:43], v[140:143], v[192:195], v[40:43]
	v_mfma_f32_16x16x32_bf16 v[32:35], v[154:157], v[192:195], v[32:35]
	v_mfma_f32_16x16x32_bf16 v[20:23], v[140:143], v[214:217], v[20:23]
	v_mfma_f32_16x16x32_bf16 v[16:19], v[154:157], v[214:217], v[16:19]
	v_mfma_f32_16x16x32_bf16 v[4:7], v[140:143], v[222:225], v[4:7]
	v_mfma_f32_16x16x32_bf16 v[0:3], v[154:157], v[222:225], v[0:3]
	v_mfma_f32_16x16x32_bf16 v[52:55], v[144:147], v[188:191], v[52:55]
	v_mfma_f32_16x16x32_bf16 v[56:59], v[158:161], v[188:191], v[56:59]
	v_mfma_f32_16x16x32_bf16 v[40:43], v[144:147], v[210:213], v[40:43]
	v_mfma_f32_16x16x32_bf16 v[32:35], v[158:161], v[210:213], v[32:35]
	v_mfma_f32_16x16x32_bf16 v[20:23], v[144:147], v[218:221], v[20:23]
	v_mfma_f32_16x16x32_bf16 v[16:19], v[158:161], v[218:221], v[16:19]
	v_mfma_f32_16x16x32_bf16 v[4:7], v[144:147], v[226:229], v[4:7]
	v_mfma_f32_16x16x32_bf16 v[0:3], v[158:161], v[226:229], v[0:3]
	s_setprio 0
	s_setprio 1
	v_mfma_f32_16x16x32_bf16 v[60:63], v[162:165], v[184:187], v[60:63]
	v_mfma_f32_16x16x32_bf16 v[48:51], v[170:173], v[184:187], v[48:51]
	v_mfma_f32_16x16x32_bf16 v[44:47], v[162:165], v[192:195], v[44:47]
	v_mfma_f32_16x16x32_bf16 v[36:39], v[170:173], v[192:195], v[36:39]
	v_mfma_f32_16x16x32_bf16 v[28:31], v[162:165], v[214:217], v[28:31]
	v_mfma_f32_16x16x32_bf16 v[24:27], v[170:173], v[214:217], v[24:27]
	v_mfma_f32_16x16x32_bf16 v[12:15], v[162:165], v[222:225], v[12:15]
	v_mfma_f32_16x16x32_bf16 v[8:11], v[170:173], v[222:225], v[8:11]
	v_mfma_f32_16x16x32_bf16 v[60:63], v[166:169], v[188:191], v[60:63]
	v_mfma_f32_16x16x32_bf16 v[48:51], v[180:183], v[188:191], v[48:51]
	v_mfma_f32_16x16x32_bf16 v[44:47], v[166:169], v[210:213], v[44:47]
	v_mfma_f32_16x16x32_bf16 v[36:39], v[180:183], v[210:213], v[36:39]
	v_mfma_f32_16x16x32_bf16 v[28:31], v[166:169], v[218:221], v[28:31]
	v_mfma_f32_16x16x32_bf16 v[24:27], v[180:183], v[218:221], v[24:27]
	v_mfma_f32_16x16x32_bf16 v[12:15], v[166:169], v[226:229], v[12:15]
	v_mfma_f32_16x16x32_bf16 v[8:11], v[180:183], v[226:229], v[8:11]
	s_barrier
	s_setprio 0
	s_add_i32 s30, s30, 2
	s_add_u32 s28, s28, 0x100
	s_addc_u32 s29, s29, 0
	s_cmpk_gt_u32 s30, 0x55
	s_mov_b64 s[46:47], s[88:89]
	s_cbranch_scc0 .LBB0_106
	s_and_b64 vcc, exec, s[80:81]
	s_cbranch_vccz .LBB0_109
	s_barrier

; #define PG8_STAGE(bufoff, gbase, voff) do { _Pragma("unroll") for (int _i = 0; _i < 2; ++_i) \
;         __builtin_amdgcn_global_load_lds((const unsigned*)((const char*)(gbase) + (voff)[_i]), (LAS unsigned*)(lds + (bufoff) + ldsw + _i * 8192), 16, 0, 0); } while (0)
; #define PG8_LDA(dst, b, h) do { _Pragma("unroll") for (int m = 0; m < 4; ++m) _Pragma("unroll") for (int k = 0; k < 2; ++k) dst[m][k] = *(const LAS bf16x8*)(lds + PG8_SA(b, h) + aoff + m * 2048 + k * 1024); } while (0)
; #define PG8_MMA(ai, bj, At, Bt) do { __builtin_amdgcn_s_setprio(1); _Pragma("unroll") for (int m = 0; m < 4; ++m) _Pragma("unroll") for (int n = 0; n < 2; ++n) _Pragma("unroll") for (int k = 0; k < 2; ++k) \
;         acc[ai][bj][m][n] = __builtin_amdgcn_mfma_f32_16x16x32_bf16(Bt[n][k], At[m][k], acc[ai][bj][m][n], 0, 0, 0); __builtin_amdgcn_s_setprio(0); } while (0)
; #define PG8_WAIT_V(n) asm volatile("s_waitcnt vmcnt(" #n ")" ::: "memory")
; #define PG8_WAIT_L(n) asm volatile("s_waitcnt lgkmcnt(" #n ")" ::: "memory")
; #define PG8_BAR __builtin_amdgcn_s_barrier()
; #define PG8_SCHED __builtin_amdgcn_sched_barrier(0)
; template <class Epi>
; __device__ __forceinline__ void gemm_phase(LAS unsigned char* lds, const GemmD g, const Epi& E, int G, int c) {
;     ...
;             PG8_WAIT_V(8); PG8_WAIT_L(0); PG8_BAR; PG8_MMA(0, 0, At, B0); PG8_MMA(0, 1, At, B1); PG8_BAR; PG8_SCHED;
;             PG8_LDA(At, 0, 1); PG8_STAGE(PG8_SB(0, 0), b2, voffB); PG8_STAGE(PG8_SB(0, 1), b2 + hstepB, voffB); PG8_STAGE(PG8_SA(0, 0), a2, voffA);
;             PG8_WAIT_V(8); PG8_WAIT_L(0); PG8_BAR; PG8_MMA(1, 0, At, B0); PG8_MMA(1, 1, At, B1); PG8_BAR; PG8_SCHED;
.Lrw_FfnUp_0_d:
	s_waitcnt lgkmcnt(0)
	s_setprio 1
	s_barrier
	v_mfma_f32_16x16x32_bf16 v[124:127], v[138:141], v[184:187], v[124:127]
	v_mfma_f32_16x16x32_bf16 v[116:119], v[156:159], v[184:187], v[116:119]
	v_mfma_f32_16x16x32_bf16 v[108:111], v[138:141], v[192:195], v[108:111]
	v_mfma_f32_16x16x32_bf16 v[100:103], v[156:159], v[192:195], v[100:103]
	v_mfma_f32_16x16x32_bf16 v[92:95], v[138:141], v[214:217], v[92:95]
	v_mfma_f32_16x16x32_bf16 v[84:87], v[156:159], v[214:217], v[84:87]
	v_mfma_f32_16x16x32_bf16 v[76:79], v[138:141], v[222:225], v[76:79]
	v_mfma_f32_16x16x32_bf16 v[68:71], v[156:159], v[222:225], v[68:71]
	v_mfma_f32_16x16x32_bf16 v[124:127], v[152:155], v[188:191], v[124:127]
	v_mfma_f32_16x16x32_bf16 v[116:119], v[160:163], v[188:191], v[116:119]
	v_mfma_f32_16x16x32_bf16 v[108:111], v[152:155], v[210:213], v[108:111]
	v_mfma_f32_16x16x32_bf16 v[100:103], v[160:163], v[210:213], v[100:103]
	v_mfma_f32_16x16x32_bf16 v[92:95], v[152:155], v[218:221], v[92:95]
	v_mfma_f32_16x16x32_bf16 v[84:87], v[160:163], v[218:221], v[84:87]
	v_mfma_f32_16x16x32_bf16 v[76:79], v[152:155], v[226:229], v[76:79]
	v_mfma_f32_16x16x32_bf16 v[68:71], v[160:163], v[226:229], v[68:71]
	s_setprio 0
	s_setprio 1
	v_mfma_f32_16x16x32_bf16 v[120:123], v[164:167], v[184:187], v[120:123]
	v_mfma_f32_16x16x32_bf16 v[112:115], v[172:175], v[184:187], v[112:115]
	v_mfma_f32_16x16x32_bf16 v[104:107], v[164:167], v[192:195], v[104:107]
	v_mfma_f32_16x16x32_bf16 v[96:99], v[172:175], v[192:195], v[96:99]
	v_mfma_f32_16x16x32_bf16 v[88:91], v[164:167], v[214:217], v[88:91]
	v_mfma_f32_16x16x32_bf16 v[80:83], v[172:175], v[214:217], v[80:83]
	v_mfma_f32_16x16x32_bf16 v[72:75], v[164:167], v[222:225], v[72:75]
	v_mfma_f32_16x16x32_bf16 v[64:67], v[172:175], v[222:225], v[64:67]
	v_mfma_f32_16x16x32_bf16 v[120:123], v[168:171], v[188:191], v[120:123]
	v_mfma_f32_16x16x32_bf16 v[112:115], v[180:183], v[188:191], v[112:115]
	v_mfma_f32_16x16x32_bf16 v[104:107], v[168:171], v[210:213], v[104:107]
	v_mfma_f32_16x16x32_bf16 v[96:99], v[180:183], v[210:213], v[96:99]
	v_mfma_f32_16x16x32_bf16 v[88:91], v[168:171], v[218:221], v[88:91]
	v_mfma_f32_16x16x32_bf16 v[80:83], v[180:183], v[218:221], v[80:83]
	v_mfma_f32_16x16x32_bf16 v[72:75], v[168:171], v[226:229], v[72:75]
	v_mfma_f32_16x16x32_bf16 v[64:67], v[180:183], v[226:229], v[64:67]
	s_barrier
	s_setprio 0
	s_add_i32 s35, s35, s2
	v_lshl_add_u64 v[146:147], s[86:87], 0, v[178:179]
	s_mov_b32 m0, s35
	ds_read_b128 v[184:187], v151 offset:16384
	ds_read_b128 v[188:191], v151 offset:17408
	ds_read_b128 v[192:195], v151 offset:18432
	ds_read_b128 v[210:213], v151 offset:19456
	ds_read_b128 v[214:217], v151 offset:20480
	ds_read_b128 v[218:221], v151 offset:21504
	ds_read_b128 v[222:225], v151 offset:22528
	ds_read_b128 v[226:229], v151 offset:23552
	global_load_lds_dwordx4 v[146:147], off
	s_add_i32 m0, s35, 0x2000
	s_add_u32 s38, s86, 0x80000
	v_lshl_add_u64 v[198:199], s[86:87], 0, v[128:129]
	s_addc_u32 s39, s87, 0
	s_add_i32 s35, s36, s2
	global_load_lds_dwordx4 v[198:199], off
	v_lshl_add_u64 v[230:231], s[38:39], 0, v[178:179]
	s_mov_b32 m0, s35
	v_lshl_add_u64 v[232:233], s[4:5], 0, v[130:131]
	global_load_lds_dwordx4 v[230:231], off
	v_lshl_add_u64 v[230:231], s[38:39], 0, v[128:129]
	s_add_i32 m0, s35, 0x2000
	s_nop 0
	global_load_lds_dwordx4 v[230:231], off
	v_lshl_add_u64 v[230:231], s[4:5], 0, v[132:133]
	s_mov_b32 m0, s6
	s_nop 0
	global_load_lds_dwordx4 v[230:231], off
	s_mov_b32 m0, s9
	s_nop 0
	global_load_lds_dwordx4 v[232:233], off
	s_cmp_lg_u32 s99, 0
	s_cbranch_scc1 .Lrw_FfnUp_1_r
	s_waitcnt vmcnt(8)
	s_branch .Lrw_FfnUp_1_d

; #define PG8_STAGE(bufoff, gbase, voff) do { _Pragma("unroll") for (int _i = 0; _i < 2; ++_i) \
;         __builtin_amdgcn_global_load_lds((const unsigned*)((const char*)(gbase) + (voff)[_i]), (LAS unsigned*)(lds + (bufoff) + ldsw + _i * 8192), 16, 0, 0); } while (0)
; #define PG8_LDA(dst, b, h) do { _Pragma("unroll") for (int m = 0; m < 4; ++m) _Pragma("unroll") for (int k = 0; k < 2; ++k) dst[m][k] = *(const LAS bf16x8*)(lds + PG8_SA(b, h) + aoff + m * 2048 + k * 1024); } while (0)
; #define PG8_LDB(dst, b, h) do { _Pragma("unroll") for (int n = 0; n < 2; ++n) _Pragma("unroll") for (int k = 0; k < 2; ++k) dst[n][k] = *(const LAS bf16x8*)(lds + PG8_SB(b, h) + boff + n * 2048 + k * 1024); } while (0)
; #define PG8_MMA(ai, bj, At, Bt) do { __builtin_amdgcn_s_setprio(1); _Pragma("unroll") for (int m = 0; m < 4; ++m) _Pragma("unroll") for (int n = 0; n < 2; ++n) _Pragma("unroll") for (int k = 0; k < 2; ++k) \
;         acc[ai][bj][m][n] = __builtin_amdgcn_mfma_f32_16x16x32_bf16(Bt[n][k], At[m][k], acc[ai][bj][m][n], 0, 0, 0); __builtin_amdgcn_s_setprio(0); } while (0)
; #define PG8_WAIT_V(n) asm volatile("s_waitcnt vmcnt(" #n ")" ::: "memory")
; #define PG8_WAIT_L(n) asm volatile("s_waitcnt lgkmcnt(" #n ")" ::: "memory")
; #define PG8_BAR __builtin_amdgcn_s_barrier()
; #define PG8_SCHED __builtin_amdgcn_sched_barrier(0)
; template <class Epi>
; __device__ __forceinline__ void gemm_phase(LAS unsigned char* lds, const GemmD g, const Epi& E, int G, int c) {
;     ...
;             PG8_WAIT_V(8); PG8_WAIT_L(0); PG8_BAR; PG8_MMA(1, 0, At, B0); PG8_MMA(1, 1, At, B1); PG8_BAR; PG8_SCHED;
;             PG8_LDB(B0, 1, 0); PG8_LDB(B1, 1, 1); PG8_SCHED; PG8_LDA(At, 1, 0); PG8_STAGE(PG8_SA(0, 1), a2 + hstepA, voffA);
;             PG8_WAIT_V(8); PG8_WAIT_L(0); PG8_BAR; PG8_MMA(0, 0, At, B0); PG8_MMA(0, 1, At, B1); PG8_BAR; PG8_SCHED;
.Lrw_FfnUp_1_d:
	s_waitcnt lgkmcnt(0)
	s_setprio 1
	s_barrier
	v_mfma_f32_16x16x32_bf16 v[60:63], v[138:141], v[184:187], v[60:63]
	v_mfma_f32_16x16x32_bf16 v[52:55], v[156:159], v[184:187], v[52:55]
	v_mfma_f32_16x16x32_bf16 v[44:47], v[138:141], v[192:195], v[44:47]
	v_mfma_f32_16x16x32_bf16 v[36:39], v[156:159], v[192:195], v[36:39]
	v_mfma_f32_16x16x32_bf16 v[28:31], v[138:141], v[214:217], v[28:31]
	v_mfma_f32_16x16x32_bf16 v[20:23], v[156:159], v[214:217], v[20:23]
	v_mfma_f32_16x16x32_bf16 v[12:15], v[138:141], v[222:225], v[12:15]
	v_mfma_f32_16x16x32_bf16 v[4:7], v[156:159], v[222:225], v[4:7]
	v_mfma_f32_16x16x32_bf16 v[60:63], v[152:155], v[188:191], v[60:63]
	v_mfma_f32_16x16x32_bf16 v[52:55], v[160:163], v[188:191], v[52:55]
	v_mfma_f32_16x16x32_bf16 v[44:47], v[152:155], v[210:213], v[44:47]
	v_mfma_f32_16x16x32_bf16 v[36:39], v[160:163], v[210:213], v[36:39]
	v_mfma_f32_16x16x32_bf16 v[28:31], v[152:155], v[218:221], v[28:31]
	v_mfma_f32_16x16x32_bf16 v[20:23], v[160:163], v[218:221], v[20:23]
	v_mfma_f32_16x16x32_bf16 v[12:15], v[152:155], v[226:229], v[12:15]
	v_mfma_f32_16x16x32_bf16 v[4:7], v[160:163], v[226:229], v[4:7]
	s_setprio 0
	s_setprio 1
	v_mfma_f32_16x16x32_bf16 v[56:59], v[164:167], v[184:187], v[56:59]
	v_mfma_f32_16x16x32_bf16 v[48:51], v[172:175], v[184:187], v[48:51]
	v_mfma_f32_16x16x32_bf16 v[40:43], v[164:167], v[192:195], v[40:43]
	v_mfma_f32_16x16x32_bf16 v[32:35], v[172:175], v[192:195], v[32:35]
	v_mfma_f32_16x16x32_bf16 v[24:27], v[164:167], v[214:217], v[24:27]
	v_mfma_f32_16x16x32_bf16 v[16:19], v[172:175], v[214:217], v[16:19]
	v_mfma_f32_16x16x32_bf16 v[8:11], v[164:167], v[222:225], v[8:11]
	v_mfma_f32_16x16x32_bf16 v[0:3], v[172:175], v[222:225], v[0:3]
	v_mfma_f32_16x16x32_bf16 v[56:59], v[168:171], v[188:191], v[56:59]
	v_mfma_f32_16x16x32_bf16 v[48:51], v[180:183], v[188:191], v[48:51]
	v_mfma_f32_16x16x32_bf16 v[40:43], v[168:171], v[210:213], v[40:43]
	v_mfma_f32_16x16x32_bf16 v[32:35], v[180:183], v[210:213], v[32:35]
	v_mfma_f32_16x16x32_bf16 v[24:27], v[168:171], v[218:221], v[24:27]
	v_mfma_f32_16x16x32_bf16 v[16:19], v[180:183], v[218:221], v[16:19]
	v_mfma_f32_16x16x32_bf16 v[8:11], v[168:171], v[226:229], v[8:11]
	v_mfma_f32_16x16x32_bf16 v[0:3], v[180:183], v[226:229], v[0:3]
	s_barrier
	s_setprio 0
	s_add_i32 s35, 0, 0x18000
	v_add_u32_e32 v142, s35, v145
	s_add_i32 s36, 0, 0x1c000
	ds_read_b128 v[138:141], v142
	ds_read_b128 v[152:155], v142 offset:1024
	ds_read_b128 v[156:159], v142 offset:2048
	ds_read_b128 v[160:163], v142 offset:3072
	v_add_u32_e32 v142, s36, v145
	ds_read_b128 v[164:167], v142
	ds_read_b128 v[168:171], v142 offset:1024
	ds_read_b128 v[172:175], v142 offset:2048
	ds_read_b128 v[180:183], v142 offset:3072
	s_add_u32 s4, s4, 0x80000
	s_addc_u32 s5, s5, 0
	s_mov_b32 m0, s10
	v_lshl_add_u64 v[234:235], s[4:5], 0, v[132:133]
	ds_read_b128 v[184:187], v151 offset:32768
	ds_read_b128 v[188:191], v151 offset:33792
	ds_read_b128 v[192:195], v151 offset:34816
	ds_read_b128 v[210:213], v151 offset:35840
	ds_read_b128 v[214:217], v151 offset:36864
	ds_read_b128 v[218:221], v151 offset:37888
	ds_read_b128 v[222:225], v151 offset:38912
	ds_read_b128 v[226:229], v151 offset:39936
	global_load_lds_dwordx4 v[234:235], off
	v_lshl_add_u64 v[234:235], s[4:5], 0, v[130:131]
	s_mov_b32 m0, s11
	s_nop 0
	global_load_lds_dwordx4 v[234:235], off
	s_waitcnt vmcnt(8)
	s_waitcnt lgkmcnt(0)
	s_setprio 1
	s_barrier
	v_mfma_f32_16x16x32_bf16 v[124:127], v[138:141], v[184:187], v[124:127]
	v_mfma_f32_16x16x32_bf16 v[116:119], v[156:159], v[184:187], v[116:119]
	v_mfma_f32_16x16x32_bf16 v[108:111], v[138:141], v[192:195], v[108:111]
	v_mfma_f32_16x16x32_bf16 v[100:103], v[156:159], v[192:195], v[100:103]
	v_mfma_f32_16x16x32_bf16 v[92:95], v[138:141], v[214:217], v[92:95]
	v_mfma_f32_16x16x32_bf16 v[84:87], v[156:159], v[214:217], v[84:87]
	v_mfma_f32_16x16x32_bf16 v[76:79], v[138:141], v[222:225], v[76:79]
	v_mfma_f32_16x16x32_bf16 v[68:71], v[156:159], v[222:225], v[68:71]
	v_mfma_f32_16x16x32_bf16 v[124:127], v[152:155], v[188:191], v[124:127]
	v_mfma_f32_16x16x32_bf16 v[116:119], v[160:163], v[188:191], v[116:119]
	v_mfma_f32_16x16x32_bf16 v[108:111], v[152:155], v[210:213], v[108:111]
	v_mfma_f32_16x16x32_bf16 v[100:103], v[160:163], v[210:213], v[100:103]
	v_mfma_f32_16x16x32_bf16 v[92:95], v[152:155], v[218:221], v[92:95]
	v_mfma_f32_16x16x32_bf16 v[84:87], v[160:163], v[218:221], v[84:87]
	v_mfma_f32_16x16x32_bf16 v[76:79], v[152:155], v[226:229], v[76:79]
	v_mfma_f32_16x16x32_bf16 v[68:71], v[160:163], v[226:229], v[68:71]
	s_setprio 0
	s_setprio 1
	v_mfma_f32_16x16x32_bf16 v[120:123], v[164:167], v[184:187], v[120:123]
	v_mfma_f32_16x16x32_bf16 v[112:115], v[172:175], v[184:187], v[112:115]
	v_mfma_f32_16x16x32_bf16 v[104:107], v[164:167], v[192:195], v[104:107]
	v_mfma_f32_16x16x32_bf16 v[96:99], v[172:175], v[192:195], v[96:99]
	v_mfma_f32_16x16x32_bf16 v[88:91], v[164:167], v[214:217], v[88:91]
	v_mfma_f32_16x16x32_bf16 v[80:83], v[172:175], v[214:217], v[80:83]
	v_mfma_f32_16x16x32_bf16 v[72:75], v[164:167], v[222:225], v[72:75]
	v_mfma_f32_16x16x32_bf16 v[64:67], v[172:175], v[222:225], v[64:67]
	v_mfma_f32_16x16x32_bf16 v[120:123], v[168:171], v[188:191], v[120:123]
	v_mfma_f32_16x16x32_bf16 v[112:115], v[180:183], v[188:191], v[112:115]
	v_mfma_f32_16x16x32_bf16 v[104:107], v[168:171], v[210:213], v[104:107]
	v_mfma_f32_16x16x32_bf16 v[96:99], v[180:183], v[210:213], v[96:99]
	v_mfma_f32_16x16x32_bf16 v[88:91], v[168:171], v[218:221], v[88:91]
	v_mfma_f32_16x16x32_bf16 v[80:83], v[180:183], v[218:221], v[80:83]
	v_mfma_f32_16x16x32_bf16 v[72:75], v[168:171], v[226:229], v[72:75]
	v_mfma_f32_16x16x32_bf16 v[64:67], v[180:183], v[226:229], v[64:67]
	s_barrier
; #define PG8_STAGE(bufoff, gbase, voff) do { _Pragma("unroll") for (int _i = 0; _i < 2; ++_i) \
;         __builtin_amdgcn_global_load_lds((const unsigned*)((const char*)(gbase) + (voff)[_i]), (LAS unsigned*)(lds + (bufoff) + ldsw + _i * 8192), 16, 0, 0); } while (0)
; #define PG8_LDA(dst, b, h) do { _Pragma("unroll") for (int m = 0; m < 4; ++m) _Pragma("unroll") for (int k = 0; k < 2; ++k) dst[m][k] = *(const LAS bf16x8*)(lds + PG8_SA(b, h) + aoff + m * 2048 + k * 1024); } while (0)
; #define PG8_MMA(ai, bj, At, Bt) do { __builtin_amdgcn_s_setprio(1); _Pragma("unroll") for (int m = 0; m < 4; ++m) _Pragma("unroll") for (int n = 0; n < 2; ++n) _Pragma("unroll") for (int k = 0; k < 2; ++k) \
;         acc[ai][bj][m][n] = __builtin_amdgcn_mfma_f32_16x16x32_bf16(Bt[n][k], At[m][k], acc[ai][bj][m][n], 0, 0, 0); __builtin_amdgcn_s_setprio(0); } while (0)
; #define PG8_WAIT_V(n) asm volatile("s_waitcnt vmcnt(" #n ")" ::: "memory")
; #define PG8_WAIT_L(n) asm volatile("s_waitcnt lgkmcnt(" #n ")" ::: "memory")
; #define PG8_BAR __builtin_amdgcn_s_barrier()
; #define PG8_SCHED __builtin_amdgcn_sched_barrier(0)
; template <class Epi>
; __device__ __forceinline__ void gemm_phase(LAS unsigned char* lds, const GemmD g, const Epi& E, int G, int c) {
;     ...
;             PG8_LDA(At, 1, 1); PG8_STAGE(PG8_SB(1, 0), b3, voffB); PG8_STAGE(PG8_SB(1, 1), b3 + hstepB, voffB); PG8_STAGE(PG8_SA(1, 0), a3, voffA);
;             PG8_WAIT_V(8); PG8_WAIT_L(0); PG8_BAR; PG8_MMA(1, 0, At, B0); PG8_MMA(1, 1, At, B1); PG8_BAR; PG8_SCHED;
;         }
;         if (wr == 0) PG8_BAR;
	s_setprio 0
	s_add_i32 s4, s35, s2
	v_lshl_add_u64 v[146:147], v[146:147], 0, s[48:49]
	s_mov_b32 m0, s4
	ds_read_b128 v[184:187], v151 offset:49152
	ds_read_b128 v[188:191], v151 offset:50176
	ds_read_b128 v[192:195], v151 offset:51200
	ds_read_b128 v[210:213], v151 offset:52224
	ds_read_b128 v[214:217], v151 offset:53248
	ds_read_b128 v[218:221], v151 offset:54272
	ds_read_b128 v[222:225], v151 offset:55296
	ds_read_b128 v[226:229], v151 offset:56320
	global_load_lds_dwordx4 v[146:147], off
	s_add_i32 m0, s4, 0x2000
	s_add_u32 s4, s86, 0x80080
	v_lshl_add_u64 v[146:147], v[198:199], 0, s[48:49]
	s_addc_u32 s5, s87, 0
	s_add_i32 s35, s36, s2
	global_load_lds_dwordx4 v[146:147], off
	v_lshl_add_u64 v[146:147], s[4:5], 0, v[178:179]
	s_mov_b32 m0, s35
	s_nop 0
	global_load_lds_dwordx4 v[146:147], off
	v_lshl_add_u64 v[146:147], s[4:5], 0, v[128:129]
	s_add_i32 m0, s35, 0x2000
	s_nop 0
	global_load_lds_dwordx4 v[146:147], off
	v_lshl_add_u64 v[146:147], v[230:231], 0, s[48:49]
	s_mov_b32 m0, s16
	s_nop 0
	global_load_lds_dwordx4 v[146:147], off
	v_lshl_add_u64 v[146:147], v[232:233], 0, s[48:49]
	s_mov_b32 m0, s17
	s_nop 0
	global_load_lds_dwordx4 v[146:147], off
	s_waitcnt vmcnt(8)
	s_waitcnt lgkmcnt(0)
	s_setprio 1
	s_barrier
	v_mfma_f32_16x16x32_bf16 v[60:63], v[138:141], v[184:187], v[60:63]
	v_mfma_f32_16x16x32_bf16 v[52:55], v[156:159], v[184:187], v[52:55]
	v_mfma_f32_16x16x32_bf16 v[44:47], v[138:141], v[192:195], v[44:47]
	v_mfma_f32_16x16x32_bf16 v[36:39], v[156:159], v[192:195], v[36:39]
	v_mfma_f32_16x16x32_bf16 v[28:31], v[138:141], v[214:217], v[28:31]
	v_mfma_f32_16x16x32_bf16 v[20:23], v[156:159], v[214:217], v[20:23]
	v_mfma_f32_16x16x32_bf16 v[12:15], v[138:141], v[222:225], v[12:15]
	v_mfma_f32_16x16x32_bf16 v[4:7], v[156:159], v[222:225], v[4:7]
	v_mfma_f32_16x16x32_bf16 v[60:63], v[152:155], v[188:191], v[60:63]
	v_mfma_f32_16x16x32_bf16 v[52:55], v[160:163], v[188:191], v[52:55]
	v_mfma_f32_16x16x32_bf16 v[44:47], v[152:155], v[210:213], v[44:47]
	v_mfma_f32_16x16x32_bf16 v[36:39], v[160:163], v[210:213], v[36:39]
	v_mfma_f32_16x16x32_bf16 v[28:31], v[152:155], v[218:221], v[28:31]
	v_mfma_f32_16x16x32_bf16 v[20:23], v[160:163], v[218:221], v[20:23]
	v_mfma_f32_16x16x32_bf16 v[12:15], v[152:155], v[226:229], v[12:15]
	v_mfma_f32_16x16x32_bf16 v[4:7], v[160:163], v[226:229], v[4:7]
	s_setprio 0
	s_setprio 1
	v_mfma_f32_16x16x32_bf16 v[56:59], v[164:167], v[184:187], v[56:59]
	v_mfma_f32_16x16x32_bf16 v[48:51], v[172:175], v[184:187], v[48:51]
	v_mfma_f32_16x16x32_bf16 v[40:43], v[164:167], v[192:195], v[40:43]
	v_mfma_f32_16x16x32_bf16 v[32:35], v[172:175], v[192:195], v[32:35]
	v_mfma_f32_16x16x32_bf16 v[24:27], v[164:167], v[214:217], v[24:27]
	v_mfma_f32_16x16x32_bf16 v[16:19], v[172:175], v[214:217], v[16:19]
	v_mfma_f32_16x16x32_bf16 v[8:11], v[164:167], v[222:225], v[8:11]
	v_mfma_f32_16x16x32_bf16 v[0:3], v[172:175], v[222:225], v[0:3]
	v_mfma_f32_16x16x32_bf16 v[56:59], v[168:171], v[188:191], v[56:59]
	v_mfma_f32_16x16x32_bf16 v[48:51], v[180:183], v[188:191], v[48:51]
	v_mfma_f32_16x16x32_bf16 v[40:43], v[168:171], v[210:213], v[40:43]
	v_mfma_f32_16x16x32_bf16 v[32:35], v[180:183], v[210:213], v[32:35]
	v_mfma_f32_16x16x32_bf16 v[24:27], v[168:171], v[218:221], v[24:27]
	v_mfma_f32_16x16x32_bf16 v[16:19], v[180:183], v[218:221], v[16:19]
	v_mfma_f32_16x16x32_bf16 v[8:11], v[168:171], v[226:229], v[8:11]
	v_mfma_f32_16x16x32_bf16 v[0:3], v[180:183], v[226:229], v[0:3]
	s_barrier
	s_setprio 0
	s_add_i32 s33, s33, 2
	s_add_u32 s42, s42, 0x100
	s_addc_u32 s43, s43, 0
	s_add_u32 s30, s30, 0x100
	s_addc_u32 s31, s31, 0
	s_cmp_gt_u32 s33, 29
	s_cbranch_scc0 .LBB0_202
	s_and_b64 vcc, exec, s[46:47]
	s_cbranch_vccz .LBB0_205
	s_barrier

; #define PG8_STAGE(bufoff, gbase, voff) do { _Pragma("unroll") for (int _i = 0; _i < 2; ++_i) \
;         __builtin_amdgcn_global_load_lds((const unsigned*)((const char*)(gbase) + (voff)[_i]), (LAS unsigned*)(lds + (bufoff) + ldsw + _i * 8192), 16, 0, 0); } while (0)
; #define PG8_LDA(dst, b, h) do { _Pragma("unroll") for (int m = 0; m < 4; ++m) _Pragma("unroll") for (int k = 0; k < 2; ++k) dst[m][k] = *(const LAS bf16x8*)(lds + PG8_SA(b, h) + aoff + m * 2048 + k * 1024); } while (0)
; #define PG8_LDB(dst, b, h) do { _Pragma("unroll") for (int n = 0; n < 2; ++n) _Pragma("unroll") for (int k = 0; k < 2; ++k) dst[n][k] = *(const LAS bf16x8*)(lds + PG8_SB(b, h) + boff + n * 2048 + k * 1024); } while (0)
; #define PG8_MMA(ai, bj, At, Bt) do { __builtin_amdgcn_s_setprio(1); _Pragma("unroll") for (int m = 0; m < 4; ++m) _Pragma("unroll") for (int n = 0; n < 2; ++n) _Pragma("unroll") for (int k = 0; k < 2; ++k) \
;         acc[ai][bj][m][n] = __builtin_amdgcn_mfma_f32_16x16x32_bf16(Bt[n][k], At[m][k], acc[ai][bj][m][n], 0, 0, 0); __builtin_amdgcn_s_setprio(0); } while (0)
; #define PG8_WAIT_V(n) asm volatile("s_waitcnt vmcnt(" #n ")" ::: "memory")
; #define PG8_WAIT_L(n) asm volatile("s_waitcnt lgkmcnt(" #n ")" ::: "memory")
; #define PG8_BAR __builtin_amdgcn_s_barrier()
; #define PG8_SCHED __builtin_amdgcn_sched_barrier(0)
; template <class Epi>
; __device__ __forceinline__ void gemm_phase(LAS unsigned char* lds, const GemmD g, const Epi& E, int G, int c) {
;     ...
;             const bool last = (t == nt - 2);
;             const char* a1 = cA + (size_t)(t + 1) * kstep;
;             const char* a2 = last ? nA : cA + (size_t)(t + 2) * kstep; const char* b2 = last ? nB : cB + (size_t)(t + 2) * kstep;
;             const char* a3 = a2 + kstep; const char* b3 = b2 + kstep;
;             PG8_LDB(B0, 0, 0); PG8_LDB(B1, 0, 1); PG8_SCHED; PG8_LDA(At, 0, 0); PG8_STAGE(PG8_SA(1, 1), a1 + hstepA, voffA);
;             PG8_WAIT_V(8); PG8_WAIT_L(0); PG8_BAR; PG8_MMA(0, 0, At, B0); PG8_MMA(0, 1, At, B1); PG8_BAR; PG8_SCHED;
;             PG8_LDA(At, 0, 1); PG8_STAGE(PG8_SB(0, 0), b2, voffB); PG8_STAGE(PG8_SB(0, 1), b2 + hstepB, voffB); PG8_STAGE(PG8_SA(0, 0), a2, voffA);
;             PG8_WAIT_V(8); PG8_WAIT_L(0); PG8_BAR; PG8_MMA(1, 0, At, B0); PG8_MMA(1, 1, At, B1); PG8_BAR; PG8_SCHED;
.LBB0_224:
	s_add_u32 s4, s86, 0xfff80080
	s_addc_u32 s5, s87, -1
	s_add_i32 s35, 0, 0x10000
	s_cmp_eq_u32 s33, 28
	s_cselect_b32 s5, s26, s5
	s_cselect_b32 s4, s27, s4
	v_add_u32_e32 v140, s35, v143
	s_cselect_b32 s85, s28, s31
	s_cselect_b32 s84, s29, s30
	s_add_i32 s36, 0, 0x14000
	ds_read_b128 v[148:151], v140
	ds_read_b128 v[152:155], v140 offset:1024
	ds_read_b128 v[156:159], v140 offset:2048
	ds_read_b128 v[160:163], v140 offset:3072
	v_add_u32_e32 v140, s36, v143
	ds_read_b128 v[164:167], v140
	ds_read_b128 v[168:171], v140 offset:1024
	ds_read_b128 v[172:175], v140 offset:2048
	ds_read_b128 v[180:183], v140 offset:3072
	v_lshl_add_u64 v[140:141], s[86:87], 0, v[136:137]
	s_add_i32 m0, s6, 0xc000
	ds_read_b128 v[184:187], v145
	ds_read_b128 v[188:191], v145 offset:1024
	ds_read_b128 v[192:195], v145 offset:2048
	ds_read_b128 v[210:213], v145 offset:3072
	ds_read_b128 v[214:217], v145 offset:4096
	ds_read_b128 v[218:221], v145 offset:5120
	ds_read_b128 v[222:225], v145 offset:6144
	ds_read_b128 v[226:229], v145 offset:7168
	global_load_lds_dwordx4 v[140:141], off
	v_lshl_add_u64 v[140:141], s[86:87], 0, v[138:139]
	s_add_i32 m0, s6, 0xe000
	s_nop 0
	global_load_lds_dwordx4 v[140:141], off
	s_waitcnt vmcnt(8)
	s_waitcnt lgkmcnt(0)
	s_setprio 1
	s_barrier
	v_mfma_f32_16x16x32_bf16 v[124:127], v[148:151], v[184:187], v[124:127]
	v_mfma_f32_16x16x32_bf16 v[120:123], v[156:159], v[184:187], v[120:123]
	v_mfma_f32_16x16x32_bf16 v[108:111], v[148:151], v[192:195], v[108:111]
	v_mfma_f32_16x16x32_bf16 v[104:107], v[156:159], v[192:195], v[104:107]
	v_mfma_f32_16x16x32_bf16 v[92:95], v[148:151], v[214:217], v[92:95]
	v_mfma_f32_16x16x32_bf16 v[88:91], v[156:159], v[214:217], v[88:91]
	v_mfma_f32_16x16x32_bf16 v[76:79], v[148:151], v[222:225], v[76:79]
	v_mfma_f32_16x16x32_bf16 v[72:75], v[156:159], v[222:225], v[72:75]
	v_mfma_f32_16x16x32_bf16 v[124:127], v[152:155], v[188:191], v[124:127]
	v_mfma_f32_16x16x32_bf16 v[120:123], v[160:163], v[188:191], v[120:123]
	v_mfma_f32_16x16x32_bf16 v[108:111], v[152:155], v[210:213], v[108:111]
	v_mfma_f32_16x16x32_bf16 v[104:107], v[160:163], v[210:213], v[104:107]
	v_mfma_f32_16x16x32_bf16 v[92:95], v[152:155], v[218:221], v[92:95]
	v_mfma_f32_16x16x32_bf16 v[88:91], v[160:163], v[218:221], v[88:91]
	v_mfma_f32_16x16x32_bf16 v[76:79], v[152:155], v[226:229], v[76:79]
	v_mfma_f32_16x16x32_bf16 v[72:75], v[160:163], v[226:229], v[72:75]
	s_setprio 0
	s_setprio 1
	v_mfma_f32_16x16x32_bf16 v[116:119], v[164:167], v[184:187], v[116:119]
	v_mfma_f32_16x16x32_bf16 v[112:115], v[172:175], v[184:187], v[112:115]
	v_mfma_f32_16x16x32_bf16 v[100:103], v[164:167], v[192:195], v[100:103]
	v_mfma_f32_16x16x32_bf16 v[96:99], v[172:175], v[192:195], v[96:99]
	v_mfma_f32_16x16x32_bf16 v[84:87], v[164:167], v[214:217], v[84:87]
	v_mfma_f32_16x16x32_bf16 v[80:83], v[172:175], v[214:217], v[80:83]
	v_mfma_f32_16x16x32_bf16 v[68:71], v[164:167], v[222:225], v[68:71]
	v_mfma_f32_16x16x32_bf16 v[64:67], v[172:175], v[222:225], v[64:67]
	v_mfma_f32_16x16x32_bf16 v[116:119], v[168:171], v[188:191], v[116:119]
	v_mfma_f32_16x16x32_bf16 v[112:115], v[180:183], v[188:191], v[112:115]
	v_mfma_f32_16x16x32_bf16 v[100:103], v[168:171], v[210:213], v[100:103]
	v_mfma_f32_16x16x32_bf16 v[96:99], v[180:183], v[210:213], v[96:99]
	v_mfma_f32_16x16x32_bf16 v[84:87], v[168:171], v[218:221], v[84:87]
	v_mfma_f32_16x16x32_bf16 v[80:83], v[180:183], v[218:221], v[80:83]
	v_mfma_f32_16x16x32_bf16 v[68:71], v[168:171], v[226:229], v[68:71]
	v_mfma_f32_16x16x32_bf16 v[64:67], v[180:183], v[226:229], v[64:67]
	s_barrier
	s_setprio 0
	s_add_i32 s35, s35, s2
	v_lshl_add_u64 v[140:141], s[84:85], 0, v[178:179]
	s_mov_b32 m0, s35
	ds_read_b128 v[184:187], v145 offset:16384
	ds_read_b128 v[188:191], v145 offset:17408
	ds_read_b128 v[192:195], v145 offset:18432
	ds_read_b128 v[210:213], v145 offset:19456
	ds_read_b128 v[214:217], v145 offset:20480
	ds_read_b128 v[218:221], v145 offset:21504
	ds_read_b128 v[222:225], v145 offset:22528
	ds_read_b128 v[226:229], v145 offset:23552
	global_load_lds_dwordx4 v[140:141], off
	s_add_i32 m0, s35, 0x2000
	s_add_u32 s38, s84, 0x80000
	v_lshl_add_u64 v[198:199], s[84:85], 0, v[128:129]
	s_addc_u32 s39, s85, 0
	s_add_i32 s35, s36, s2
	global_load_lds_dwordx4 v[198:199], off
	v_lshl_add_u64 v[230:231], s[38:39], 0, v[178:179]
	s_mov_b32 m0, s35
	v_lshl_add_u64 v[232:233], s[4:5], 0, v[130:131]
	global_load_lds_dwordx4 v[230:231], off
	v_lshl_add_u64 v[230:231], s[38:39], 0, v[128:129]
	s_add_i32 m0, s35, 0x2000
	s_nop 0
	global_load_lds_dwordx4 v[230:231], off
	v_lshl_add_u64 v[230:231], s[4:5], 0, v[132:133]
	s_mov_b32 m0, s6
	s_nop 0
	global_load_lds_dwordx4 v[230:231], off
	s_mov_b32 m0, s9
	s_nop 0
	global_load_lds_dwordx4 v[232:233], off
	s_waitcnt vmcnt(8)
	s_waitcnt lgkmcnt(0)
	s_setprio 1
	s_barrier
; #define PG8_STAGE(bufoff, gbase, voff) do { _Pragma("unroll") for (int _i = 0; _i < 2; ++_i) \
;         __builtin_amdgcn_global_load_lds((const unsigned*)((const char*)(gbase) + (voff)[_i]), (LAS unsigned*)(lds + (bufoff) + ldsw + _i * 8192), 16, 0, 0); } while (0)
; #define PG8_LDA(dst, b, h) do { _Pragma("unroll") for (int m = 0; m < 4; ++m) _Pragma("unroll") for (int k = 0; k < 2; ++k) dst[m][k] = *(const LAS bf16x8*)(lds + PG8_SA(b, h) + aoff + m * 2048 + k * 1024); } while (0)
; #define PG8_LDB(dst, b, h) do { _Pragma("unroll") for (int n = 0; n < 2; ++n) _Pragma("unroll") for (int k = 0; k < 2; ++k) dst[n][k] = *(const LAS bf16x8*)(lds + PG8_SB(b, h) + boff + n * 2048 + k * 1024); } while (0)
; #define PG8_MMA(ai, bj, At, Bt) do { __builtin_amdgcn_s_setprio(1); _Pragma("unroll") for (int m = 0; m < 4; ++m) _Pragma("unroll") for (int n = 0; n < 2; ++n) _Pragma("unroll") for (int k = 0; k < 2; ++k) \
;         acc[ai][bj][m][n] = __builtin_amdgcn_mfma_f32_16x16x32_bf16(Bt[n][k], At[m][k], acc[ai][bj][m][n], 0, 0, 0); __builtin_amdgcn_s_setprio(0); } while (0)
; #define PG8_WAIT_V(n) asm volatile("s_waitcnt vmcnt(" #n ")" ::: "memory")
; #define PG8_WAIT_L(n) asm volatile("s_waitcnt lgkmcnt(" #n ")" ::: "memory")
; #define PG8_BAR __builtin_amdgcn_s_barrier()
; #define PG8_SCHED __builtin_amdgcn_sched_barrier(0)
; template <class Epi>
; __device__ __forceinline__ void gemm_phase(LAS unsigned char* lds, const GemmD g, const Epi& E, int G, int c) {
;     ...
;             PG8_WAIT_V(8); PG8_WAIT_L(0); PG8_BAR; PG8_MMA(1, 0, At, B0); PG8_MMA(1, 1, At, B1); PG8_BAR; PG8_SCHED;
;             PG8_LDB(B0, 1, 0); PG8_LDB(B1, 1, 1); PG8_SCHED; PG8_LDA(At, 1, 0); PG8_STAGE(PG8_SA(0, 1), a2 + hstepA, voffA);
;             PG8_WAIT_V(8); PG8_WAIT_L(0); PG8_BAR; PG8_MMA(0, 0, At, B0); PG8_MMA(0, 1, At, B1); PG8_BAR; PG8_SCHED;
	v_mfma_f32_16x16x32_bf16 v[56:59], v[148:151], v[184:187], v[56:59]
	v_mfma_f32_16x16x32_bf16 v[60:63], v[156:159], v[184:187], v[60:63]
	v_mfma_f32_16x16x32_bf16 v[40:43], v[148:151], v[192:195], v[40:43]
	v_mfma_f32_16x16x32_bf16 v[36:39], v[156:159], v[192:195], v[36:39]
	v_mfma_f32_16x16x32_bf16 v[28:31], v[148:151], v[214:217], v[28:31]
	v_mfma_f32_16x16x32_bf16 v[24:27], v[156:159], v[214:217], v[24:27]
	v_mfma_f32_16x16x32_bf16 v[12:15], v[148:151], v[222:225], v[12:15]
	v_mfma_f32_16x16x32_bf16 v[8:11], v[156:159], v[222:225], v[8:11]
	v_mfma_f32_16x16x32_bf16 v[56:59], v[152:155], v[188:191], v[56:59]
	v_mfma_f32_16x16x32_bf16 v[60:63], v[160:163], v[188:191], v[60:63]
	v_mfma_f32_16x16x32_bf16 v[40:43], v[152:155], v[210:213], v[40:43]
	v_mfma_f32_16x16x32_bf16 v[36:39], v[160:163], v[210:213], v[36:39]
	v_mfma_f32_16x16x32_bf16 v[28:31], v[152:155], v[218:221], v[28:31]
	v_mfma_f32_16x16x32_bf16 v[24:27], v[160:163], v[218:221], v[24:27]
	v_mfma_f32_16x16x32_bf16 v[12:15], v[152:155], v[226:229], v[12:15]
	v_mfma_f32_16x16x32_bf16 v[8:11], v[160:163], v[226:229], v[8:11]
	s_setprio 0
	s_setprio 1
	v_mfma_f32_16x16x32_bf16 v[52:55], v[164:167], v[184:187], v[52:55]
	v_mfma_f32_16x16x32_bf16 v[48:51], v[172:175], v[184:187], v[48:51]
	v_mfma_f32_16x16x32_bf16 v[44:47], v[164:167], v[192:195], v[44:47]
	v_mfma_f32_16x16x32_bf16 v[32:35], v[172:175], v[192:195], v[32:35]
	v_mfma_f32_16x16x32_bf16 v[20:23], v[164:167], v[214:217], v[20:23]
	v_mfma_f32_16x16x32_bf16 v[16:19], v[172:175], v[214:217], v[16:19]
	v_mfma_f32_16x16x32_bf16 v[4:7], v[164:167], v[222:225], v[4:7]
	v_mfma_f32_16x16x32_bf16 v[0:3], v[172:175], v[222:225], v[0:3]
	v_mfma_f32_16x16x32_bf16 v[52:55], v[168:171], v[188:191], v[52:55]
	v_mfma_f32_16x16x32_bf16 v[48:51], v[180:183], v[188:191], v[48:51]
	v_mfma_f32_16x16x32_bf16 v[44:47], v[168:171], v[210:213], v[44:47]
	v_mfma_f32_16x16x32_bf16 v[32:35], v[180:183], v[210:213], v[32:35]
	v_mfma_f32_16x16x32_bf16 v[20:23], v[168:171], v[218:221], v[20:23]
	v_mfma_f32_16x16x32_bf16 v[16:19], v[180:183], v[218:221], v[16:19]
	v_mfma_f32_16x16x32_bf16 v[4:7], v[168:171], v[226:229], v[4:7]
	v_mfma_f32_16x16x32_bf16 v[0:3], v[180:183], v[226:229], v[0:3]
	s_barrier
	s_setprio 0
	s_add_i32 s35, 0, 0x18000
	v_add_u32_e32 v147, s35, v143
	s_add_i32 s36, 0, 0x1c000
	ds_read_b128 v[148:151], v147
	ds_read_b128 v[152:155], v147 offset:1024
	ds_read_b128 v[156:159], v147 offset:2048
	ds_read_b128 v[160:163], v147 offset:3072
	v_add_u32_e32 v147, s36, v143
	ds_read_b128 v[164:167], v147
	ds_read_b128 v[168:171], v147 offset:1024
	ds_read_b128 v[172:175], v147 offset:2048
	ds_read_b128 v[180:183], v147 offset:3072
	s_add_u32 s4, s4, 0x80000
	s_addc_u32 s5, s5, 0
	s_mov_b32 m0, s10
	v_lshl_add_u64 v[234:235], s[4:5], 0, v[132:133]
	ds_read_b128 v[184:187], v145 offset:32768
	ds_read_b128 v[188:191], v145 offset:33792
	ds_read_b128 v[192:195], v145 offset:34816
	ds_read_b128 v[210:213], v145 offset:35840
	ds_read_b128 v[214:217], v145 offset:36864
	ds_read_b128 v[218:221], v145 offset:37888
	ds_read_b128 v[222:225], v145 offset:38912
	ds_read_b128 v[226:229], v145 offset:39936
	global_load_lds_dwordx4 v[234:235], off
	v_lshl_add_u64 v[234:235], s[4:5], 0, v[130:131]
	s_mov_b32 m0, s11
	s_nop 0
	global_load_lds_dwordx4 v[234:235], off
	s_waitcnt vmcnt(8)
	s_waitcnt lgkmcnt(0)
	s_setprio 1
	s_barrier
	v_mfma_f32_16x16x32_bf16 v[124:127], v[148:151], v[184:187], v[124:127]
	v_mfma_f32_16x16x32_bf16 v[120:123], v[156:159], v[184:187], v[120:123]
	v_mfma_f32_16x16x32_bf16 v[108:111], v[148:151], v[192:195], v[108:111]
	v_mfma_f32_16x16x32_bf16 v[104:107], v[156:159], v[192:195], v[104:107]
	v_mfma_f32_16x16x32_bf16 v[92:95], v[148:151], v[214:217], v[92:95]
	v_mfma_f32_16x16x32_bf16 v[88:91], v[156:159], v[214:217], v[88:91]
	v_mfma_f32_16x16x32_bf16 v[76:79], v[148:151], v[222:225], v[76:79]
	v_mfma_f32_16x16x32_bf16 v[72:75], v[156:159], v[222:225], v[72:75]
	v_mfma_f32_16x16x32_bf16 v[124:127], v[152:155], v[188:191], v[124:127]
	v_mfma_f32_16x16x32_bf16 v[120:123], v[160:163], v[188:191], v[120:123]
	v_mfma_f32_16x16x32_bf16 v[108:111], v[152:155], v[210:213], v[108:111]
	v_mfma_f32_16x16x32_bf16 v[104:107], v[160:163], v[210:213], v[104:107]
	v_mfma_f32_16x16x32_bf16 v[92:95], v[152:155], v[218:221], v[92:95]
	v_mfma_f32_16x16x32_bf16 v[88:91], v[160:163], v[218:221], v[88:91]
	v_mfma_f32_16x16x32_bf16 v[76:79], v[152:155], v[226:229], v[76:79]
	v_mfma_f32_16x16x32_bf16 v[72:75], v[160:163], v[226:229], v[72:75]
	s_setprio 0
	s_setprio 1
	v_mfma_f32_16x16x32_bf16 v[116:119], v[164:167], v[184:187], v[116:119]
	v_mfma_f32_16x16x32_bf16 v[112:115], v[172:175], v[184:187], v[112:115]
	v_mfma_f32_16x16x32_bf16 v[100:103], v[164:167], v[192:195], v[100:103]
	v_mfma_f32_16x16x32_bf16 v[96:99], v[172:175], v[192:195], v[96:99]
	v_mfma_f32_16x16x32_bf16 v[84:87], v[164:167], v[214:217], v[84:87]
	v_mfma_f32_16x16x32_bf16 v[80:83], v[172:175], v[214:217], v[80:83]
	v_mfma_f32_16x16x32_bf16 v[68:71], v[164:167], v[222:225], v[68:71]
	v_mfma_f32_16x16x32_bf16 v[64:67], v[172:175], v[222:225], v[64:67]
	v_mfma_f32_16x16x32_bf16 v[116:119], v[168:171], v[188:191], v[116:119]
	v_mfma_f32_16x16x32_bf16 v[112:115], v[180:183], v[188:191], v[112:115]
	v_mfma_f32_16x16x32_bf16 v[100:103], v[168:171], v[210:213], v[100:103]
	v_mfma_f32_16x16x32_bf16 v[96:99], v[180:183], v[210:213], v[96:99]
	v_mfma_f32_16x16x32_bf16 v[84:87], v[168:171], v[218:221], v[84:87]
	v_mfma_f32_16x16x32_bf16 v[80:83], v[180:183], v[218:221], v[80:83]
	v_mfma_f32_16x16x32_bf16 v[68:71], v[168:171], v[226:229], v[68:71]
	v_mfma_f32_16x16x32_bf16 v[64:67], v[180:183], v[226:229], v[64:67]
	s_barrier
; #define PG8_STAGE(bufoff, gbase, voff) do { _Pragma("unroll") for (int _i = 0; _i < 2; ++_i) \
;         __builtin_amdgcn_global_load_lds((const unsigned*)((const char*)(gbase) + (voff)[_i]), (LAS unsigned*)(lds + (bufoff) + ldsw + _i * 8192), 16, 0, 0); } while (0)
; #define PG8_LDA(dst, b, h) do { _Pragma("unroll") for (int m = 0; m < 4; ++m) _Pragma("unroll") for (int k = 0; k < 2; ++k) dst[m][k] = *(const LAS bf16x8*)(lds + PG8_SA(b, h) + aoff + m * 2048 + k * 1024); } while (0)
; #define PG8_MMA(ai, bj, At, Bt) do { __builtin_amdgcn_s_setprio(1); _Pragma("unroll") for (int m = 0; m < 4; ++m) _Pragma("unroll") for (int n = 0; n < 2; ++n) _Pragma("unroll") for (int k = 0; k < 2; ++k) \
;         acc[ai][bj][m][n] = __builtin_amdgcn_mfma_f32_16x16x32_bf16(Bt[n][k], At[m][k], acc[ai][bj][m][n], 0, 0, 0); __builtin_amdgcn_s_setprio(0); } while (0)
; #define PG8_WAIT_V(n) asm volatile("s_waitcnt vmcnt(" #n ")" ::: "memory")
; #define PG8_WAIT_L(n) asm volatile("s_waitcnt lgkmcnt(" #n ")" ::: "memory")
; #define PG8_BAR __builtin_amdgcn_s_barrier()
; #define PG8_SCHED __builtin_amdgcn_sched_barrier(0)
; template <class Epi>
; __device__ __forceinline__ void gemm_phase(LAS unsigned char* lds, const GemmD g, const Epi& E, int G, int c) {
;     ...
;             PG8_LDA(At, 1, 1); PG8_STAGE(PG8_SB(1, 0), b3, voffB); PG8_STAGE(PG8_SB(1, 1), b3 + hstepB, voffB); PG8_STAGE(PG8_SA(1, 0), a3, voffA);
;             PG8_WAIT_V(8); PG8_WAIT_L(0); PG8_BAR; PG8_MMA(1, 0, At, B0); PG8_MMA(1, 1, At, B1); PG8_BAR; PG8_SCHED;
;         }
;         if (wr == 0) PG8_BAR;
	s_setprio 0
	s_add_i32 s4, s35, s2
	v_lshl_add_u64 v[140:141], v[140:141], 0, s[48:49]
	s_mov_b32 m0, s4
	ds_read_b128 v[184:187], v145 offset:49152
	ds_read_b128 v[188:191], v145 offset:50176
	ds_read_b128 v[192:195], v145 offset:51200
	ds_read_b128 v[210:213], v145 offset:52224
	ds_read_b128 v[214:217], v145 offset:53248
	ds_read_b128 v[218:221], v145 offset:54272
	ds_read_b128 v[222:225], v145 offset:55296
	ds_read_b128 v[226:229], v145 offset:56320
	global_load_lds_dwordx4 v[140:141], off
	s_add_i32 m0, s4, 0x2000
	s_add_u32 s4, s84, 0x80080
	v_lshl_add_u64 v[140:141], v[198:199], 0, s[48:49]
	s_addc_u32 s5, s85, 0
	s_add_i32 s35, s36, s2
	global_load_lds_dwordx4 v[140:141], off
	v_lshl_add_u64 v[140:141], s[4:5], 0, v[178:179]
	s_mov_b32 m0, s35
	s_nop 0
	global_load_lds_dwordx4 v[140:141], off
	v_lshl_add_u64 v[140:141], s[4:5], 0, v[128:129]
	s_add_i32 m0, s35, 0x2000
	s_nop 0
	global_load_lds_dwordx4 v[140:141], off
	v_lshl_add_u64 v[140:141], v[230:231], 0, s[48:49]
	s_mov_b32 m0, s16
	s_nop 0
	global_load_lds_dwordx4 v[140:141], off
	v_lshl_add_u64 v[140:141], v[232:233], 0, s[48:49]
	s_mov_b32 m0, s17
	s_nop 0
	global_load_lds_dwordx4 v[140:141], off
	s_waitcnt vmcnt(8)
	s_waitcnt lgkmcnt(0)
	s_setprio 1
	s_barrier
	v_mfma_f32_16x16x32_bf16 v[56:59], v[148:151], v[184:187], v[56:59]
	v_mfma_f32_16x16x32_bf16 v[60:63], v[156:159], v[184:187], v[60:63]
	v_mfma_f32_16x16x32_bf16 v[40:43], v[148:151], v[192:195], v[40:43]
	v_mfma_f32_16x16x32_bf16 v[36:39], v[156:159], v[192:195], v[36:39]
	v_mfma_f32_16x16x32_bf16 v[28:31], v[148:151], v[214:217], v[28:31]
	v_mfma_f32_16x16x32_bf16 v[24:27], v[156:159], v[214:217], v[24:27]
	v_mfma_f32_16x16x32_bf16 v[12:15], v[148:151], v[222:225], v[12:15]
	v_mfma_f32_16x16x32_bf16 v[8:11], v[156:159], v[222:225], v[8:11]
	v_mfma_f32_16x16x32_bf16 v[56:59], v[152:155], v[188:191], v[56:59]
	v_mfma_f32_16x16x32_bf16 v[60:63], v[160:163], v[188:191], v[60:63]
	v_mfma_f32_16x16x32_bf16 v[40:43], v[152:155], v[210:213], v[40:43]
	v_mfma_f32_16x16x32_bf16 v[36:39], v[160:163], v[210:213], v[36:39]
	v_mfma_f32_16x16x32_bf16 v[28:31], v[152:155], v[218:221], v[28:31]
	v_mfma_f32_16x16x32_bf16 v[24:27], v[160:163], v[218:221], v[24:27]
	v_mfma_f32_16x16x32_bf16 v[12:15], v[152:155], v[226:229], v[12:15]
	v_mfma_f32_16x16x32_bf16 v[8:11], v[160:163], v[226:229], v[8:11]
	s_setprio 0
	s_setprio 1
	v_mfma_f32_16x16x32_bf16 v[52:55], v[164:167], v[184:187], v[52:55]
	v_mfma_f32_16x16x32_bf16 v[48:51], v[172:175], v[184:187], v[48:51]
	v_mfma_f32_16x16x32_bf16 v[44:47], v[164:167], v[192:195], v[44:47]
	v_mfma_f32_16x16x32_bf16 v[32:35], v[172:175], v[192:195], v[32:35]
	v_mfma_f32_16x16x32_bf16 v[20:23], v[164:167], v[214:217], v[20:23]
	v_mfma_f32_16x16x32_bf16 v[16:19], v[172:175], v[214:217], v[16:19]
	v_mfma_f32_16x16x32_bf16 v[4:7], v[164:167], v[222:225], v[4:7]
	v_mfma_f32_16x16x32_bf16 v[0:3], v[172:175], v[222:225], v[0:3]
	v_mfma_f32_16x16x32_bf16 v[52:55], v[168:171], v[188:191], v[52:55]
	v_mfma_f32_16x16x32_bf16 v[48:51], v[180:183], v[188:191], v[48:51]
	v_mfma_f32_16x16x32_bf16 v[44:47], v[168:171], v[210:213], v[44:47]
	v_mfma_f32_16x16x32_bf16 v[32:35], v[180:183], v[210:213], v[32:35]
	v_mfma_f32_16x16x32_bf16 v[20:23], v[168:171], v[218:221], v[20:23]
	v_mfma_f32_16x16x32_bf16 v[16:19], v[180:183], v[218:221], v[16:19]
	v_mfma_f32_16x16x32_bf16 v[4:7], v[168:171], v[226:229], v[4:7]
	v_mfma_f32_16x16x32_bf16 v[0:3], v[180:183], v[226:229], v[0:3]
	s_barrier
	s_setprio 0
	s_add_i32 s33, s33, 2
	s_add_u32 s86, s86, 0x100
	s_addc_u32 s87, s87, 0
	s_add_u32 s30, s30, 0x100
	s_addc_u32 s31, s31, 0
	s_cmp_gt_u32 s33, 29
	s_cbranch_scc0 .LBB0_224
	s_and_b64 vcc, exec, s[46:47]
	s_cbranch_vccz .LBB0_227
	s_barrier

; #define PG8_STAGE(bufoff, gbase, voff) do { _Pragma("unroll") for (int _i = 0; _i < 2; ++_i) \
;         __builtin_amdgcn_global_load_lds((const unsigned*)((const char*)(gbase) + (voff)[_i]), (LAS unsigned*)(lds + (bufoff) + ldsw + _i * 8192), 16, 0, 0); } while (0)
; #define PG8_LDA(dst, b, h) do { _Pragma("unroll") for (int m = 0; m < 4; ++m) _Pragma("unroll") for (int k = 0; k < 2; ++k) dst[m][k] = *(const LAS bf16x8*)(lds + PG8_SA(b, h) + aoff + m * 2048 + k * 1024); } while (0)
; #define PG8_MMA(ai, bj, At, Bt) do { __builtin_amdgcn_s_setprio(1); _Pragma("unroll") for (int m = 0; m < 4; ++m) _Pragma("unroll") for (int n = 0; n < 2; ++n) _Pragma("unroll") for (int k = 0; k < 2; ++k) \
;         acc[ai][bj][m][n] = __builtin_amdgcn_mfma_f32_16x16x32_bf16(Bt[n][k], At[m][k], acc[ai][bj][m][n], 0, 0, 0); __builtin_amdgcn_s_setprio(0); } while (0)
; #define PG8_WAIT_V(n) asm volatile("s_waitcnt vmcnt(" #n ")" ::: "memory")
; #define PG8_WAIT_L(n) asm volatile("s_waitcnt lgkmcnt(" #n ")" ::: "memory")
; #define PG8_BAR __builtin_amdgcn_s_barrier()
; #define PG8_SCHED __builtin_amdgcn_sched_barrier(0)
; template <class Epi>
; __device__ __forceinline__ void gemm_phase(LAS unsigned char* lds, const GemmD g, const Epi& E, int G, int c) {
;     ...
;             PG8_WAIT_V(8); PG8_WAIT_L(0); PG8_BAR; PG8_MMA(0, 0, At, B0); PG8_MMA(0, 1, At, B1); PG8_BAR; PG8_SCHED;
;             PG8_LDA(At, 0, 1); PG8_STAGE(PG8_SB(0, 0), b2, voffB); PG8_STAGE(PG8_SB(0, 1), b2 + hstepB, voffB); PG8_STAGE(PG8_SA(0, 0), a2, voffA);
;             PG8_WAIT_V(8); PG8_WAIT_L(0); PG8_BAR; PG8_MMA(1, 0, At, B0); PG8_MMA(1, 1, At, B1); PG8_BAR; PG8_SCHED;
.Lrw_Glu_0_d:
	s_waitcnt lgkmcnt(0)
	s_setprio 1
	s_barrier
	v_mfma_f32_16x16x32_bf16 v[140:143], v[24:27], v[160:163], v[140:143]
	v_mfma_f32_16x16x32_bf16 v[136:139], v[36:39], v[160:163], v[136:139]
	v_mfma_f32_16x16x32_bf16 v[124:127], v[24:27], v[168:171], v[124:127]
	v_mfma_f32_16x16x32_bf16 v[120:123], v[36:39], v[168:171], v[120:123]
	v_mfma_f32_16x16x32_bf16 v[108:111], v[24:27], v[190:193], v[108:111]
	v_mfma_f32_16x16x32_bf16 v[104:107], v[36:39], v[190:193], v[104:107]
	v_mfma_f32_16x16x32_bf16 v[92:95], v[24:27], v[218:221], v[92:95]
	v_mfma_f32_16x16x32_bf16 v[88:91], v[36:39], v[218:221], v[88:91]
	v_mfma_f32_16x16x32_bf16 v[140:143], v[28:31], v[164:167], v[140:143]
	v_mfma_f32_16x16x32_bf16 v[136:139], v[44:47], v[164:167], v[136:139]
	v_mfma_f32_16x16x32_bf16 v[124:127], v[28:31], v[172:175], v[124:127]
	v_mfma_f32_16x16x32_bf16 v[120:123], v[44:47], v[172:175], v[120:123]
	v_mfma_f32_16x16x32_bf16 v[108:111], v[28:31], v[214:217], v[108:111]
	v_mfma_f32_16x16x32_bf16 v[104:107], v[44:47], v[214:217], v[104:107]
	v_mfma_f32_16x16x32_bf16 v[92:95], v[28:31], v[222:225], v[92:95]
	v_mfma_f32_16x16x32_bf16 v[88:91], v[44:47], v[222:225], v[88:91]
	s_setprio 0
	s_setprio 1
	v_mfma_f32_16x16x32_bf16 v[132:135], v[144:147], v[160:163], v[132:135]
	v_mfma_f32_16x16x32_bf16 v[128:131], v[152:155], v[160:163], v[128:131]
	v_mfma_f32_16x16x32_bf16 v[116:119], v[144:147], v[168:171], v[116:119]
	v_mfma_f32_16x16x32_bf16 v[112:115], v[152:155], v[168:171], v[112:115]
	v_mfma_f32_16x16x32_bf16 v[100:103], v[144:147], v[190:193], v[100:103]
	v_mfma_f32_16x16x32_bf16 v[96:99], v[152:155], v[190:193], v[96:99]
	v_mfma_f32_16x16x32_bf16 v[84:87], v[144:147], v[218:221], v[84:87]
	v_mfma_f32_16x16x32_bf16 v[80:83], v[152:155], v[218:221], v[80:83]
	v_mfma_f32_16x16x32_bf16 v[132:135], v[148:151], v[164:167], v[132:135]
	v_mfma_f32_16x16x32_bf16 v[128:131], v[156:159], v[164:167], v[128:131]
	v_mfma_f32_16x16x32_bf16 v[116:119], v[148:151], v[172:175], v[116:119]
	v_mfma_f32_16x16x32_bf16 v[112:115], v[156:159], v[172:175], v[112:115]
	v_mfma_f32_16x16x32_bf16 v[100:103], v[148:151], v[214:217], v[100:103]
	v_mfma_f32_16x16x32_bf16 v[96:99], v[156:159], v[214:217], v[96:99]
	v_mfma_f32_16x16x32_bf16 v[84:87], v[148:151], v[222:225], v[84:87]
	v_mfma_f32_16x16x32_bf16 v[80:83], v[156:159], v[222:225], v[80:83]
	s_barrier
	s_setprio 0
	s_add_i32 s28, s28, s16
	v_lshl_add_u64 v[194:195], s[88:89], 0, v[178:179]
	s_mov_b32 m0, s28
	ds_read_b128 v[160:163], v212 offset:16384
	ds_read_b128 v[164:167], v212 offset:17408
	ds_read_b128 v[168:171], v212 offset:18432
	ds_read_b128 v[172:175], v212 offset:19456
	ds_read_b128 v[190:193], v212 offset:20480
	ds_read_b128 v[214:217], v212 offset:21504
	ds_read_b128 v[218:221], v212 offset:22528
	ds_read_b128 v[222:225], v212 offset:23552
	global_load_lds_dwordx4 v[194:195], off
	s_add_i32 m0, s28, 0x2000
	s_add_u32 s28, s88, 0x80000
	v_lshl_add_u64 v[198:199], s[88:89], 0, v[180:181]
	s_addc_u32 s29, s89, 0
	s_add_i32 s31, s31, s16
	global_load_lds_dwordx4 v[198:199], off
	v_lshl_add_u64 v[226:227], s[28:29], 0, v[178:179]
	s_mov_b32 m0, s31
	v_lshl_add_u64 v[228:229], s[4:5], 0, v[182:183]
	global_load_lds_dwordx4 v[226:227], off
	v_lshl_add_u64 v[226:227], s[28:29], 0, v[180:181]
	s_add_i32 m0, s31, 0x2000
	s_nop 0
	global_load_lds_dwordx4 v[226:227], off
	v_lshl_add_u64 v[226:227], s[4:5], 0, v[184:185]
	s_mov_b32 m0, s23
	s_nop 0
	global_load_lds_dwordx4 v[226:227], off
	s_mov_b32 m0, s26
	s_nop 0
	global_load_lds_dwordx4 v[228:229], off
	s_cmp_lg_u32 s99, 0
	s_cbranch_scc1 .Lrw_Glu_1_r
	s_waitcnt vmcnt(8)
	s_branch .Lrw_Glu_1_d

; #define PG8_STAGE(bufoff, gbase, voff) do { _Pragma("unroll") for (int _i = 0; _i < 2; ++_i) \
;         __builtin_amdgcn_global_load_lds((const unsigned*)((const char*)(gbase) + (voff)[_i]), (LAS unsigned*)(lds + (bufoff) + ldsw + _i * 8192), 16, 0, 0); } while (0)
; #define PG8_LDA(dst, b, h) do { _Pragma("unroll") for (int m = 0; m < 4; ++m) _Pragma("unroll") for (int k = 0; k < 2; ++k) dst[m][k] = *(const LAS bf16x8*)(lds + PG8_SA(b, h) + aoff + m * 2048 + k * 1024); } while (0)
; #define PG8_LDB(dst, b, h) do { _Pragma("unroll") for (int n = 0; n < 2; ++n) _Pragma("unroll") for (int k = 0; k < 2; ++k) dst[n][k] = *(const LAS bf16x8*)(lds + PG8_SB(b, h) + boff + n * 2048 + k * 1024); } while (0)
; #define PG8_MMA(ai, bj, At, Bt) do { __builtin_amdgcn_s_setprio(1); _Pragma("unroll") for (int m = 0; m < 4; ++m) _Pragma("unroll") for (int n = 0; n < 2; ++n) _Pragma("unroll") for (int k = 0; k < 2; ++k) \
;         acc[ai][bj][m][n] = __builtin_amdgcn_mfma_f32_16x16x32_bf16(Bt[n][k], At[m][k], acc[ai][bj][m][n], 0, 0, 0); __builtin_amdgcn_s_setprio(0); } while (0)
; #define PG8_WAIT_V(n) asm volatile("s_waitcnt vmcnt(" #n ")" ::: "memory")
; #define PG8_WAIT_L(n) asm volatile("s_waitcnt lgkmcnt(" #n ")" ::: "memory")
; #define PG8_BAR __builtin_amdgcn_s_barrier()
; #define PG8_SCHED __builtin_amdgcn_sched_barrier(0)
; template <class Epi>
; __device__ __forceinline__ void gemm_phase(LAS unsigned char* lds, const GemmD g, const Epi& E, int G, int c) {
;     ...
;             PG8_WAIT_V(8); PG8_WAIT_L(0); PG8_BAR; PG8_MMA(1, 0, At, B0); PG8_MMA(1, 1, At, B1); PG8_BAR; PG8_SCHED;
;             PG8_LDB(B0, 1, 0); PG8_LDB(B1, 1, 1); PG8_SCHED; PG8_LDA(At, 1, 0); PG8_STAGE(PG8_SA(0, 1), a2 + hstepA, voffA);
;             PG8_WAIT_V(8); PG8_WAIT_L(0); PG8_BAR; PG8_MMA(0, 0, At, B0); PG8_MMA(0, 1, At, B1); PG8_BAR; PG8_SCHED;
.Lrw_Glu_1_d:
	s_waitcnt lgkmcnt(0)
	s_setprio 1
	s_barrier
	v_mfma_f32_16x16x32_bf16 v[76:79], v[24:27], v[160:163], v[76:79]
	v_mfma_f32_16x16x32_bf16 v[72:75], v[36:39], v[160:163], v[72:75]
	v_mfma_f32_16x16x32_bf16 v[60:63], v[24:27], v[168:171], v[60:63]
	v_mfma_f32_16x16x32_bf16 v[56:59], v[36:39], v[168:171], v[56:59]
	v_mfma_f32_16x16x32_bf16 v[40:43], v[24:27], v[190:193], v[40:43]
	v_mfma_f32_16x16x32_bf16 v[32:35], v[36:39], v[190:193], v[32:35]
	v_mfma_f32_16x16x32_bf16 v[12:15], v[24:27], v[218:221], v[12:15]
	v_mfma_f32_16x16x32_bf16 v[8:11], v[36:39], v[218:221], v[8:11]
	v_mfma_f32_16x16x32_bf16 v[76:79], v[28:31], v[164:167], v[76:79]
	v_mfma_f32_16x16x32_bf16 v[72:75], v[44:47], v[164:167], v[72:75]
	v_mfma_f32_16x16x32_bf16 v[60:63], v[28:31], v[172:175], v[60:63]
	v_mfma_f32_16x16x32_bf16 v[56:59], v[44:47], v[172:175], v[56:59]
	v_mfma_f32_16x16x32_bf16 v[40:43], v[28:31], v[214:217], v[40:43]
	v_mfma_f32_16x16x32_bf16 v[32:35], v[44:47], v[214:217], v[32:35]
	v_mfma_f32_16x16x32_bf16 v[12:15], v[28:31], v[222:225], v[12:15]
	v_mfma_f32_16x16x32_bf16 v[8:11], v[44:47], v[222:225], v[8:11]
	s_setprio 0
	s_setprio 1
	v_mfma_f32_16x16x32_bf16 v[20:23], v[144:147], v[190:193], v[20:23]
	v_mfma_f32_16x16x32_bf16 v[16:19], v[152:155], v[190:193], v[16:19]
	v_mfma_f32_16x16x32_bf16 v[4:7], v[144:147], v[218:221], v[4:7]
	v_mfma_f32_16x16x32_bf16 v[0:3], v[152:155], v[218:221], v[0:3]
	v_mfma_f32_16x16x32_bf16 v[24:27], v[144:147], v[160:163], v[68:71]
	v_mfma_f32_16x16x32_bf16 v[28:31], v[152:155], v[160:163], v[64:67]
	v_mfma_f32_16x16x32_bf16 v[36:39], v[144:147], v[168:171], v[52:55]
	v_mfma_f32_16x16x32_bf16 v[44:47], v[152:155], v[168:171], v[48:51]
	v_mfma_f32_16x16x32_bf16 v[20:23], v[148:151], v[214:217], v[20:23]
	v_mfma_f32_16x16x32_bf16 v[16:19], v[156:159], v[214:217], v[16:19]
	v_mfma_f32_16x16x32_bf16 v[4:7], v[148:151], v[222:225], v[4:7]
	v_mfma_f32_16x16x32_bf16 v[0:3], v[156:159], v[222:225], v[0:3]
	v_mfma_f32_16x16x32_bf16 v[24:27], v[148:151], v[164:167], v[24:27]
	v_mfma_f32_16x16x32_bf16 v[28:31], v[156:159], v[164:167], v[28:31]
	v_mfma_f32_16x16x32_bf16 v[36:39], v[148:151], v[172:175], v[36:39]
	v_mfma_f32_16x16x32_bf16 v[44:47], v[156:159], v[172:175], v[44:47]
	s_barrier
	s_setprio 0
	s_add_i32 s28, 0, 0x18000
	s_add_i32 s29, 0, 0x1c000
	v_add_u32_e32 v68, s28, v210
	v_add_u32_e32 v156, s29, v210
	ds_read_b128 v[48:51], v68
	ds_read_b128 v[52:55], v68 offset:1024
	ds_read_b128 v[64:67], v68 offset:2048
	ds_read_b128 v[68:71], v68 offset:3072
	ds_read_b128 v[144:147], v156
	ds_read_b128 v[148:151], v156 offset:1024
	ds_read_b128 v[152:155], v156 offset:2048
	ds_read_b128 v[156:159], v156 offset:3072
	s_add_u32 s4, s4, 0x80000
	s_addc_u32 s5, s5, 0
	s_mov_b32 m0, s30
	v_lshl_add_u64 v[230:231], s[4:5], 0, v[184:185]
	ds_read_b128 v[160:163], v212 offset:32768
	ds_read_b128 v[164:167], v212 offset:33792
	ds_read_b128 v[168:171], v212 offset:34816
	ds_read_b128 v[172:175], v212 offset:35840
	ds_read_b128 v[190:193], v212 offset:36864
	ds_read_b128 v[214:217], v212 offset:37888
	ds_read_b128 v[218:221], v212 offset:38912
	ds_read_b128 v[222:225], v212 offset:39936
	global_load_lds_dwordx4 v[230:231], off
	v_lshl_add_u64 v[230:231], s[4:5], 0, v[182:183]
	s_mov_b32 m0, s35
	s_nop 0
	global_load_lds_dwordx4 v[230:231], off
	s_waitcnt vmcnt(8)
	s_waitcnt lgkmcnt(0)
	s_setprio 1
	s_barrier
	v_mfma_f32_16x16x32_bf16 v[140:143], v[48:51], v[160:163], v[140:143]
	v_mfma_f32_16x16x32_bf16 v[136:139], v[64:67], v[160:163], v[136:139]
	v_mfma_f32_16x16x32_bf16 v[124:127], v[48:51], v[168:171], v[124:127]
	v_mfma_f32_16x16x32_bf16 v[120:123], v[64:67], v[168:171], v[120:123]
	v_mfma_f32_16x16x32_bf16 v[108:111], v[48:51], v[190:193], v[108:111]
	v_mfma_f32_16x16x32_bf16 v[104:107], v[64:67], v[190:193], v[104:107]
	v_mfma_f32_16x16x32_bf16 v[92:95], v[48:51], v[218:221], v[92:95]
	v_mfma_f32_16x16x32_bf16 v[88:91], v[64:67], v[218:221], v[88:91]
	v_mfma_f32_16x16x32_bf16 v[140:143], v[52:55], v[164:167], v[140:143]
	v_mfma_f32_16x16x32_bf16 v[136:139], v[68:71], v[164:167], v[136:139]
	v_mfma_f32_16x16x32_bf16 v[124:127], v[52:55], v[172:175], v[124:127]
	v_mfma_f32_16x16x32_bf16 v[120:123], v[68:71], v[172:175], v[120:123]
	v_mfma_f32_16x16x32_bf16 v[108:111], v[52:55], v[214:217], v[108:111]
	v_mfma_f32_16x16x32_bf16 v[104:107], v[68:71], v[214:217], v[104:107]
	v_mfma_f32_16x16x32_bf16 v[92:95], v[52:55], v[222:225], v[92:95]
	v_mfma_f32_16x16x32_bf16 v[88:91], v[68:71], v[222:225], v[88:91]
	s_setprio 0
	s_setprio 1
	v_mfma_f32_16x16x32_bf16 v[132:135], v[144:147], v[160:163], v[132:135]
	v_mfma_f32_16x16x32_bf16 v[128:131], v[152:155], v[160:163], v[128:131]
	v_mfma_f32_16x16x32_bf16 v[116:119], v[144:147], v[168:171], v[116:119]
	v_mfma_f32_16x16x32_bf16 v[112:115], v[152:155], v[168:171], v[112:115]
	v_mfma_f32_16x16x32_bf16 v[100:103], v[144:147], v[190:193], v[100:103]
	v_mfma_f32_16x16x32_bf16 v[96:99], v[152:155], v[190:193], v[96:99]
	v_mfma_f32_16x16x32_bf16 v[84:87], v[144:147], v[218:221], v[84:87]
	v_mfma_f32_16x16x32_bf16 v[80:83], v[152:155], v[218:221], v[80:83]
	v_mfma_f32_16x16x32_bf16 v[132:135], v[148:151], v[164:167], v[132:135]
	v_mfma_f32_16x16x32_bf16 v[128:131], v[156:159], v[164:167], v[128:131]
	v_mfma_f32_16x16x32_bf16 v[116:119], v[148:151], v[172:175], v[116:119]
	v_mfma_f32_16x16x32_bf16 v[112:115], v[156:159], v[172:175], v[112:115]
	v_mfma_f32_16x16x32_bf16 v[100:103], v[148:151], v[214:217], v[100:103]
	v_mfma_f32_16x16x32_bf16 v[96:99], v[156:159], v[214:217], v[96:99]
	v_mfma_f32_16x16x32_bf16 v[84:87], v[148:151], v[222:225], v[84:87]
	v_mfma_f32_16x16x32_bf16 v[80:83], v[156:159], v[222:225], v[80:83]
	s_barrier
; #define PG8_STAGE(bufoff, gbase, voff) do { _Pragma("unroll") for (int _i = 0; _i < 2; ++_i) \
;         __builtin_amdgcn_global_load_lds((const unsigned*)((const char*)(gbase) + (voff)[_i]), (LAS unsigned*)(lds + (bufoff) + ldsw + _i * 8192), 16, 0, 0); } while (0)
; #define PG8_LDA(dst, b, h) do { _Pragma("unroll") for (int m = 0; m < 4; ++m) _Pragma("unroll") for (int k = 0; k < 2; ++k) dst[m][k] = *(const LAS bf16x8*)(lds + PG8_SA(b, h) + aoff + m * 2048 + k * 1024); } while (0)
; #define PG8_MMA(ai, bj, At, Bt) do { __builtin_amdgcn_s_setprio(1); _Pragma("unroll") for (int m = 0; m < 4; ++m) _Pragma("unroll") for (int n = 0; n < 2; ++n) _Pragma("unroll") for (int k = 0; k < 2; ++k) \
;         acc[ai][bj][m][n] = __builtin_amdgcn_mfma_f32_16x16x32_bf16(Bt[n][k], At[m][k], acc[ai][bj][m][n], 0, 0, 0); __builtin_amdgcn_s_setprio(0); } while (0)
; #define PG8_WAIT_V(n) asm volatile("s_waitcnt vmcnt(" #n ")" ::: "memory")
; #define PG8_WAIT_L(n) asm volatile("s_waitcnt lgkmcnt(" #n ")" ::: "memory")
; #define PG8_BAR __builtin_amdgcn_s_barrier()
; #define PG8_SCHED __builtin_amdgcn_sched_barrier(0)
; template <class Epi>
; __device__ __forceinline__ void gemm_phase(LAS unsigned char* lds, const GemmD g, const Epi& E, int G, int c) {
;     ...
;             PG8_LDA(At, 1, 1); PG8_STAGE(PG8_SB(1, 0), b3, voffB); PG8_STAGE(PG8_SB(1, 1), b3 + hstepB, voffB); PG8_STAGE(PG8_SA(1, 0), a3, voffA);
;             PG8_WAIT_V(8); PG8_WAIT_L(0); PG8_BAR; PG8_MMA(1, 0, At, B0); PG8_MMA(1, 1, At, B1); PG8_BAR; PG8_SCHED;
;         }
;         if (wr == 0) PG8_BAR;
	s_setprio 0
	s_add_i32 s4, s28, s16
	v_lshl_add_u64 v[194:195], v[194:195], 0, s[48:49]
	s_mov_b32 m0, s4
	ds_read_b128 v[160:163], v212 offset:49152
	ds_read_b128 v[164:167], v212 offset:50176
	ds_read_b128 v[168:171], v212 offset:51200
	ds_read_b128 v[172:175], v212 offset:52224
	ds_read_b128 v[190:193], v212 offset:53248
	ds_read_b128 v[214:217], v212 offset:54272
	ds_read_b128 v[218:221], v212 offset:55296
	ds_read_b128 v[222:225], v212 offset:56320
	global_load_lds_dwordx4 v[194:195], off
	s_add_i32 m0, s4, 0x2000
	s_add_u32 s4, s88, 0x80080
	v_lshl_add_u64 v[194:195], v[198:199], 0, s[48:49]
	s_addc_u32 s5, s89, 0
	s_add_i32 s28, s29, s16
	global_load_lds_dwordx4 v[194:195], off
	v_lshl_add_u64 v[194:195], s[4:5], 0, v[178:179]
	s_mov_b32 m0, s28
	s_nop 0
	global_load_lds_dwordx4 v[194:195], off
	v_lshl_add_u64 v[194:195], s[4:5], 0, v[180:181]
	s_add_i32 m0, s28, 0x2000
	s_nop 0
	global_load_lds_dwordx4 v[194:195], off
	v_lshl_add_u64 v[194:195], v[226:227], 0, s[48:49]
	s_mov_b32 m0, s36
	s_nop 0
	global_load_lds_dwordx4 v[194:195], off
	v_lshl_add_u64 v[194:195], v[228:229], 0, s[48:49]
	s_mov_b32 m0, s90
	s_nop 0
	global_load_lds_dwordx4 v[194:195], off
	s_waitcnt vmcnt(8)
	s_waitcnt lgkmcnt(0)
	s_setprio 1
	s_barrier
	v_mfma_f32_16x16x32_bf16 v[76:79], v[48:51], v[160:163], v[76:79]
	v_mfma_f32_16x16x32_bf16 v[72:75], v[64:67], v[160:163], v[72:75]
	v_mfma_f32_16x16x32_bf16 v[60:63], v[48:51], v[168:171], v[60:63]
	v_mfma_f32_16x16x32_bf16 v[56:59], v[64:67], v[168:171], v[56:59]
	v_mfma_f32_16x16x32_bf16 v[40:43], v[48:51], v[190:193], v[40:43]
	v_mfma_f32_16x16x32_bf16 v[32:35], v[64:67], v[190:193], v[32:35]
	v_mfma_f32_16x16x32_bf16 v[12:15], v[48:51], v[218:221], v[12:15]
	v_mfma_f32_16x16x32_bf16 v[8:11], v[64:67], v[218:221], v[8:11]
	v_mfma_f32_16x16x32_bf16 v[76:79], v[52:55], v[164:167], v[76:79]
	v_mfma_f32_16x16x32_bf16 v[72:75], v[68:71], v[164:167], v[72:75]
	v_mfma_f32_16x16x32_bf16 v[60:63], v[52:55], v[172:175], v[60:63]
	v_mfma_f32_16x16x32_bf16 v[56:59], v[68:71], v[172:175], v[56:59]
	v_mfma_f32_16x16x32_bf16 v[40:43], v[52:55], v[214:217], v[40:43]
	v_mfma_f32_16x16x32_bf16 v[32:35], v[68:71], v[214:217], v[32:35]
	v_mfma_f32_16x16x32_bf16 v[12:15], v[52:55], v[222:225], v[12:15]
	v_mfma_f32_16x16x32_bf16 v[8:11], v[68:71], v[222:225], v[8:11]
	s_setprio 0
	s_setprio 1
	v_mfma_f32_16x16x32_bf16 v[24:27], v[144:147], v[160:163], v[24:27]
	v_mfma_f32_16x16x32_bf16 v[68:71], v[148:151], v[164:167], v[24:27]
	v_mfma_f32_16x16x32_bf16 v[24:27], v[152:155], v[160:163], v[28:31]
	v_mfma_f32_16x16x32_bf16 v[64:67], v[156:159], v[164:167], v[24:27]
	v_mfma_f32_16x16x32_bf16 v[24:27], v[144:147], v[168:171], v[36:39]
	v_mfma_f32_16x16x32_bf16 v[52:55], v[148:151], v[172:175], v[24:27]
	v_mfma_f32_16x16x32_bf16 v[24:27], v[152:155], v[168:171], v[44:47]
	v_mfma_f32_16x16x32_bf16 v[20:23], v[144:147], v[190:193], v[20:23]
	v_mfma_f32_16x16x32_bf16 v[16:19], v[152:155], v[190:193], v[16:19]
	v_mfma_f32_16x16x32_bf16 v[4:7], v[144:147], v[218:221], v[4:7]
	v_mfma_f32_16x16x32_bf16 v[0:3], v[152:155], v[218:221], v[0:3]
	v_mfma_f32_16x16x32_bf16 v[48:51], v[156:159], v[172:175], v[24:27]
	v_mfma_f32_16x16x32_bf16 v[20:23], v[148:151], v[214:217], v[20:23]
	v_mfma_f32_16x16x32_bf16 v[16:19], v[156:159], v[214:217], v[16:19]
	v_mfma_f32_16x16x32_bf16 v[4:7], v[148:151], v[222:225], v[4:7]
	v_mfma_f32_16x16x32_bf16 v[0:3], v[156:159], v[222:225], v[0:3]
	s_barrier
	s_setprio 0
	s_add_i32 s27, s27, 2
	s_add_u32 s42, s42, 0x100
	s_addc_u32 s43, s43, 0
	s_add_u32 s19, s19, 0x100
	s_addc_u32 s22, s22, 0
	s_cmp_gt_u32 s27, 29
	s_cbranch_scc0 .LBB0_271
	s_and_b64 vcc, exec, s[66:67]
	s_cbranch_vccz .LBB0_274
	s_barrier

; #define PG8_STAGE(bufoff, gbase, voff) do { _Pragma("unroll") for (int _i = 0; _i < 2; ++_i) \
;         __builtin_amdgcn_global_load_lds((const unsigned*)((const char*)(gbase) + (voff)[_i]), (LAS unsigned*)(lds + (bufoff) + ldsw + _i * 8192), 16, 0, 0); } while (0)
; #define PG8_LDA(dst, b, h) do { _Pragma("unroll") for (int m = 0; m < 4; ++m) _Pragma("unroll") for (int k = 0; k < 2; ++k) dst[m][k] = *(const LAS bf16x8*)(lds + PG8_SA(b, h) + aoff + m * 2048 + k * 1024); } while (0)
; #define PG8_MMA(ai, bj, At, Bt) do { __builtin_amdgcn_s_setprio(1); _Pragma("unroll") for (int m = 0; m < 4; ++m) _Pragma("unroll") for (int n = 0; n < 2; ++n) _Pragma("unroll") for (int k = 0; k < 2; ++k) \
;         acc[ai][bj][m][n] = __builtin_amdgcn_mfma_f32_16x16x32_bf16(Bt[n][k], At[m][k], acc[ai][bj][m][n], 0, 0, 0); __builtin_amdgcn_s_setprio(0); } while (0)
; #define PG8_WAIT_V(n) asm volatile("s_waitcnt vmcnt(" #n ")" ::: "memory")
; #define PG8_WAIT_L(n) asm volatile("s_waitcnt lgkmcnt(" #n ")" ::: "memory")
; #define PG8_BAR __builtin_amdgcn_s_barrier()
; #define PG8_SCHED __builtin_amdgcn_sched_barrier(0)
; template <class Epi>
; __device__ __forceinline__ void gemm_phase(LAS unsigned char* lds, const GemmD g, const Epi& E, int G, int c) {
;     ...
;             PG8_WAIT_V(8); PG8_WAIT_L(0); PG8_BAR; PG8_MMA(0, 0, At, B0); PG8_MMA(0, 1, At, B1); PG8_BAR; PG8_SCHED;
;             PG8_LDA(At, 0, 1); PG8_STAGE(PG8_SB(0, 0), b2, voffB); PG8_STAGE(PG8_SB(0, 1), b2 + hstepB, voffB); PG8_STAGE(PG8_SA(0, 0), a2, voffA);
;             PG8_WAIT_V(8); PG8_WAIT_L(0); PG8_BAR; PG8_MMA(1, 0, At, B0); PG8_MMA(1, 1, At, B1); PG8_BAR; PG8_SCHED;
.Lrw_PV_0_d:
	s_waitcnt lgkmcnt(0)
	s_setprio 1
	s_barrier
	v_mfma_f32_16x16x32_bf16 v[124:127], v[146:149], v[184:187], v[124:127]
	v_mfma_f32_16x16x32_bf16 v[120:123], v[154:157], v[184:187], v[120:123]
	v_mfma_f32_16x16x32_bf16 v[112:115], v[146:149], v[192:195], v[112:115]
	v_mfma_f32_16x16x32_bf16 v[104:107], v[154:157], v[192:195], v[104:107]
	v_mfma_f32_16x16x32_bf16 v[96:99], v[146:149], v[214:217], v[96:99]
	v_mfma_f32_16x16x32_bf16 v[88:91], v[154:157], v[214:217], v[88:91]
	v_mfma_f32_16x16x32_bf16 v[80:83], v[146:149], v[222:225], v[80:83]
	v_mfma_f32_16x16x32_bf16 v[72:75], v[154:157], v[222:225], v[72:75]
	v_mfma_f32_16x16x32_bf16 v[124:127], v[150:153], v[188:191], v[124:127]
	v_mfma_f32_16x16x32_bf16 v[120:123], v[158:161], v[188:191], v[120:123]
	v_mfma_f32_16x16x32_bf16 v[112:115], v[150:153], v[210:213], v[112:115]
	v_mfma_f32_16x16x32_bf16 v[104:107], v[158:161], v[210:213], v[104:107]
	v_mfma_f32_16x16x32_bf16 v[96:99], v[150:153], v[218:221], v[96:99]
	v_mfma_f32_16x16x32_bf16 v[88:91], v[158:161], v[218:221], v[88:91]
	v_mfma_f32_16x16x32_bf16 v[80:83], v[150:153], v[226:229], v[80:83]
	v_mfma_f32_16x16x32_bf16 v[72:75], v[158:161], v[226:229], v[72:75]
	s_setprio 0
	s_setprio 1
	v_mfma_f32_16x16x32_bf16 v[116:119], v[162:165], v[184:187], v[116:119]
	v_mfma_f32_16x16x32_bf16 v[108:111], v[170:173], v[184:187], v[108:111]
	v_mfma_f32_16x16x32_bf16 v[100:103], v[162:165], v[192:195], v[100:103]
	v_mfma_f32_16x16x32_bf16 v[92:95], v[170:173], v[192:195], v[92:95]
	v_mfma_f32_16x16x32_bf16 v[84:87], v[162:165], v[214:217], v[84:87]
	v_mfma_f32_16x16x32_bf16 v[76:79], v[170:173], v[214:217], v[76:79]
	v_mfma_f32_16x16x32_bf16 v[68:71], v[162:165], v[222:225], v[68:71]
	v_mfma_f32_16x16x32_bf16 v[64:67], v[170:173], v[222:225], v[64:67]
	v_mfma_f32_16x16x32_bf16 v[116:119], v[166:169], v[188:191], v[116:119]
	v_mfma_f32_16x16x32_bf16 v[108:111], v[180:183], v[188:191], v[108:111]
	v_mfma_f32_16x16x32_bf16 v[100:103], v[166:169], v[210:213], v[100:103]
	v_mfma_f32_16x16x32_bf16 v[92:95], v[180:183], v[210:213], v[92:95]
	v_mfma_f32_16x16x32_bf16 v[84:87], v[166:169], v[218:221], v[84:87]
	v_mfma_f32_16x16x32_bf16 v[76:79], v[180:183], v[218:221], v[76:79]
	v_mfma_f32_16x16x32_bf16 v[68:71], v[166:169], v[226:229], v[68:71]
	v_mfma_f32_16x16x32_bf16 v[64:67], v[180:183], v[226:229], v[64:67]
	s_barrier
	s_setprio 0
	s_add_i32 s31, s31, s2
	v_lshl_add_u64 v[138:139], s[84:85], 0, v[178:179]
	s_mov_b32 m0, s31
	ds_read_b128 v[184:187], v143 offset:16384
	ds_read_b128 v[188:191], v143 offset:17408
	ds_read_b128 v[192:195], v143 offset:18432
	ds_read_b128 v[210:213], v143 offset:19456
	ds_read_b128 v[214:217], v143 offset:20480
	ds_read_b128 v[218:221], v143 offset:21504
	ds_read_b128 v[222:225], v143 offset:22528
	ds_read_b128 v[226:229], v143 offset:23552
	global_load_lds_dwordx4 v[138:139], off
	s_add_i32 m0, s31, 0x2000
	s_add_u32 s38, s84, 0x400000
	v_lshl_add_u64 v[174:175], s[84:85], 0, v[128:129]
	s_addc_u32 s39, s85, 0
	s_add_i32 s31, s33, s2
	global_load_lds_dwordx4 v[174:175], off
	v_lshl_add_u64 v[198:199], s[38:39], 0, v[178:179]
	s_mov_b32 m0, s31
	v_lshl_add_u64 v[230:231], s[4:5], 0, v[130:131]
	global_load_lds_dwordx4 v[198:199], off
	v_lshl_add_u64 v[198:199], s[38:39], 0, v[128:129]
	s_add_i32 m0, s31, 0x2000
	s_nop 0
	global_load_lds_dwordx4 v[198:199], off
	v_lshl_add_u64 v[198:199], s[4:5], 0, v[132:133]
	s_mov_b32 m0, s6
	s_nop 0
	global_load_lds_dwordx4 v[198:199], off
	s_mov_b32 m0, s9
	s_nop 0
	global_load_lds_dwordx4 v[230:231], off
	s_cmp_lg_u32 s99, 0
	s_cbranch_scc1 .Lrw_PV_1_r
	s_waitcnt vmcnt(8)
	s_branch .Lrw_PV_1_d

; #define PG8_STAGE(bufoff, gbase, voff) do { _Pragma("unroll") for (int _i = 0; _i < 2; ++_i) \
;         __builtin_amdgcn_global_load_lds((const unsigned*)((const char*)(gbase) + (voff)[_i]), (LAS unsigned*)(lds + (bufoff) + ldsw + _i * 8192), 16, 0, 0); } while (0)
; #define PG8_LDA(dst, b, h) do { _Pragma("unroll") for (int m = 0; m < 4; ++m) _Pragma("unroll") for (int k = 0; k < 2; ++k) dst[m][k] = *(const LAS bf16x8*)(lds + PG8_SA(b, h) + aoff + m * 2048 + k * 1024); } while (0)
; #define PG8_LDB(dst, b, h) do { _Pragma("unroll") for (int n = 0; n < 2; ++n) _Pragma("unroll") for (int k = 0; k < 2; ++k) dst[n][k] = *(const LAS bf16x8*)(lds + PG8_SB(b, h) + boff + n * 2048 + k * 1024); } while (0)
; #define PG8_MMA(ai, bj, At, Bt) do { __builtin_amdgcn_s_setprio(1); _Pragma("unroll") for (int m = 0; m < 4; ++m) _Pragma("unroll") for (int n = 0; n < 2; ++n) _Pragma("unroll") for (int k = 0; k < 2; ++k) \
;         acc[ai][bj][m][n] = __builtin_amdgcn_mfma_f32_16x16x32_bf16(Bt[n][k], At[m][k], acc[ai][bj][m][n], 0, 0, 0); __builtin_amdgcn_s_setprio(0); } while (0)
; #define PG8_WAIT_V(n) asm volatile("s_waitcnt vmcnt(" #n ")" ::: "memory")
; #define PG8_WAIT_L(n) asm volatile("s_waitcnt lgkmcnt(" #n ")" ::: "memory")
; #define PG8_BAR __builtin_amdgcn_s_barrier()
; #define PG8_SCHED __builtin_amdgcn_sched_barrier(0)
; template <class Epi>
; __device__ __forceinline__ void gemm_phase(LAS unsigned char* lds, const GemmD g, const Epi& E, int G, int c) {
;     ...
;             PG8_WAIT_V(8); PG8_WAIT_L(0); PG8_BAR; PG8_MMA(1, 0, At, B0); PG8_MMA(1, 1, At, B1); PG8_BAR; PG8_SCHED;
;             PG8_LDB(B0, 1, 0); PG8_LDB(B1, 1, 1); PG8_SCHED; PG8_LDA(At, 1, 0); PG8_STAGE(PG8_SA(0, 1), a2 + hstepA, voffA);
;             PG8_WAIT_V(8); PG8_WAIT_L(0); PG8_BAR; PG8_MMA(0, 0, At, B0); PG8_MMA(0, 1, At, B1); PG8_BAR; PG8_SCHED;
.Lrw_PV_1_d:
	s_waitcnt lgkmcnt(0)
	s_setprio 1
	s_barrier
	v_mfma_f32_16x16x32_bf16 v[60:63], v[146:149], v[184:187], v[60:63]
	v_mfma_f32_16x16x32_bf16 v[56:59], v[154:157], v[184:187], v[56:59]
	v_mfma_f32_16x16x32_bf16 v[52:55], v[146:149], v[192:195], v[52:55]
	v_mfma_f32_16x16x32_bf16 v[44:47], v[154:157], v[192:195], v[44:47]
	v_mfma_f32_16x16x32_bf16 v[36:39], v[146:149], v[214:217], v[36:39]
	v_mfma_f32_16x16x32_bf16 v[28:31], v[154:157], v[214:217], v[28:31]
	v_mfma_f32_16x16x32_bf16 v[20:23], v[146:149], v[222:225], v[20:23]
	v_mfma_f32_16x16x32_bf16 v[12:15], v[154:157], v[222:225], v[12:15]
	v_mfma_f32_16x16x32_bf16 v[60:63], v[150:153], v[188:191], v[60:63]
	v_mfma_f32_16x16x32_bf16 v[56:59], v[158:161], v[188:191], v[56:59]
	v_mfma_f32_16x16x32_bf16 v[52:55], v[150:153], v[210:213], v[52:55]
	v_mfma_f32_16x16x32_bf16 v[44:47], v[158:161], v[210:213], v[44:47]
	v_mfma_f32_16x16x32_bf16 v[36:39], v[150:153], v[218:221], v[36:39]
	v_mfma_f32_16x16x32_bf16 v[28:31], v[158:161], v[218:221], v[28:31]
	v_mfma_f32_16x16x32_bf16 v[20:23], v[150:153], v[226:229], v[20:23]
	v_mfma_f32_16x16x32_bf16 v[12:15], v[158:161], v[226:229], v[12:15]
	s_setprio 0
	s_setprio 1
	v_mfma_f32_16x16x32_bf16 v[48:51], v[162:165], v[184:187], v[48:51]
	v_mfma_f32_16x16x32_bf16 v[40:43], v[170:173], v[184:187], v[40:43]
	v_mfma_f32_16x16x32_bf16 v[32:35], v[162:165], v[192:195], v[32:35]
	v_mfma_f32_16x16x32_bf16 v[24:27], v[170:173], v[192:195], v[24:27]
	v_mfma_f32_16x16x32_bf16 v[16:19], v[162:165], v[214:217], v[16:19]
	v_mfma_f32_16x16x32_bf16 v[8:11], v[170:173], v[214:217], v[8:11]
	v_mfma_f32_16x16x32_bf16 v[4:7], v[162:165], v[222:225], v[4:7]
	v_mfma_f32_16x16x32_bf16 v[0:3], v[170:173], v[222:225], v[0:3]
	v_mfma_f32_16x16x32_bf16 v[48:51], v[166:169], v[188:191], v[48:51]
	v_mfma_f32_16x16x32_bf16 v[40:43], v[180:183], v[188:191], v[40:43]
	v_mfma_f32_16x16x32_bf16 v[32:35], v[166:169], v[210:213], v[32:35]
	v_mfma_f32_16x16x32_bf16 v[24:27], v[180:183], v[210:213], v[24:27]
	v_mfma_f32_16x16x32_bf16 v[16:19], v[166:169], v[218:221], v[16:19]
	v_mfma_f32_16x16x32_bf16 v[8:11], v[180:183], v[218:221], v[8:11]
	v_mfma_f32_16x16x32_bf16 v[4:7], v[166:169], v[226:229], v[4:7]
	v_mfma_f32_16x16x32_bf16 v[0:3], v[180:183], v[226:229], v[0:3]
	s_barrier
	s_setprio 0
	s_add_i32 s31, 0, 0x18000
	v_add_u32_e32 v145, s31, v141
	s_add_i32 s33, 0, 0x1c000
	ds_read_b128 v[146:149], v145
	ds_read_b128 v[150:153], v145 offset:1024
	ds_read_b128 v[154:157], v145 offset:2048
	ds_read_b128 v[158:161], v145 offset:3072
	v_add_u32_e32 v145, s33, v141
	ds_read_b128 v[162:165], v145
	ds_read_b128 v[166:169], v145 offset:1024
	ds_read_b128 v[170:173], v145 offset:2048
	ds_read_b128 v[180:183], v145 offset:3072
	s_add_u32 s4, s4, 0x80000
	s_addc_u32 s5, s5, 0
	s_mov_b32 m0, s10
	v_lshl_add_u64 v[232:233], s[4:5], 0, v[132:133]
	ds_read_b128 v[184:187], v143 offset:32768
	ds_read_b128 v[188:191], v143 offset:33792
	ds_read_b128 v[192:195], v143 offset:34816
	ds_read_b128 v[210:213], v143 offset:35840
	ds_read_b128 v[214:217], v143 offset:36864
	ds_read_b128 v[218:221], v143 offset:37888
	ds_read_b128 v[222:225], v143 offset:38912
	ds_read_b128 v[226:229], v143 offset:39936
	global_load_lds_dwordx4 v[232:233], off
	v_lshl_add_u64 v[232:233], s[4:5], 0, v[130:131]
	s_mov_b32 m0, s11
	s_nop 0
	global_load_lds_dwordx4 v[232:233], off
	s_waitcnt vmcnt(8)
	s_waitcnt lgkmcnt(0)
	s_setprio 1
	s_barrier
	v_mfma_f32_16x16x32_bf16 v[124:127], v[146:149], v[184:187], v[124:127]
	v_mfma_f32_16x16x32_bf16 v[120:123], v[154:157], v[184:187], v[120:123]
	v_mfma_f32_16x16x32_bf16 v[112:115], v[146:149], v[192:195], v[112:115]
	v_mfma_f32_16x16x32_bf16 v[104:107], v[154:157], v[192:195], v[104:107]
	v_mfma_f32_16x16x32_bf16 v[96:99], v[146:149], v[214:217], v[96:99]
	v_mfma_f32_16x16x32_bf16 v[88:91], v[154:157], v[214:217], v[88:91]
	v_mfma_f32_16x16x32_bf16 v[80:83], v[146:149], v[222:225], v[80:83]
	v_mfma_f32_16x16x32_bf16 v[72:75], v[154:157], v[222:225], v[72:75]
	v_mfma_f32_16x16x32_bf16 v[124:127], v[150:153], v[188:191], v[124:127]
	v_mfma_f32_16x16x32_bf16 v[120:123], v[158:161], v[188:191], v[120:123]
	v_mfma_f32_16x16x32_bf16 v[112:115], v[150:153], v[210:213], v[112:115]
	v_mfma_f32_16x16x32_bf16 v[104:107], v[158:161], v[210:213], v[104:107]
	v_mfma_f32_16x16x32_bf16 v[96:99], v[150:153], v[218:221], v[96:99]
	v_mfma_f32_16x16x32_bf16 v[88:91], v[158:161], v[218:221], v[88:91]
	v_mfma_f32_16x16x32_bf16 v[80:83], v[150:153], v[226:229], v[80:83]
	v_mfma_f32_16x16x32_bf16 v[72:75], v[158:161], v[226:229], v[72:75]
	s_setprio 0
	s_setprio 1
	v_mfma_f32_16x16x32_bf16 v[116:119], v[162:165], v[184:187], v[116:119]
	v_mfma_f32_16x16x32_bf16 v[108:111], v[170:173], v[184:187], v[108:111]
	v_mfma_f32_16x16x32_bf16 v[100:103], v[162:165], v[192:195], v[100:103]
	v_mfma_f32_16x16x32_bf16 v[92:95], v[170:173], v[192:195], v[92:95]
	v_mfma_f32_16x16x32_bf16 v[84:87], v[162:165], v[214:217], v[84:87]
	v_mfma_f32_16x16x32_bf16 v[76:79], v[170:173], v[214:217], v[76:79]
	v_mfma_f32_16x16x32_bf16 v[68:71], v[162:165], v[222:225], v[68:71]
	v_mfma_f32_16x16x32_bf16 v[64:67], v[170:173], v[222:225], v[64:67]
	v_mfma_f32_16x16x32_bf16 v[116:119], v[166:169], v[188:191], v[116:119]
	v_mfma_f32_16x16x32_bf16 v[108:111], v[180:183], v[188:191], v[108:111]
	v_mfma_f32_16x16x32_bf16 v[100:103], v[166:169], v[210:213], v[100:103]
	v_mfma_f32_16x16x32_bf16 v[92:95], v[180:183], v[210:213], v[92:95]
	v_mfma_f32_16x16x32_bf16 v[84:87], v[166:169], v[218:221], v[84:87]
	v_mfma_f32_16x16x32_bf16 v[76:79], v[180:183], v[218:221], v[76:79]
	v_mfma_f32_16x16x32_bf16 v[68:71], v[166:169], v[226:229], v[68:71]
	v_mfma_f32_16x16x32_bf16 v[64:67], v[180:183], v[226:229], v[64:67]
	s_barrier
; #define PG8_STAGE(bufoff, gbase, voff) do { _Pragma("unroll") for (int _i = 0; _i < 2; ++_i) \
;         __builtin_amdgcn_global_load_lds((const unsigned*)((const char*)(gbase) + (voff)[_i]), (LAS unsigned*)(lds + (bufoff) + ldsw + _i * 8192), 16, 0, 0); } while (0)
; #define PG8_LDA(dst, b, h) do { _Pragma("unroll") for (int m = 0; m < 4; ++m) _Pragma("unroll") for (int k = 0; k < 2; ++k) dst[m][k] = *(const LAS bf16x8*)(lds + PG8_SA(b, h) + aoff + m * 2048 + k * 1024); } while (0)
; #define PG8_MMA(ai, bj, At, Bt) do { __builtin_amdgcn_s_setprio(1); _Pragma("unroll") for (int m = 0; m < 4; ++m) _Pragma("unroll") for (int n = 0; n < 2; ++n) _Pragma("unroll") for (int k = 0; k < 2; ++k) \
;         acc[ai][bj][m][n] = __builtin_amdgcn_mfma_f32_16x16x32_bf16(Bt[n][k], At[m][k], acc[ai][bj][m][n], 0, 0, 0); __builtin_amdgcn_s_setprio(0); } while (0)
; #define PG8_WAIT_V(n) asm volatile("s_waitcnt vmcnt(" #n ")" ::: "memory")
; #define PG8_WAIT_L(n) asm volatile("s_waitcnt lgkmcnt(" #n ")" ::: "memory")
; #define PG8_BAR __builtin_amdgcn_s_barrier()
; #define PG8_SCHED __builtin_amdgcn_sched_barrier(0)
; template <class Epi>
; __device__ __forceinline__ void gemm_phase(LAS unsigned char* lds, const GemmD g, const Epi& E, int G, int c) {
;     ...
;             PG8_LDA(At, 1, 1); PG8_STAGE(PG8_SB(1, 0), b3, voffB); PG8_STAGE(PG8_SB(1, 1), b3 + hstepB, voffB); PG8_STAGE(PG8_SA(1, 0), a3, voffA);
;             PG8_WAIT_V(8); PG8_WAIT_L(0); PG8_BAR; PG8_MMA(1, 0, At, B0); PG8_MMA(1, 1, At, B1); PG8_BAR; PG8_SCHED;
;         }
;         if (wr == 0) PG8_BAR;
	s_setprio 0
	s_add_i32 s4, s31, s2
	v_lshl_add_u64 v[138:139], v[138:139], 0, s[48:49]
	s_mov_b32 m0, s4
	ds_read_b128 v[184:187], v143 offset:49152
	ds_read_b128 v[188:191], v143 offset:50176
	ds_read_b128 v[192:195], v143 offset:51200
	ds_read_b128 v[210:213], v143 offset:52224
	ds_read_b128 v[214:217], v143 offset:53248
	ds_read_b128 v[218:221], v143 offset:54272
	ds_read_b128 v[222:225], v143 offset:55296
	ds_read_b128 v[226:229], v143 offset:56320
	global_load_lds_dwordx4 v[138:139], off
	s_add_i32 m0, s4, 0x2000
	s_add_u32 s4, s84, 0x400080
	v_lshl_add_u64 v[138:139], v[174:175], 0, s[48:49]
	s_addc_u32 s5, s85, 0
	s_add_i32 s31, s33, s2
	global_load_lds_dwordx4 v[138:139], off
	v_lshl_add_u64 v[138:139], s[4:5], 0, v[178:179]
	s_mov_b32 m0, s31
	s_nop 0
	global_load_lds_dwordx4 v[138:139], off
	v_lshl_add_u64 v[138:139], s[4:5], 0, v[128:129]
	s_add_i32 m0, s31, 0x2000
	s_nop 0
	global_load_lds_dwordx4 v[138:139], off
	v_lshl_add_u64 v[138:139], v[198:199], 0, s[48:49]
	s_mov_b32 m0, s16
	s_nop 0
	global_load_lds_dwordx4 v[138:139], off
	v_lshl_add_u64 v[138:139], v[230:231], 0, s[48:49]
	s_mov_b32 m0, s17
	s_nop 0
	global_load_lds_dwordx4 v[138:139], off
	s_waitcnt vmcnt(8)
	s_waitcnt lgkmcnt(0)
	s_setprio 1
	s_barrier
	v_mfma_f32_16x16x32_bf16 v[60:63], v[146:149], v[184:187], v[60:63]
	v_mfma_f32_16x16x32_bf16 v[56:59], v[154:157], v[184:187], v[56:59]
	v_mfma_f32_16x16x32_bf16 v[52:55], v[146:149], v[192:195], v[52:55]
	v_mfma_f32_16x16x32_bf16 v[44:47], v[154:157], v[192:195], v[44:47]
	v_mfma_f32_16x16x32_bf16 v[36:39], v[146:149], v[214:217], v[36:39]
	v_mfma_f32_16x16x32_bf16 v[28:31], v[154:157], v[214:217], v[28:31]
	v_mfma_f32_16x16x32_bf16 v[20:23], v[146:149], v[222:225], v[20:23]
	v_mfma_f32_16x16x32_bf16 v[12:15], v[154:157], v[222:225], v[12:15]
	v_mfma_f32_16x16x32_bf16 v[60:63], v[150:153], v[188:191], v[60:63]
	v_mfma_f32_16x16x32_bf16 v[56:59], v[158:161], v[188:191], v[56:59]
	v_mfma_f32_16x16x32_bf16 v[52:55], v[150:153], v[210:213], v[52:55]
	v_mfma_f32_16x16x32_bf16 v[44:47], v[158:161], v[210:213], v[44:47]
	v_mfma_f32_16x16x32_bf16 v[36:39], v[150:153], v[218:221], v[36:39]
	v_mfma_f32_16x16x32_bf16 v[28:31], v[158:161], v[218:221], v[28:31]
	v_mfma_f32_16x16x32_bf16 v[20:23], v[150:153], v[226:229], v[20:23]
	v_mfma_f32_16x16x32_bf16 v[12:15], v[158:161], v[226:229], v[12:15]
	s_setprio 0
	s_setprio 1
	v_mfma_f32_16x16x32_bf16 v[48:51], v[162:165], v[184:187], v[48:51]
	v_mfma_f32_16x16x32_bf16 v[40:43], v[170:173], v[184:187], v[40:43]
	v_mfma_f32_16x16x32_bf16 v[32:35], v[162:165], v[192:195], v[32:35]
	v_mfma_f32_16x16x32_bf16 v[24:27], v[170:173], v[192:195], v[24:27]
	v_mfma_f32_16x16x32_bf16 v[16:19], v[162:165], v[214:217], v[16:19]
	v_mfma_f32_16x16x32_bf16 v[8:11], v[170:173], v[214:217], v[8:11]
	v_mfma_f32_16x16x32_bf16 v[4:7], v[162:165], v[222:225], v[4:7]
	v_mfma_f32_16x16x32_bf16 v[0:3], v[170:173], v[222:225], v[0:3]
	v_mfma_f32_16x16x32_bf16 v[48:51], v[166:169], v[188:191], v[48:51]
	v_mfma_f32_16x16x32_bf16 v[40:43], v[180:183], v[188:191], v[40:43]
	v_mfma_f32_16x16x32_bf16 v[32:35], v[166:169], v[210:213], v[32:35]
	v_mfma_f32_16x16x32_bf16 v[24:27], v[180:183], v[210:213], v[24:27]
	v_mfma_f32_16x16x32_bf16 v[16:19], v[166:169], v[218:221], v[16:19]
	v_mfma_f32_16x16x32_bf16 v[8:11], v[180:183], v[218:221], v[8:11]
	v_mfma_f32_16x16x32_bf16 v[4:7], v[166:169], v[226:229], v[4:7]
	v_mfma_f32_16x16x32_bf16 v[0:3], v[180:183], v[226:229], v[0:3]
	s_barrier
	s_setprio 0
	s_add_i32 s30, s30, 2
	s_add_u32 s82, s82, 0x100
	s_addc_u32 s83, s83, 0
	s_add_u32 s28, s28, 0x100
	s_addc_u32 s29, s29, 0
	s_cmp_gt_u32 s30, 29
	s_cbranch_scc0 .LBB0_297
	s_and_b64 vcc, exec, s[60:61]
	s_cbranch_vccz .LBB0_300
	s_barrier

; #define PG8_STAGE(bufoff, gbase, voff) do { _Pragma("unroll") for (int _i = 0; _i < 2; ++_i) \
;         __builtin_amdgcn_global_load_lds((const unsigned*)((const char*)(gbase) + (voff)[_i]), (LAS unsigned*)(lds + (bufoff) + ldsw + _i * 8192), 16, 0, 0); } while (0)
; #define PG8_LDA(dst, b, h) do { _Pragma("unroll") for (int m = 0; m < 4; ++m) _Pragma("unroll") for (int k = 0; k < 2; ++k) dst[m][k] = *(const LAS bf16x8*)(lds + PG8_SA(b, h) + aoff + m * 2048 + k * 1024); } while (0)
; #define PG8_MMA(ai, bj, At, Bt) do { __builtin_amdgcn_s_setprio(1); _Pragma("unroll") for (int m = 0; m < 4; ++m) _Pragma("unroll") for (int n = 0; n < 2; ++n) _Pragma("unroll") for (int k = 0; k < 2; ++k) \
;         acc[ai][bj][m][n] = __builtin_amdgcn_mfma_f32_16x16x32_bf16(Bt[n][k], At[m][k], acc[ai][bj][m][n], 0, 0, 0); __builtin_amdgcn_s_setprio(0); } while (0)
; #define PG8_WAIT_V(n) asm volatile("s_waitcnt vmcnt(" #n ")" ::: "memory")
; #define PG8_WAIT_L(n) asm volatile("s_waitcnt lgkmcnt(" #n ")" ::: "memory")
; #define PG8_BAR __builtin_amdgcn_s_barrier()
; #define PG8_SCHED __builtin_amdgcn_sched_barrier(0)
; template <class Epi>
; __device__ __forceinline__ void gemm_phase(LAS unsigned char* lds, const GemmD g, const Epi& E, int G, int c) {
;     ...
;             PG8_WAIT_V(8); PG8_WAIT_L(0); PG8_BAR; PG8_MMA(0, 0, At, B0); PG8_MMA(0, 1, At, B1); PG8_BAR; PG8_SCHED;
;             PG8_LDA(At, 0, 1); PG8_STAGE(PG8_SB(0, 0), b2, voffB); PG8_STAGE(PG8_SB(0, 1), b2 + hstepB, voffB); PG8_STAGE(PG8_SA(0, 0), a2, voffA);
;             PG8_WAIT_V(8); PG8_WAIT_L(0); PG8_BAR; PG8_MMA(1, 0, At, B0); PG8_MMA(1, 1, At, B1); PG8_BAR; PG8_SCHED;
.Lrw_S_0_d:
	s_waitcnt lgkmcnt(0)
	s_setprio 1
	s_barrier
	v_mfma_f32_16x16x32_bf16 v[124:127], v[128:131], v[166:169], v[124:127]
	v_mfma_f32_16x16x32_bf16 v[120:123], v[142:145], v[166:169], v[120:123]
	v_mfma_f32_16x16x32_bf16 v[108:111], v[128:131], v[184:187], v[108:111]
	v_mfma_f32_16x16x32_bf16 v[104:107], v[142:145], v[184:187], v[104:107]
	v_mfma_f32_16x16x32_bf16 v[92:95], v[128:131], v[192:195], v[92:95]
	v_mfma_f32_16x16x32_bf16 v[88:91], v[142:145], v[192:195], v[88:91]
	v_mfma_f32_16x16x32_bf16 v[76:79], v[128:131], v[214:217], v[76:79]
	v_mfma_f32_16x16x32_bf16 v[72:75], v[142:145], v[214:217], v[72:75]
	v_mfma_f32_16x16x32_bf16 v[124:127], v[138:141], v[180:183], v[124:127]
	v_mfma_f32_16x16x32_bf16 v[120:123], v[146:149], v[180:183], v[120:123]
	v_mfma_f32_16x16x32_bf16 v[108:111], v[138:141], v[188:191], v[108:111]
	v_mfma_f32_16x16x32_bf16 v[104:107], v[146:149], v[188:191], v[104:107]
	v_mfma_f32_16x16x32_bf16 v[92:95], v[138:141], v[210:213], v[92:95]
	v_mfma_f32_16x16x32_bf16 v[88:91], v[146:149], v[210:213], v[88:91]
	v_mfma_f32_16x16x32_bf16 v[76:79], v[138:141], v[218:221], v[76:79]
	v_mfma_f32_16x16x32_bf16 v[72:75], v[146:149], v[218:221], v[72:75]
	s_setprio 0
	s_setprio 1
	v_mfma_f32_16x16x32_bf16 v[116:119], v[150:153], v[166:169], v[116:119]
	v_mfma_f32_16x16x32_bf16 v[112:115], v[158:161], v[166:169], v[112:115]
	v_mfma_f32_16x16x32_bf16 v[100:103], v[150:153], v[184:187], v[100:103]
	v_mfma_f32_16x16x32_bf16 v[96:99], v[158:161], v[184:187], v[96:99]
	v_mfma_f32_16x16x32_bf16 v[84:87], v[150:153], v[192:195], v[84:87]
	v_mfma_f32_16x16x32_bf16 v[80:83], v[158:161], v[192:195], v[80:83]
	v_mfma_f32_16x16x32_bf16 v[68:71], v[150:153], v[214:217], v[68:71]
	v_mfma_f32_16x16x32_bf16 v[64:67], v[158:161], v[214:217], v[64:67]
	v_mfma_f32_16x16x32_bf16 v[116:119], v[154:157], v[180:183], v[116:119]
	v_mfma_f32_16x16x32_bf16 v[112:115], v[162:165], v[180:183], v[112:115]
	v_mfma_f32_16x16x32_bf16 v[100:103], v[154:157], v[188:191], v[100:103]
	v_mfma_f32_16x16x32_bf16 v[96:99], v[162:165], v[188:191], v[96:99]
	v_mfma_f32_16x16x32_bf16 v[84:87], v[154:157], v[210:213], v[84:87]
	v_mfma_f32_16x16x32_bf16 v[80:83], v[162:165], v[210:213], v[80:83]
	v_mfma_f32_16x16x32_bf16 v[68:71], v[154:157], v[218:221], v[68:71]
	v_mfma_f32_16x16x32_bf16 v[64:67], v[162:165], v[218:221], v[64:67]
	s_barrier
	s_setprio 0
	s_mov_b32 m0, s38
	v_lshl_add_u64 v[174:175], s[94:95], 0, v[178:179]
	ds_read_b128 v[166:169], v173 offset:16384
	ds_read_b128 v[180:183], v173 offset:17408
	ds_read_b128 v[184:187], v173 offset:18432
	ds_read_b128 v[188:191], v173 offset:19456
	ds_read_b128 v[192:195], v173 offset:20480
	ds_read_b128 v[210:213], v173 offset:21504
	ds_read_b128 v[214:217], v173 offset:22528
	ds_read_b128 v[218:221], v173 offset:23552
	global_load_lds_dwordx4 v[174:175], off
	v_lshl_add_u64 v[198:199], s[94:95], 0, v[132:133]
	s_mov_b32 m0, s29
	v_lshl_add_u64 v[222:223], s[96:97], 0, v[178:179]
	global_load_lds_dwordx4 v[198:199], off
	s_mov_b32 m0, s33
	v_lshl_add_u64 v[224:225], s[92:93], 0, v[134:135]
	global_load_lds_dwordx4 v[222:223], off
	v_lshl_add_u64 v[222:223], s[96:97], 0, v[132:133]
	s_mov_b32 m0, s31
	s_nop 0
	global_load_lds_dwordx4 v[222:223], off
	v_lshl_add_u64 v[222:223], s[92:93], 0, v[136:137]
	s_mov_b32 m0, s30
	s_nop 0
	global_load_lds_dwordx4 v[222:223], off
	s_mov_b32 m0, s35
	s_nop 0
	global_load_lds_dwordx4 v[224:225], off
	s_cmp_lg_u32 s99, 0
	s_cbranch_scc1 .Lrw_S_1_r
	s_waitcnt vmcnt(8)
	s_branch .Lrw_S_1_d

; #define PG8_STAGE(bufoff, gbase, voff) do { _Pragma("unroll") for (int _i = 0; _i < 2; ++_i) \
;         __builtin_amdgcn_global_load_lds((const unsigned*)((const char*)(gbase) + (voff)[_i]), (LAS unsigned*)(lds + (bufoff) + ldsw + _i * 8192), 16, 0, 0); } while (0)
; #define PG8_LDA(dst, b, h) do { _Pragma("unroll") for (int m = 0; m < 4; ++m) _Pragma("unroll") for (int k = 0; k < 2; ++k) dst[m][k] = *(const LAS bf16x8*)(lds + PG8_SA(b, h) + aoff + m * 2048 + k * 1024); } while (0)
; #define PG8_LDB(dst, b, h) do { _Pragma("unroll") for (int n = 0; n < 2; ++n) _Pragma("unroll") for (int k = 0; k < 2; ++k) dst[n][k] = *(const LAS bf16x8*)(lds + PG8_SB(b, h) + boff + n * 2048 + k * 1024); } while (0)
; #define PG8_MMA(ai, bj, At, Bt) do { __builtin_amdgcn_s_setprio(1); _Pragma("unroll") for (int m = 0; m < 4; ++m) _Pragma("unroll") for (int n = 0; n < 2; ++n) _Pragma("unroll") for (int k = 0; k < 2; ++k) \
;         acc[ai][bj][m][n] = __builtin_amdgcn_mfma_f32_16x16x32_bf16(Bt[n][k], At[m][k], acc[ai][bj][m][n], 0, 0, 0); __builtin_amdgcn_s_setprio(0); } while (0)
; #define PG8_WAIT_V(n) asm volatile("s_waitcnt vmcnt(" #n ")" ::: "memory")
; #define PG8_WAIT_L(n) asm volatile("s_waitcnt lgkmcnt(" #n ")" ::: "memory")
; #define PG8_BAR __builtin_amdgcn_s_barrier()
; #define PG8_SCHED __builtin_amdgcn_sched_barrier(0)
; template <class Epi>
; __device__ __forceinline__ void gemm_phase(LAS unsigned char* lds, const GemmD g, const Epi& E, int G, int c) {
;     ...
;             PG8_WAIT_V(8); PG8_WAIT_L(0); PG8_BAR; PG8_MMA(1, 0, At, B0); PG8_MMA(1, 1, At, B1); PG8_BAR; PG8_SCHED;
;             PG8_LDB(B0, 1, 0); PG8_LDB(B1, 1, 1); PG8_SCHED; PG8_LDA(At, 1, 0); PG8_STAGE(PG8_SA(0, 1), a2 + hstepA, voffA);
;             PG8_WAIT_V(8); PG8_WAIT_L(0); PG8_BAR; PG8_MMA(0, 0, At, B0); PG8_MMA(0, 1, At, B1); PG8_BAR; PG8_SCHED;
.Lrw_S_1_d:
	s_waitcnt lgkmcnt(0)
	s_setprio 1
	s_barrier
	v_mfma_f32_16x16x32_bf16 v[60:63], v[128:131], v[166:169], v[60:63]
	v_mfma_f32_16x16x32_bf16 v[56:59], v[142:145], v[166:169], v[56:59]
	v_mfma_f32_16x16x32_bf16 v[44:47], v[128:131], v[184:187], v[44:47]
	v_mfma_f32_16x16x32_bf16 v[40:43], v[142:145], v[184:187], v[40:43]
	v_mfma_f32_16x16x32_bf16 v[28:31], v[128:131], v[192:195], v[28:31]
	v_mfma_f32_16x16x32_bf16 v[24:27], v[142:145], v[192:195], v[24:27]
	v_mfma_f32_16x16x32_bf16 v[12:15], v[128:131], v[214:217], v[12:15]
	v_mfma_f32_16x16x32_bf16 v[8:11], v[142:145], v[214:217], v[8:11]
	v_mfma_f32_16x16x32_bf16 v[60:63], v[138:141], v[180:183], v[60:63]
	v_mfma_f32_16x16x32_bf16 v[56:59], v[146:149], v[180:183], v[56:59]
	v_mfma_f32_16x16x32_bf16 v[44:47], v[138:141], v[188:191], v[44:47]
	v_mfma_f32_16x16x32_bf16 v[40:43], v[146:149], v[188:191], v[40:43]
	v_mfma_f32_16x16x32_bf16 v[28:31], v[138:141], v[210:213], v[28:31]
	v_mfma_f32_16x16x32_bf16 v[24:27], v[146:149], v[210:213], v[24:27]
	v_mfma_f32_16x16x32_bf16 v[12:15], v[138:141], v[218:221], v[12:15]
	v_mfma_f32_16x16x32_bf16 v[8:11], v[146:149], v[218:221], v[8:11]
	s_setprio 0
	s_setprio 1
	v_mfma_f32_16x16x32_bf16 v[52:55], v[150:153], v[166:169], v[52:55]
	v_mfma_f32_16x16x32_bf16 v[48:51], v[158:161], v[166:169], v[48:51]
	v_mfma_f32_16x16x32_bf16 v[36:39], v[150:153], v[184:187], v[36:39]
	v_mfma_f32_16x16x32_bf16 v[32:35], v[158:161], v[184:187], v[32:35]
	v_mfma_f32_16x16x32_bf16 v[20:23], v[150:153], v[192:195], v[20:23]
	v_mfma_f32_16x16x32_bf16 v[16:19], v[158:161], v[192:195], v[16:19]
	v_mfma_f32_16x16x32_bf16 v[4:7], v[150:153], v[214:217], v[4:7]
	v_mfma_f32_16x16x32_bf16 v[0:3], v[158:161], v[214:217], v[0:3]
	v_mfma_f32_16x16x32_bf16 v[52:55], v[154:157], v[180:183], v[52:55]
	v_mfma_f32_16x16x32_bf16 v[48:51], v[162:165], v[180:183], v[48:51]
	v_mfma_f32_16x16x32_bf16 v[36:39], v[154:157], v[188:191], v[36:39]
	v_mfma_f32_16x16x32_bf16 v[32:35], v[162:165], v[188:191], v[32:35]
	v_mfma_f32_16x16x32_bf16 v[20:23], v[154:157], v[210:213], v[20:23]
	v_mfma_f32_16x16x32_bf16 v[16:19], v[162:165], v[210:213], v[16:19]
	v_mfma_f32_16x16x32_bf16 v[4:7], v[154:157], v[218:221], v[4:7]
	v_mfma_f32_16x16x32_bf16 v[0:3], v[162:165], v[218:221], v[0:3]
	s_barrier
	s_setprio 0
	v_add_u32_e32 v146, s28, v171
	v_add_u32_e32 v162, s27, v171
	ds_read_b128 v[128:131], v146
	ds_read_b128 v[138:141], v146 offset:1024
	ds_read_b128 v[142:145], v146 offset:2048
	ds_read_b128 v[146:149], v146 offset:3072
	ds_read_b128 v[150:153], v162
	ds_read_b128 v[154:157], v162 offset:1024
	ds_read_b128 v[158:161], v162 offset:2048
	ds_read_b128 v[162:165], v162 offset:3072
	s_mov_b32 m0, s36
	v_lshl_add_u64 v[226:227], vcc, 0, v[136:137]
	ds_read_b128 v[166:169], v173 offset:32768
	ds_read_b128 v[180:183], v173 offset:33792
	ds_read_b128 v[184:187], v173 offset:34816
	ds_read_b128 v[188:191], v173 offset:35840
	ds_read_b128 v[192:195], v173 offset:36864
	ds_read_b128 v[210:213], v173 offset:37888
	ds_read_b128 v[214:217], v173 offset:38912
	ds_read_b128 v[218:221], v173 offset:39936
	global_load_lds_dwordx4 v[226:227], off
	v_lshl_add_u64 v[226:227], vcc, 0, v[134:135]
	s_mov_b32 m0, s9
	s_nop 0
	global_load_lds_dwordx4 v[226:227], off
	s_waitcnt vmcnt(8)
	s_waitcnt lgkmcnt(0)
	s_setprio 1
	s_barrier
	v_mfma_f32_16x16x32_bf16 v[124:127], v[128:131], v[166:169], v[124:127]
	v_mfma_f32_16x16x32_bf16 v[120:123], v[142:145], v[166:169], v[120:123]
	v_mfma_f32_16x16x32_bf16 v[108:111], v[128:131], v[184:187], v[108:111]
	v_mfma_f32_16x16x32_bf16 v[104:107], v[142:145], v[184:187], v[104:107]
	v_mfma_f32_16x16x32_bf16 v[92:95], v[128:131], v[192:195], v[92:95]
	v_mfma_f32_16x16x32_bf16 v[88:91], v[142:145], v[192:195], v[88:91]
	v_mfma_f32_16x16x32_bf16 v[76:79], v[128:131], v[214:217], v[76:79]
	v_mfma_f32_16x16x32_bf16 v[72:75], v[142:145], v[214:217], v[72:75]
	v_mfma_f32_16x16x32_bf16 v[124:127], v[138:141], v[180:183], v[124:127]
	v_mfma_f32_16x16x32_bf16 v[120:123], v[146:149], v[180:183], v[120:123]
	v_mfma_f32_16x16x32_bf16 v[108:111], v[138:141], v[188:191], v[108:111]
	v_mfma_f32_16x16x32_bf16 v[104:107], v[146:149], v[188:191], v[104:107]
	v_mfma_f32_16x16x32_bf16 v[92:95], v[138:141], v[210:213], v[92:95]
	v_mfma_f32_16x16x32_bf16 v[88:91], v[146:149], v[210:213], v[88:91]
	v_mfma_f32_16x16x32_bf16 v[76:79], v[138:141], v[218:221], v[76:79]
	v_mfma_f32_16x16x32_bf16 v[72:75], v[146:149], v[218:221], v[72:75]
	s_setprio 0
	s_setprio 1
	v_mfma_f32_16x16x32_bf16 v[116:119], v[150:153], v[166:169], v[116:119]
	v_mfma_f32_16x16x32_bf16 v[112:115], v[158:161], v[166:169], v[112:115]
	v_mfma_f32_16x16x32_bf16 v[100:103], v[150:153], v[184:187], v[100:103]
	v_mfma_f32_16x16x32_bf16 v[96:99], v[158:161], v[184:187], v[96:99]
	v_mfma_f32_16x16x32_bf16 v[84:87], v[150:153], v[192:195], v[84:87]
	v_mfma_f32_16x16x32_bf16 v[80:83], v[158:161], v[192:195], v[80:83]
	v_mfma_f32_16x16x32_bf16 v[68:71], v[150:153], v[214:217], v[68:71]
	v_mfma_f32_16x16x32_bf16 v[64:67], v[158:161], v[214:217], v[64:67]
	v_mfma_f32_16x16x32_bf16 v[116:119], v[154:157], v[180:183], v[116:119]
	v_mfma_f32_16x16x32_bf16 v[112:115], v[162:165], v[180:183], v[112:115]
	v_mfma_f32_16x16x32_bf16 v[100:103], v[154:157], v[188:191], v[100:103]
	v_mfma_f32_16x16x32_bf16 v[96:99], v[162:165], v[188:191], v[96:99]
	v_mfma_f32_16x16x32_bf16 v[84:87], v[154:157], v[210:213], v[84:87]
	v_mfma_f32_16x16x32_bf16 v[80:83], v[162:165], v[210:213], v[80:83]
	v_mfma_f32_16x16x32_bf16 v[68:71], v[154:157], v[218:221], v[68:71]
	v_mfma_f32_16x16x32_bf16 v[64:67], v[162:165], v[218:221], v[64:67]
	s_barrier
; #define PG8_STAGE(bufoff, gbase, voff) do { _Pragma("unroll") for (int _i = 0; _i < 2; ++_i) \
;         __builtin_amdgcn_global_load_lds((const unsigned*)((const char*)(gbase) + (voff)[_i]), (LAS unsigned*)(lds + (bufoff) + ldsw + _i * 8192), 16, 0, 0); } while (0)
; #define PG8_LDA(dst, b, h) do { _Pragma("unroll") for (int m = 0; m < 4; ++m) _Pragma("unroll") for (int k = 0; k < 2; ++k) dst[m][k] = *(const LAS bf16x8*)(lds + PG8_SA(b, h) + aoff + m * 2048 + k * 1024); } while (0)
; #define PG8_MMA(ai, bj, At, Bt) do { __builtin_amdgcn_s_setprio(1); _Pragma("unroll") for (int m = 0; m < 4; ++m) _Pragma("unroll") for (int n = 0; n < 2; ++n) _Pragma("unroll") for (int k = 0; k < 2; ++k) \
;         acc[ai][bj][m][n] = __builtin_amdgcn_mfma_f32_16x16x32_bf16(Bt[n][k], At[m][k], acc[ai][bj][m][n], 0, 0, 0); __builtin_amdgcn_s_setprio(0); } while (0)
; #define PG8_WAIT_V(n) asm volatile("s_waitcnt vmcnt(" #n ")" ::: "memory")
; #define PG8_WAIT_L(n) asm volatile("s_waitcnt lgkmcnt(" #n ")" ::: "memory")
; #define PG8_BAR __builtin_amdgcn_s_barrier()
; #define PG8_SCHED __builtin_amdgcn_sched_barrier(0)
; template <class Epi>
; __device__ __forceinline__ void gemm_phase(LAS unsigned char* lds, const GemmD g, const Epi& E, int G, int c) {
;     ...
;             PG8_LDA(At, 1, 1); PG8_STAGE(PG8_SB(1, 0), b3, voffB); PG8_STAGE(PG8_SB(1, 1), b3 + hstepB, voffB); PG8_STAGE(PG8_SA(1, 0), a3, voffA);
;             PG8_WAIT_V(8); PG8_WAIT_L(0); PG8_BAR; PG8_MMA(1, 0, At, B0); PG8_MMA(1, 1, At, B1); PG8_BAR; PG8_SCHED;
;         }
;         if (wr == 0) PG8_BAR;
	s_setprio 0
	s_mov_b32 m0, s19
	v_lshl_add_u64 v[174:175], v[174:175], 0, s[48:49]
	ds_read_b128 v[166:169], v173 offset:49152
	ds_read_b128 v[180:183], v173 offset:50176
	ds_read_b128 v[184:187], v173 offset:51200
	ds_read_b128 v[188:191], v173 offset:52224
	ds_read_b128 v[192:195], v173 offset:53248
	ds_read_b128 v[210:213], v173 offset:54272
	ds_read_b128 v[214:217], v173 offset:55296
	ds_read_b128 v[218:221], v173 offset:56320
	global_load_lds_dwordx4 v[174:175], off
	v_lshl_add_u64 v[174:175], v[198:199], 0, s[48:49]
	s_mov_b32 m0, s17
	s_nop 0
	global_load_lds_dwordx4 v[174:175], off
	v_lshl_add_u64 v[174:175], s[90:91], 0, v[178:179]
	s_mov_b32 m0, s50
	s_nop 0
	global_load_lds_dwordx4 v[174:175], off
	v_lshl_add_u64 v[174:175], s[90:91], 0, v[132:133]
	s_mov_b32 m0, s39
	s_nop 0
	global_load_lds_dwordx4 v[174:175], off
	v_lshl_add_u64 v[174:175], v[222:223], 0, s[48:49]
	s_mov_b32 m0, s10
	s_nop 0
	global_load_lds_dwordx4 v[174:175], off
	v_lshl_add_u64 v[174:175], v[224:225], 0, s[48:49]
	s_mov_b32 m0, s11
	s_nop 0
	global_load_lds_dwordx4 v[174:175], off
	s_waitcnt vmcnt(8)
	s_waitcnt lgkmcnt(0)
	s_setprio 1
	s_barrier
	v_mfma_f32_16x16x32_bf16 v[60:63], v[128:131], v[166:169], v[60:63]
	v_mfma_f32_16x16x32_bf16 v[56:59], v[142:145], v[166:169], v[56:59]
	v_mfma_f32_16x16x32_bf16 v[44:47], v[128:131], v[184:187], v[44:47]
	v_mfma_f32_16x16x32_bf16 v[40:43], v[142:145], v[184:187], v[40:43]
	v_mfma_f32_16x16x32_bf16 v[28:31], v[128:131], v[192:195], v[28:31]
	v_mfma_f32_16x16x32_bf16 v[24:27], v[142:145], v[192:195], v[24:27]
	v_mfma_f32_16x16x32_bf16 v[12:15], v[128:131], v[214:217], v[12:15]
	v_mfma_f32_16x16x32_bf16 v[8:11], v[142:145], v[214:217], v[8:11]
	v_mfma_f32_16x16x32_bf16 v[60:63], v[138:141], v[180:183], v[60:63]
	v_mfma_f32_16x16x32_bf16 v[56:59], v[146:149], v[180:183], v[56:59]
	v_mfma_f32_16x16x32_bf16 v[44:47], v[138:141], v[188:191], v[44:47]
	v_mfma_f32_16x16x32_bf16 v[40:43], v[146:149], v[188:191], v[40:43]
	v_mfma_f32_16x16x32_bf16 v[28:31], v[138:141], v[210:213], v[28:31]
	v_mfma_f32_16x16x32_bf16 v[24:27], v[146:149], v[210:213], v[24:27]
	v_mfma_f32_16x16x32_bf16 v[12:15], v[138:141], v[218:221], v[12:15]
	v_mfma_f32_16x16x32_bf16 v[8:11], v[146:149], v[218:221], v[8:11]
	s_setprio 0
	s_setprio 1
	v_mfma_f32_16x16x32_bf16 v[52:55], v[150:153], v[166:169], v[52:55]
	v_mfma_f32_16x16x32_bf16 v[48:51], v[158:161], v[166:169], v[48:51]
	v_mfma_f32_16x16x32_bf16 v[36:39], v[150:153], v[184:187], v[36:39]
	v_mfma_f32_16x16x32_bf16 v[32:35], v[158:161], v[184:187], v[32:35]
	v_mfma_f32_16x16x32_bf16 v[20:23], v[150:153], v[192:195], v[20:23]
	v_mfma_f32_16x16x32_bf16 v[16:19], v[158:161], v[192:195], v[16:19]
	v_mfma_f32_16x16x32_bf16 v[4:7], v[150:153], v[214:217], v[4:7]
	v_mfma_f32_16x16x32_bf16 v[0:3], v[158:161], v[214:217], v[0:3]
	v_mfma_f32_16x16x32_bf16 v[52:55], v[154:157], v[180:183], v[52:55]
	v_mfma_f32_16x16x32_bf16 v[48:51], v[162:165], v[180:183], v[48:51]
	v_mfma_f32_16x16x32_bf16 v[36:39], v[154:157], v[188:191], v[36:39]
	v_mfma_f32_16x16x32_bf16 v[32:35], v[162:165], v[188:191], v[32:35]
	v_mfma_f32_16x16x32_bf16 v[20:23], v[154:157], v[210:213], v[20:23]
	v_mfma_f32_16x16x32_bf16 v[16:19], v[162:165], v[210:213], v[16:19]
	v_mfma_f32_16x16x32_bf16 v[4:7], v[154:157], v[218:221], v[4:7]
	v_mfma_f32_16x16x32_bf16 v[0:3], v[162:165], v[218:221], v[0:3]
	s_barrier
	s_setprio 0
	s_movk_i32 s4, 0x100
	s_andn2_b64 vcc, exec, s[88:89]
	s_mov_b64 s[90:91], -1
	s_mov_b64 s[88:89], 0
	s_cbranch_vccz .LBB0_329
	s_and_b64 vcc, exec, s[62:63]
	s_cbranch_vccz .LBB0_332
	s_barrier

; #define PG8_STAGE(bufoff, gbase, voff) do { _Pragma("unroll") for (int _i = 0; _i < 2; ++_i) \
;         __builtin_amdgcn_global_load_lds((const unsigned*)((const char*)(gbase) + (voff)[_i]), (LAS unsigned*)(lds + (bufoff) + ldsw + _i * 8192), 16, 0, 0); } while (0)
; #define PG8_LDA(dst, b, h) do { _Pragma("unroll") for (int m = 0; m < 4; ++m) _Pragma("unroll") for (int k = 0; k < 2; ++k) dst[m][k] = *(const LAS bf16x8*)(lds + PG8_SA(b, h) + aoff + m * 2048 + k * 1024); } while (0)
; #define PG8_MMA(ai, bj, At, Bt) do { __builtin_amdgcn_s_setprio(1); _Pragma("unroll") for (int m = 0; m < 4; ++m) _Pragma("unroll") for (int n = 0; n < 2; ++n) _Pragma("unroll") for (int k = 0; k < 2; ++k) \
;         acc[ai][bj][m][n] = __builtin_amdgcn_mfma_f32_16x16x32_bf16(Bt[n][k], At[m][k], acc[ai][bj][m][n], 0, 0, 0); __builtin_amdgcn_s_setprio(0); } while (0)
; #define PG8_WAIT_V(n) asm volatile("s_waitcnt vmcnt(" #n ")" ::: "memory")
; #define PG8_WAIT_L(n) asm volatile("s_waitcnt lgkmcnt(" #n ")" ::: "memory")
; #define PG8_BAR __builtin_amdgcn_s_barrier()
; #define PG8_SCHED __builtin_amdgcn_sched_barrier(0)
; template <class Epi>
; __device__ __forceinline__ void gemm_phase(LAS unsigned char* lds, const GemmD g, const Epi& E, int G, int c) {
;     ...
;             PG8_WAIT_V(8); PG8_WAIT_L(0); PG8_BAR; PG8_MMA(0, 0, At, B0); PG8_MMA(0, 1, At, B1); PG8_BAR; PG8_SCHED;
;             PG8_LDA(At, 0, 1); PG8_STAGE(PG8_SB(0, 0), b2, voffB); PG8_STAGE(PG8_SB(0, 1), b2 + hstepB, voffB); PG8_STAGE(PG8_SA(0, 0), a2, voffA);
;             PG8_WAIT_V(8); PG8_WAIT_L(0); PG8_BAR; PG8_MMA(1, 0, At, B0); PG8_MMA(1, 1, At, B1); PG8_BAR; PG8_SCHED;
.Lrw_In_0_d:
	s_waitcnt lgkmcnt(0)
	s_setprio 1
	s_barrier
	v_mfma_f32_16x16x32_bf16 v[124:127], v[128:131], v[184:187], v[124:127]
	v_mfma_f32_16x16x32_bf16 v[120:123], v[136:139], v[184:187], v[120:123]
	v_mfma_f32_16x16x32_bf16 v[108:111], v[128:131], v[210:213], v[108:111]
	v_mfma_f32_16x16x32_bf16 v[104:107], v[136:139], v[210:213], v[104:107]
	v_mfma_f32_16x16x32_bf16 v[92:95], v[128:131], v[218:221], v[92:95]
	v_mfma_f32_16x16x32_bf16 v[88:91], v[136:139], v[218:221], v[88:91]
	v_mfma_f32_16x16x32_bf16 v[76:79], v[128:131], v[226:229], v[76:79]
	v_mfma_f32_16x16x32_bf16 v[72:75], v[136:139], v[226:229], v[72:75]
	v_mfma_f32_16x16x32_bf16 v[124:127], v[132:135], v[188:191], v[124:127]
	v_mfma_f32_16x16x32_bf16 v[120:123], v[140:143], v[188:191], v[120:123]
	v_mfma_f32_16x16x32_bf16 v[108:111], v[132:135], v[214:217], v[108:111]
	v_mfma_f32_16x16x32_bf16 v[104:107], v[140:143], v[214:217], v[104:107]
	v_mfma_f32_16x16x32_bf16 v[92:95], v[132:135], v[222:225], v[92:95]
	v_mfma_f32_16x16x32_bf16 v[88:91], v[140:143], v[222:225], v[88:91]
	v_mfma_f32_16x16x32_bf16 v[76:79], v[132:135], v[230:233], v[76:79]
	v_mfma_f32_16x16x32_bf16 v[72:75], v[140:143], v[230:233], v[72:75]
	s_setprio 0
	s_setprio 1
	v_mfma_f32_16x16x32_bf16 v[116:119], v[162:165], v[184:187], v[116:119]
	v_mfma_f32_16x16x32_bf16 v[112:115], v[170:173], v[184:187], v[112:115]
	v_mfma_f32_16x16x32_bf16 v[100:103], v[162:165], v[210:213], v[100:103]
	v_mfma_f32_16x16x32_bf16 v[96:99], v[170:173], v[210:213], v[96:99]
	v_mfma_f32_16x16x32_bf16 v[84:87], v[162:165], v[218:221], v[84:87]
	v_mfma_f32_16x16x32_bf16 v[80:83], v[170:173], v[218:221], v[80:83]
	v_mfma_f32_16x16x32_bf16 v[68:71], v[162:165], v[226:229], v[68:71]
	v_mfma_f32_16x16x32_bf16 v[64:67], v[170:173], v[226:229], v[64:67]
	v_mfma_f32_16x16x32_bf16 v[116:119], v[166:169], v[188:191], v[116:119]
	v_mfma_f32_16x16x32_bf16 v[112:115], v[180:183], v[188:191], v[112:115]
	v_mfma_f32_16x16x32_bf16 v[100:103], v[166:169], v[214:217], v[100:103]
	v_mfma_f32_16x16x32_bf16 v[96:99], v[180:183], v[214:217], v[96:99]
	v_mfma_f32_16x16x32_bf16 v[84:87], v[166:169], v[222:225], v[84:87]
	v_mfma_f32_16x16x32_bf16 v[80:83], v[180:183], v[222:225], v[80:83]
	v_mfma_f32_16x16x32_bf16 v[68:71], v[166:169], v[230:233], v[68:71]
	v_mfma_f32_16x16x32_bf16 v[64:67], v[180:183], v[230:233], v[64:67]
	s_barrier
	s_setprio 0
	s_add_i32 s28, s28, s16
	v_lshl_add_u64 v[174:175], s[80:81], 0, v[148:149]
	s_mov_b32 m0, s28
	ds_read_b128 v[184:187], v196 offset:16384
	ds_read_b128 v[188:191], v196 offset:17408
	ds_read_b128 v[210:213], v196 offset:18432
	ds_read_b128 v[214:217], v196 offset:19456
	ds_read_b128 v[218:221], v196 offset:20480
	ds_read_b128 v[222:225], v196 offset:21504
	ds_read_b128 v[226:229], v196 offset:22528
	ds_read_b128 v[230:233], v196 offset:23552
	global_load_lds_dwordx4 v[174:175], off
	s_add_i32 m0, s28, 0x2000
	s_add_u32 s28, s80, 0x80000
	v_lshl_add_u64 v[192:193], s[80:81], 0, v[144:145]
	s_addc_u32 s29, s81, 0
	s_add_i32 s31, s31, s16
	global_load_lds_dwordx4 v[192:193], off
	v_lshl_add_u64 v[198:199], s[28:29], 0, v[148:149]
	s_mov_b32 m0, s31
	v_lshl_add_u64 v[234:235], s[4:5], 0, v[146:147]
	global_load_lds_dwordx4 v[198:199], off
	v_lshl_add_u64 v[198:199], s[28:29], 0, v[144:145]
	s_add_i32 m0, s31, 0x2000
	s_nop 0
	global_load_lds_dwordx4 v[198:199], off
	v_lshl_add_u64 v[198:199], s[4:5], 0, v[150:151]
	s_mov_b32 m0, s23
	s_nop 0
	global_load_lds_dwordx4 v[198:199], off
	s_mov_b32 m0, s26
	s_nop 0
	global_load_lds_dwordx4 v[234:235], off
	s_cmp_lg_u32 s99, 0
	s_cbranch_scc1 .Lrw_In_1_r
	s_waitcnt vmcnt(8)
	s_branch .Lrw_In_1_d

; #define PG8_STAGE(bufoff, gbase, voff) do { _Pragma("unroll") for (int _i = 0; _i < 2; ++_i) \
;         __builtin_amdgcn_global_load_lds((const unsigned*)((const char*)(gbase) + (voff)[_i]), (LAS unsigned*)(lds + (bufoff) + ldsw + _i * 8192), 16, 0, 0); } while (0)
; #define PG8_LDA(dst, b, h) do { _Pragma("unroll") for (int m = 0; m < 4; ++m) _Pragma("unroll") for (int k = 0; k < 2; ++k) dst[m][k] = *(const LAS bf16x8*)(lds + PG8_SA(b, h) + aoff + m * 2048 + k * 1024); } while (0)
; #define PG8_LDB(dst, b, h) do { _Pragma("unroll") for (int n = 0; n < 2; ++n) _Pragma("unroll") for (int k = 0; k < 2; ++k) dst[n][k] = *(const LAS bf16x8*)(lds + PG8_SB(b, h) + boff + n * 2048 + k * 1024); } while (0)
; #define PG8_MMA(ai, bj, At, Bt) do { __builtin_amdgcn_s_setprio(1); _Pragma("unroll") for (int m = 0; m < 4; ++m) _Pragma("unroll") for (int n = 0; n < 2; ++n) _Pragma("unroll") for (int k = 0; k < 2; ++k) \
;         acc[ai][bj][m][n] = __builtin_amdgcn_mfma_f32_16x16x32_bf16(Bt[n][k], At[m][k], acc[ai][bj][m][n], 0, 0, 0); __builtin_amdgcn_s_setprio(0); } while (0)
; #define PG8_WAIT_V(n) asm volatile("s_waitcnt vmcnt(" #n ")" ::: "memory")
; #define PG8_WAIT_L(n) asm volatile("s_waitcnt lgkmcnt(" #n ")" ::: "memory")
; #define PG8_BAR __builtin_amdgcn_s_barrier()
; #define PG8_SCHED __builtin_amdgcn_sched_barrier(0)
; template <class Epi>
; __device__ __forceinline__ void gemm_phase(LAS unsigned char* lds, const GemmD g, const Epi& E, int G, int c) {
;     ...
;             PG8_WAIT_V(8); PG8_WAIT_L(0); PG8_BAR; PG8_MMA(1, 0, At, B0); PG8_MMA(1, 1, At, B1); PG8_BAR; PG8_SCHED;
;             PG8_LDB(B0, 1, 0); PG8_LDB(B1, 1, 1); PG8_SCHED; PG8_LDA(At, 1, 0); PG8_STAGE(PG8_SA(0, 1), a2 + hstepA, voffA);
;             PG8_WAIT_V(8); PG8_WAIT_L(0); PG8_BAR; PG8_MMA(0, 0, At, B0); PG8_MMA(0, 1, At, B1); PG8_BAR; PG8_SCHED;
.Lrw_In_1_d:
	s_waitcnt lgkmcnt(0)
	s_setprio 1
	s_barrier
	v_mfma_f32_16x16x32_bf16 v[60:63], v[128:131], v[184:187], v[60:63]
	v_mfma_f32_16x16x32_bf16 v[56:59], v[136:139], v[184:187], v[56:59]
	v_mfma_f32_16x16x32_bf16 v[44:47], v[128:131], v[210:213], v[44:47]
	v_mfma_f32_16x16x32_bf16 v[40:43], v[136:139], v[210:213], v[40:43]
	v_mfma_f32_16x16x32_bf16 v[28:31], v[128:131], v[218:221], v[28:31]
	v_mfma_f32_16x16x32_bf16 v[24:27], v[136:139], v[218:221], v[24:27]
	v_mfma_f32_16x16x32_bf16 v[12:15], v[128:131], v[226:229], v[12:15]
	v_mfma_f32_16x16x32_bf16 v[8:11], v[136:139], v[226:229], v[8:11]
	v_mfma_f32_16x16x32_bf16 v[60:63], v[132:135], v[188:191], v[60:63]
	v_mfma_f32_16x16x32_bf16 v[56:59], v[140:143], v[188:191], v[56:59]
	v_mfma_f32_16x16x32_bf16 v[44:47], v[132:135], v[214:217], v[44:47]
	v_mfma_f32_16x16x32_bf16 v[40:43], v[140:143], v[214:217], v[40:43]
	v_mfma_f32_16x16x32_bf16 v[28:31], v[132:135], v[222:225], v[28:31]
	v_mfma_f32_16x16x32_bf16 v[24:27], v[140:143], v[222:225], v[24:27]
	v_mfma_f32_16x16x32_bf16 v[12:15], v[132:135], v[230:233], v[12:15]
	v_mfma_f32_16x16x32_bf16 v[8:11], v[140:143], v[230:233], v[8:11]
	s_setprio 0
	s_setprio 1
	v_mfma_f32_16x16x32_bf16 v[52:55], v[162:165], v[184:187], v[52:55]
	v_mfma_f32_16x16x32_bf16 v[48:51], v[170:173], v[184:187], v[48:51]
	v_mfma_f32_16x16x32_bf16 v[36:39], v[162:165], v[210:213], v[36:39]
	v_mfma_f32_16x16x32_bf16 v[32:35], v[170:173], v[210:213], v[32:35]
	v_mfma_f32_16x16x32_bf16 v[20:23], v[162:165], v[218:221], v[20:23]
	v_mfma_f32_16x16x32_bf16 v[16:19], v[170:173], v[218:221], v[16:19]
	v_mfma_f32_16x16x32_bf16 v[4:7], v[162:165], v[226:229], v[4:7]
	v_mfma_f32_16x16x32_bf16 v[0:3], v[170:173], v[226:229], v[0:3]
	v_mfma_f32_16x16x32_bf16 v[52:55], v[166:169], v[188:191], v[52:55]
	v_mfma_f32_16x16x32_bf16 v[48:51], v[180:183], v[188:191], v[48:51]
	v_mfma_f32_16x16x32_bf16 v[36:39], v[166:169], v[214:217], v[36:39]
	v_mfma_f32_16x16x32_bf16 v[32:35], v[180:183], v[214:217], v[32:35]
	v_mfma_f32_16x16x32_bf16 v[20:23], v[166:169], v[222:225], v[20:23]
	v_mfma_f32_16x16x32_bf16 v[16:19], v[180:183], v[222:225], v[16:19]
	v_mfma_f32_16x16x32_bf16 v[4:7], v[166:169], v[230:233], v[4:7]
	v_mfma_f32_16x16x32_bf16 v[0:3], v[180:183], v[230:233], v[0:3]
	s_barrier
	s_setprio 0
	s_add_i32 s28, 0, 0x18000
	s_add_i32 s29, 0, 0x1c000
	v_add_u32_e32 v140, s28, v194
	v_add_u32_e32 v178, s29, v194
	ds_read_b128 v[128:131], v140
	ds_read_b128 v[132:135], v140 offset:1024
	ds_read_b128 v[136:139], v140 offset:2048
	ds_read_b128 v[140:143], v140 offset:3072
	ds_read_b128 v[162:165], v178
	ds_read_b128 v[166:169], v178 offset:1024
	ds_read_b128 v[170:173], v178 offset:2048
	ds_read_b128 v[180:183], v178 offset:3072
	s_add_u32 s4, s4, 0x80000
	s_addc_u32 s5, s5, 0
	s_mov_b32 m0, s30
	v_lshl_add_u64 v[236:237], s[4:5], 0, v[150:151]
	ds_read_b128 v[184:187], v196 offset:32768
	ds_read_b128 v[188:191], v196 offset:33792
	ds_read_b128 v[210:213], v196 offset:34816
	ds_read_b128 v[214:217], v196 offset:35840
	ds_read_b128 v[218:221], v196 offset:36864
	ds_read_b128 v[222:225], v196 offset:37888
	ds_read_b128 v[226:229], v196 offset:38912
	ds_read_b128 v[230:233], v196 offset:39936
	global_load_lds_dwordx4 v[236:237], off
	v_lshl_add_u64 v[236:237], s[4:5], 0, v[146:147]
	s_mov_b32 m0, s35
	s_nop 0
	global_load_lds_dwordx4 v[236:237], off
	s_waitcnt vmcnt(8)
	s_waitcnt lgkmcnt(0)
	s_setprio 1
	s_barrier
	v_mfma_f32_16x16x32_bf16 v[124:127], v[128:131], v[184:187], v[124:127]
	v_mfma_f32_16x16x32_bf16 v[120:123], v[136:139], v[184:187], v[120:123]
	v_mfma_f32_16x16x32_bf16 v[108:111], v[128:131], v[210:213], v[108:111]
	v_mfma_f32_16x16x32_bf16 v[104:107], v[136:139], v[210:213], v[104:107]
	v_mfma_f32_16x16x32_bf16 v[92:95], v[128:131], v[218:221], v[92:95]
	v_mfma_f32_16x16x32_bf16 v[88:91], v[136:139], v[218:221], v[88:91]
	v_mfma_f32_16x16x32_bf16 v[76:79], v[128:131], v[226:229], v[76:79]
	v_mfma_f32_16x16x32_bf16 v[72:75], v[136:139], v[226:229], v[72:75]
	v_mfma_f32_16x16x32_bf16 v[124:127], v[132:135], v[188:191], v[124:127]
	v_mfma_f32_16x16x32_bf16 v[120:123], v[140:143], v[188:191], v[120:123]
	v_mfma_f32_16x16x32_bf16 v[108:111], v[132:135], v[214:217], v[108:111]
	v_mfma_f32_16x16x32_bf16 v[104:107], v[140:143], v[214:217], v[104:107]
	v_mfma_f32_16x16x32_bf16 v[92:95], v[132:135], v[222:225], v[92:95]
	v_mfma_f32_16x16x32_bf16 v[88:91], v[140:143], v[222:225], v[88:91]
	v_mfma_f32_16x16x32_bf16 v[76:79], v[132:135], v[230:233], v[76:79]
	v_mfma_f32_16x16x32_bf16 v[72:75], v[140:143], v[230:233], v[72:75]
	s_setprio 0
	s_setprio 1
	v_mfma_f32_16x16x32_bf16 v[116:119], v[162:165], v[184:187], v[116:119]
	v_mfma_f32_16x16x32_bf16 v[112:115], v[170:173], v[184:187], v[112:115]
	v_mfma_f32_16x16x32_bf16 v[100:103], v[162:165], v[210:213], v[100:103]
	v_mfma_f32_16x16x32_bf16 v[96:99], v[170:173], v[210:213], v[96:99]
	v_mfma_f32_16x16x32_bf16 v[84:87], v[162:165], v[218:221], v[84:87]
	v_mfma_f32_16x16x32_bf16 v[80:83], v[170:173], v[218:221], v[80:83]
	v_mfma_f32_16x16x32_bf16 v[68:71], v[162:165], v[226:229], v[68:71]
	v_mfma_f32_16x16x32_bf16 v[64:67], v[170:173], v[226:229], v[64:67]
	v_mfma_f32_16x16x32_bf16 v[116:119], v[166:169], v[188:191], v[116:119]
	v_mfma_f32_16x16x32_bf16 v[112:115], v[180:183], v[188:191], v[112:115]
	v_mfma_f32_16x16x32_bf16 v[100:103], v[166:169], v[214:217], v[100:103]
	v_mfma_f32_16x16x32_bf16 v[96:99], v[180:183], v[214:217], v[96:99]
	v_mfma_f32_16x16x32_bf16 v[84:87], v[166:169], v[222:225], v[84:87]
	v_mfma_f32_16x16x32_bf16 v[80:83], v[180:183], v[222:225], v[80:83]
	v_mfma_f32_16x16x32_bf16 v[68:71], v[166:169], v[230:233], v[68:71]
	v_mfma_f32_16x16x32_bf16 v[64:67], v[180:183], v[230:233], v[64:67]
	s_barrier
; #define PG8_STAGE(bufoff, gbase, voff) do { _Pragma("unroll") for (int _i = 0; _i < 2; ++_i) \
;         __builtin_amdgcn_global_load_lds((const unsigned*)((const char*)(gbase) + (voff)[_i]), (LAS unsigned*)(lds + (bufoff) + ldsw + _i * 8192), 16, 0, 0); } while (0)
; #define PG8_LDA(dst, b, h) do { _Pragma("unroll") for (int m = 0; m < 4; ++m) _Pragma("unroll") for (int k = 0; k < 2; ++k) dst[m][k] = *(const LAS bf16x8*)(lds + PG8_SA(b, h) + aoff + m * 2048 + k * 1024); } while (0)
; #define PG8_MMA(ai, bj, At, Bt) do { __builtin_amdgcn_s_setprio(1); _Pragma("unroll") for (int m = 0; m < 4; ++m) _Pragma("unroll") for (int n = 0; n < 2; ++n) _Pragma("unroll") for (int k = 0; k < 2; ++k) \
;         acc[ai][bj][m][n] = __builtin_amdgcn_mfma_f32_16x16x32_bf16(Bt[n][k], At[m][k], acc[ai][bj][m][n], 0, 0, 0); __builtin_amdgcn_s_setprio(0); } while (0)
; #define PG8_WAIT_V(n) asm volatile("s_waitcnt vmcnt(" #n ")" ::: "memory")
; #define PG8_WAIT_L(n) asm volatile("s_waitcnt lgkmcnt(" #n ")" ::: "memory")
; #define PG8_BAR __builtin_amdgcn_s_barrier()
; #define PG8_SCHED __builtin_amdgcn_sched_barrier(0)
; template <class Epi>
; __device__ __forceinline__ void gemm_phase(LAS unsigned char* lds, const GemmD g, const Epi& E, int G, int c) {
;     ...
;             PG8_LDA(At, 1, 1); PG8_STAGE(PG8_SB(1, 0), b3, voffB); PG8_STAGE(PG8_SB(1, 1), b3 + hstepB, voffB); PG8_STAGE(PG8_SA(1, 0), a3, voffA);
;             PG8_WAIT_V(8); PG8_WAIT_L(0); PG8_BAR; PG8_MMA(1, 0, At, B0); PG8_MMA(1, 1, At, B1); PG8_BAR; PG8_SCHED;
;         }
;         if (wr == 0) PG8_BAR;
	s_setprio 0
	s_add_i32 s4, s28, s16
	v_lshl_add_u64 v[174:175], v[174:175], 0, s[48:49]
	s_mov_b32 m0, s4
	ds_read_b128 v[184:187], v196 offset:49152
	ds_read_b128 v[188:191], v196 offset:50176
	ds_read_b128 v[210:213], v196 offset:51200
	ds_read_b128 v[214:217], v196 offset:52224
	ds_read_b128 v[218:221], v196 offset:53248
	ds_read_b128 v[222:225], v196 offset:54272
	ds_read_b128 v[226:229], v196 offset:55296
	ds_read_b128 v[230:233], v196 offset:56320
	global_load_lds_dwordx4 v[174:175], off
	s_add_i32 m0, s4, 0x2000
	s_add_u32 s4, s80, 0x80080
	v_lshl_add_u64 v[174:175], v[192:193], 0, s[48:49]
	s_addc_u32 s5, s81, 0
	s_add_i32 s28, s29, s16
	global_load_lds_dwordx4 v[174:175], off
	v_lshl_add_u64 v[174:175], s[4:5], 0, v[148:149]
	s_mov_b32 m0, s28
	s_nop 0
	global_load_lds_dwordx4 v[174:175], off
	v_lshl_add_u64 v[174:175], s[4:5], 0, v[144:145]
	s_add_i32 m0, s28, 0x2000
	s_nop 0
	global_load_lds_dwordx4 v[174:175], off
	v_lshl_add_u64 v[174:175], v[198:199], 0, s[48:49]
	s_mov_b32 m0, s36
	s_nop 0
	global_load_lds_dwordx4 v[174:175], off
	v_lshl_add_u64 v[174:175], v[234:235], 0, s[48:49]
	s_mov_b32 m0, s82
	s_nop 0
	global_load_lds_dwordx4 v[174:175], off
	s_waitcnt vmcnt(8)
	s_waitcnt lgkmcnt(0)
	s_setprio 1
	s_barrier
	v_mfma_f32_16x16x32_bf16 v[60:63], v[128:131], v[184:187], v[60:63]
	v_mfma_f32_16x16x32_bf16 v[56:59], v[136:139], v[184:187], v[56:59]
	v_mfma_f32_16x16x32_bf16 v[44:47], v[128:131], v[210:213], v[44:47]
	v_mfma_f32_16x16x32_bf16 v[40:43], v[136:139], v[210:213], v[40:43]
	v_mfma_f32_16x16x32_bf16 v[28:31], v[128:131], v[218:221], v[28:31]
	v_mfma_f32_16x16x32_bf16 v[24:27], v[136:139], v[218:221], v[24:27]
	v_mfma_f32_16x16x32_bf16 v[12:15], v[128:131], v[226:229], v[12:15]
	v_mfma_f32_16x16x32_bf16 v[8:11], v[136:139], v[226:229], v[8:11]
	v_mfma_f32_16x16x32_bf16 v[60:63], v[132:135], v[188:191], v[60:63]
	v_mfma_f32_16x16x32_bf16 v[56:59], v[140:143], v[188:191], v[56:59]
	v_mfma_f32_16x16x32_bf16 v[44:47], v[132:135], v[214:217], v[44:47]
	v_mfma_f32_16x16x32_bf16 v[40:43], v[140:143], v[214:217], v[40:43]
	v_mfma_f32_16x16x32_bf16 v[28:31], v[132:135], v[222:225], v[28:31]
	v_mfma_f32_16x16x32_bf16 v[24:27], v[140:143], v[222:225], v[24:27]
	v_mfma_f32_16x16x32_bf16 v[12:15], v[132:135], v[230:233], v[12:15]
	v_mfma_f32_16x16x32_bf16 v[8:11], v[140:143], v[230:233], v[8:11]
	s_setprio 0
	s_setprio 1
	v_mfma_f32_16x16x32_bf16 v[52:55], v[162:165], v[184:187], v[52:55]
	v_mfma_f32_16x16x32_bf16 v[48:51], v[170:173], v[184:187], v[48:51]
	v_mfma_f32_16x16x32_bf16 v[36:39], v[162:165], v[210:213], v[36:39]
	v_mfma_f32_16x16x32_bf16 v[32:35], v[170:173], v[210:213], v[32:35]
	v_mfma_f32_16x16x32_bf16 v[20:23], v[162:165], v[218:221], v[20:23]
	v_mfma_f32_16x16x32_bf16 v[16:19], v[170:173], v[218:221], v[16:19]
	v_mfma_f32_16x16x32_bf16 v[4:7], v[162:165], v[226:229], v[4:7]
	v_mfma_f32_16x16x32_bf16 v[0:3], v[170:173], v[226:229], v[0:3]
	v_mfma_f32_16x16x32_bf16 v[52:55], v[166:169], v[188:191], v[52:55]
	v_mfma_f32_16x16x32_bf16 v[48:51], v[180:183], v[188:191], v[48:51]
	v_mfma_f32_16x16x32_bf16 v[36:39], v[166:169], v[214:217], v[36:39]
	v_mfma_f32_16x16x32_bf16 v[32:35], v[180:183], v[214:217], v[32:35]
	v_mfma_f32_16x16x32_bf16 v[20:23], v[166:169], v[222:225], v[20:23]
	v_mfma_f32_16x16x32_bf16 v[16:19], v[180:183], v[222:225], v[16:19]
	v_mfma_f32_16x16x32_bf16 v[4:7], v[166:169], v[230:233], v[4:7]
	v_mfma_f32_16x16x32_bf16 v[0:3], v[180:183], v[230:233], v[0:3]
	s_barrier
	s_setprio 0
	s_add_i32 s27, s27, 2
	s_add_u32 s42, s42, 0x100
	s_addc_u32 s43, s43, 0
	s_add_u32 s19, s19, 0x100
	s_addc_u32 s22, s22, 0
	s_cmp_gt_u32 s27, 29
	s_cbranch_scc0 .LBB0_394
	s_and_b64 vcc, exec, s[46:47]
	s_cbranch_vccz .LBB0_397
	s_barrier

; #define PG8_STAGE(bufoff, gbase, voff) do { _Pragma("unroll") for (int _i = 0; _i < 2; ++_i) \
;         __builtin_amdgcn_global_load_lds((const unsigned*)((const char*)(gbase) + (voff)[_i]), (LAS unsigned*)(lds + (bufoff) + ldsw + _i * 8192), 16, 0, 0); } while (0)
; #define PG8_LDA(dst, b, h) do { _Pragma("unroll") for (int m = 0; m < 4; ++m) _Pragma("unroll") for (int k = 0; k < 2; ++k) dst[m][k] = *(const LAS bf16x8*)(lds + PG8_SA(b, h) + aoff + m * 2048 + k * 1024); } while (0)
; #define PG8_MMA(ai, bj, At, Bt) do { __builtin_amdgcn_s_setprio(1); _Pragma("unroll") for (int m = 0; m < 4; ++m) _Pragma("unroll") for (int n = 0; n < 2; ++n) _Pragma("unroll") for (int k = 0; k < 2; ++k) \
;         acc[ai][bj][m][n] = __builtin_amdgcn_mfma_f32_16x16x32_bf16(Bt[n][k], At[m][k], acc[ai][bj][m][n], 0, 0, 0); __builtin_amdgcn_s_setprio(0); } while (0)
; #define PG8_WAIT_V(n) asm volatile("s_waitcnt vmcnt(" #n ")" ::: "memory")
; #define PG8_WAIT_L(n) asm volatile("s_waitcnt lgkmcnt(" #n ")" ::: "memory")
; #define PG8_BAR __builtin_amdgcn_s_barrier()
; #define PG8_SCHED __builtin_amdgcn_sched_barrier(0)
; template <class Epi>
; __device__ __forceinline__ void gemm_phase(LAS unsigned char* lds, const GemmD g, const Epi& E, int G, int c) {
;     ...
;             PG8_WAIT_V(8); PG8_WAIT_L(0); PG8_BAR; PG8_MMA(0, 0, At, B0); PG8_MMA(0, 1, At, B1); PG8_BAR; PG8_SCHED;
;             PG8_LDA(At, 0, 1); PG8_STAGE(PG8_SB(0, 0), b2, voffB); PG8_STAGE(PG8_SB(0, 1), b2 + hstepB, voffB); PG8_STAGE(PG8_SA(0, 0), a2, voffA);
;             PG8_WAIT_V(8); PG8_WAIT_L(0); PG8_BAR; PG8_MMA(1, 0, At, B0); PG8_MMA(1, 1, At, B1); PG8_BAR; PG8_SCHED;
.Lrw_Bf16_0_d:
	s_waitcnt lgkmcnt(0)
	s_setprio 1
	s_barrier
	v_mfma_f32_16x16x32_bf16 v[124:127], v[128:131], v[180:183], v[124:127]
	v_mfma_f32_16x16x32_bf16 v[120:123], v[146:149], v[180:183], v[120:123]
	v_mfma_f32_16x16x32_bf16 v[112:115], v[128:131], v[188:191], v[112:115]
	v_mfma_f32_16x16x32_bf16 v[108:111], v[146:149], v[188:191], v[108:111]
	v_mfma_f32_16x16x32_bf16 v[100:103], v[128:131], v[210:213], v[100:103]
	v_mfma_f32_16x16x32_bf16 v[92:95], v[146:149], v[210:213], v[92:95]
	v_mfma_f32_16x16x32_bf16 v[84:87], v[128:131], v[218:221], v[84:87]
	v_mfma_f32_16x16x32_bf16 v[76:79], v[146:149], v[218:221], v[76:79]
	v_mfma_f32_16x16x32_bf16 v[124:127], v[132:135], v[184:187], v[124:127]
	v_mfma_f32_16x16x32_bf16 v[120:123], v[150:153], v[184:187], v[120:123]
	v_mfma_f32_16x16x32_bf16 v[112:115], v[132:135], v[192:195], v[112:115]
	v_mfma_f32_16x16x32_bf16 v[108:111], v[150:153], v[192:195], v[108:111]
	v_mfma_f32_16x16x32_bf16 v[100:103], v[132:135], v[214:217], v[100:103]
	v_mfma_f32_16x16x32_bf16 v[92:95], v[150:153], v[214:217], v[92:95]
	v_mfma_f32_16x16x32_bf16 v[84:87], v[132:135], v[222:225], v[84:87]
	v_mfma_f32_16x16x32_bf16 v[76:79], v[150:153], v[222:225], v[76:79]
	s_setprio 0
	s_setprio 1
	v_mfma_f32_16x16x32_bf16 v[116:119], v[154:157], v[180:183], v[116:119]
	v_mfma_f32_16x16x32_bf16 v[104:107], v[166:169], v[180:183], v[104:107]
	v_mfma_f32_16x16x32_bf16 v[96:99], v[154:157], v[188:191], v[96:99]
	v_mfma_f32_16x16x32_bf16 v[88:91], v[166:169], v[188:191], v[88:91]
	v_mfma_f32_16x16x32_bf16 v[80:83], v[154:157], v[210:213], v[80:83]
	v_mfma_f32_16x16x32_bf16 v[72:75], v[166:169], v[210:213], v[72:75]
	v_mfma_f32_16x16x32_bf16 v[68:71], v[154:157], v[218:221], v[68:71]
	v_mfma_f32_16x16x32_bf16 v[64:67], v[166:169], v[218:221], v[64:67]
	v_mfma_f32_16x16x32_bf16 v[116:119], v[162:165], v[184:187], v[116:119]
	v_mfma_f32_16x16x32_bf16 v[104:107], v[170:173], v[184:187], v[104:107]
	v_mfma_f32_16x16x32_bf16 v[96:99], v[162:165], v[192:195], v[96:99]
	v_mfma_f32_16x16x32_bf16 v[88:91], v[170:173], v[192:195], v[88:91]
	v_mfma_f32_16x16x32_bf16 v[80:83], v[162:165], v[214:217], v[80:83]
	v_mfma_f32_16x16x32_bf16 v[72:75], v[170:173], v[214:217], v[72:75]
	v_mfma_f32_16x16x32_bf16 v[68:71], v[162:165], v[222:225], v[68:71]
	v_mfma_f32_16x16x32_bf16 v[64:67], v[170:173], v[222:225], v[64:67]
	s_barrier
	s_setprio 0
	s_add_i32 s38, s38, s9
	v_lshl_add_u64 v[174:175], s[76:77], 0, v[178:179]
	s_mov_b32 m0, s38
	ds_read_b128 v[180:183], v161 offset:16384
	ds_read_b128 v[184:187], v161 offset:17408
	ds_read_b128 v[188:191], v161 offset:18432
	ds_read_b128 v[192:195], v161 offset:19456
	ds_read_b128 v[210:213], v161 offset:20480
	ds_read_b128 v[214:217], v161 offset:21504
	ds_read_b128 v[218:221], v161 offset:22528
	ds_read_b128 v[222:225], v161 offset:23552
	global_load_lds_dwordx4 v[174:175], off
	s_add_i32 m0, s38, 0x2000
	s_add_u32 s38, s76, 0x80000
	v_lshl_add_u64 v[198:199], s[76:77], 0, v[136:137]
	s_addc_u32 s39, s77, 0
	s_add_i32 s50, s50, s9
	global_load_lds_dwordx4 v[198:199], off
	v_lshl_add_u64 v[226:227], s[38:39], 0, v[178:179]
	s_mov_b32 m0, s50
	v_lshl_add_u64 v[228:229], s[4:5], 0, v[138:139]
	global_load_lds_dwordx4 v[226:227], off
	v_lshl_add_u64 v[226:227], s[38:39], 0, v[136:137]
	s_add_i32 m0, s50, 0x2000
	s_nop 0
	global_load_lds_dwordx4 v[226:227], off
	v_lshl_add_u64 v[226:227], s[4:5], 0, v[140:141]
	s_mov_b32 m0, s10
	s_nop 0
	global_load_lds_dwordx4 v[226:227], off
	s_mov_b32 m0, s11
	s_nop 0
	global_load_lds_dwordx4 v[228:229], off
	s_cmp_lg_u32 s99, 0
	s_cbranch_scc1 .Lrw_Bf16_1_r
	s_waitcnt vmcnt(8)
	s_branch .Lrw_Bf16_1_d

; #define PG8_STAGE(bufoff, gbase, voff) do { _Pragma("unroll") for (int _i = 0; _i < 2; ++_i) \
;         __builtin_amdgcn_global_load_lds((const unsigned*)((const char*)(gbase) + (voff)[_i]), (LAS unsigned*)(lds + (bufoff) + ldsw + _i * 8192), 16, 0, 0); } while (0)
; #define PG8_LDA(dst, b, h) do { _Pragma("unroll") for (int m = 0; m < 4; ++m) _Pragma("unroll") for (int k = 0; k < 2; ++k) dst[m][k] = *(const LAS bf16x8*)(lds + PG8_SA(b, h) + aoff + m * 2048 + k * 1024); } while (0)
; #define PG8_LDB(dst, b, h) do { _Pragma("unroll") for (int n = 0; n < 2; ++n) _Pragma("unroll") for (int k = 0; k < 2; ++k) dst[n][k] = *(const LAS bf16x8*)(lds + PG8_SB(b, h) + boff + n * 2048 + k * 1024); } while (0)
; #define PG8_MMA(ai, bj, At, Bt) do { __builtin_amdgcn_s_setprio(1); _Pragma("unroll") for (int m = 0; m < 4; ++m) _Pragma("unroll") for (int n = 0; n < 2; ++n) _Pragma("unroll") for (int k = 0; k < 2; ++k) \
;         acc[ai][bj][m][n] = __builtin_amdgcn_mfma_f32_16x16x32_bf16(Bt[n][k], At[m][k], acc[ai][bj][m][n], 0, 0, 0); __builtin_amdgcn_s_setprio(0); } while (0)
; #define PG8_WAIT_V(n) asm volatile("s_waitcnt vmcnt(" #n ")" ::: "memory")
; #define PG8_WAIT_L(n) asm volatile("s_waitcnt lgkmcnt(" #n ")" ::: "memory")
; #define PG8_BAR __builtin_amdgcn_s_barrier()
; #define PG8_SCHED __builtin_amdgcn_sched_barrier(0)
; template <class Epi>
; __device__ __forceinline__ void gemm_phase(LAS unsigned char* lds, const GemmD g, const Epi& E, int G, int c) {
;     ...
;             PG8_WAIT_V(8); PG8_WAIT_L(0); PG8_BAR; PG8_MMA(1, 0, At, B0); PG8_MMA(1, 1, At, B1); PG8_BAR; PG8_SCHED;
;             PG8_LDB(B0, 1, 0); PG8_LDB(B1, 1, 1); PG8_SCHED; PG8_LDA(At, 1, 0); PG8_STAGE(PG8_SA(0, 1), a2 + hstepA, voffA);
;             PG8_WAIT_V(8); PG8_WAIT_L(0); PG8_BAR; PG8_MMA(0, 0, At, B0); PG8_MMA(0, 1, At, B1); PG8_BAR; PG8_SCHED;
.Lrw_Bf16_1_d:
	s_waitcnt lgkmcnt(0)
	s_setprio 1
	s_barrier
	v_mfma_f32_16x16x32_bf16 v[60:63], v[128:131], v[180:183], v[60:63]
	v_mfma_f32_16x16x32_bf16 v[56:59], v[146:149], v[180:183], v[56:59]
	v_mfma_f32_16x16x32_bf16 v[52:55], v[128:131], v[188:191], v[52:55]
	v_mfma_f32_16x16x32_bf16 v[44:47], v[146:149], v[188:191], v[44:47]
	v_mfma_f32_16x16x32_bf16 v[36:39], v[128:131], v[210:213], v[36:39]
	v_mfma_f32_16x16x32_bf16 v[28:31], v[146:149], v[210:213], v[28:31]
	v_mfma_f32_16x16x32_bf16 v[20:23], v[128:131], v[218:221], v[20:23]
	v_mfma_f32_16x16x32_bf16 v[12:15], v[146:149], v[218:221], v[12:15]
	v_mfma_f32_16x16x32_bf16 v[60:63], v[132:135], v[184:187], v[60:63]
	v_mfma_f32_16x16x32_bf16 v[56:59], v[150:153], v[184:187], v[56:59]
	v_mfma_f32_16x16x32_bf16 v[52:55], v[132:135], v[192:195], v[52:55]
	v_mfma_f32_16x16x32_bf16 v[44:47], v[150:153], v[192:195], v[44:47]
	v_mfma_f32_16x16x32_bf16 v[36:39], v[132:135], v[214:217], v[36:39]
	v_mfma_f32_16x16x32_bf16 v[28:31], v[150:153], v[214:217], v[28:31]
	v_mfma_f32_16x16x32_bf16 v[20:23], v[132:135], v[222:225], v[20:23]
	v_mfma_f32_16x16x32_bf16 v[12:15], v[150:153], v[222:225], v[12:15]
	s_setprio 0
	s_setprio 1
	v_mfma_f32_16x16x32_bf16 v[48:51], v[154:157], v[180:183], v[48:51]
	v_mfma_f32_16x16x32_bf16 v[40:43], v[166:169], v[180:183], v[40:43]
	v_mfma_f32_16x16x32_bf16 v[32:35], v[154:157], v[188:191], v[32:35]
	v_mfma_f32_16x16x32_bf16 v[24:27], v[166:169], v[188:191], v[24:27]
	v_mfma_f32_16x16x32_bf16 v[16:19], v[154:157], v[210:213], v[16:19]
	v_mfma_f32_16x16x32_bf16 v[8:11], v[166:169], v[210:213], v[8:11]
	v_mfma_f32_16x16x32_bf16 v[4:7], v[154:157], v[218:221], v[4:7]
	v_mfma_f32_16x16x32_bf16 v[0:3], v[166:169], v[218:221], v[0:3]
	v_mfma_f32_16x16x32_bf16 v[48:51], v[162:165], v[184:187], v[48:51]
	v_mfma_f32_16x16x32_bf16 v[40:43], v[170:173], v[184:187], v[40:43]
	v_mfma_f32_16x16x32_bf16 v[32:35], v[162:165], v[192:195], v[32:35]
	v_mfma_f32_16x16x32_bf16 v[24:27], v[170:173], v[192:195], v[24:27]
	v_mfma_f32_16x16x32_bf16 v[16:19], v[162:165], v[214:217], v[16:19]
	v_mfma_f32_16x16x32_bf16 v[8:11], v[170:173], v[214:217], v[8:11]
	v_mfma_f32_16x16x32_bf16 v[4:7], v[162:165], v[222:225], v[4:7]
	v_mfma_f32_16x16x32_bf16 v[0:3], v[170:173], v[222:225], v[0:3]
	s_barrier
	s_setprio 0
	s_add_i32 s38, 0, 0x18000
	s_add_i32 s39, 0, 0x1c000
	v_add_u32_e32 v150, s38, v159
	v_add_u32_e32 v170, s39, v159
	ds_read_b128 v[128:131], v150
	ds_read_b128 v[132:135], v150 offset:1024
	ds_read_b128 v[146:149], v150 offset:2048
	ds_read_b128 v[150:153], v150 offset:3072
	ds_read_b128 v[154:157], v170
	ds_read_b128 v[162:165], v170 offset:1024
	ds_read_b128 v[166:169], v170 offset:2048
	ds_read_b128 v[170:173], v170 offset:3072
	s_add_u32 s4, s4, 0x80000
	s_addc_u32 s5, s5, 0
	s_mov_b32 m0, s16
	v_lshl_add_u64 v[230:231], s[4:5], 0, v[140:141]
	ds_read_b128 v[180:183], v161 offset:32768
	ds_read_b128 v[184:187], v161 offset:33792
	ds_read_b128 v[188:191], v161 offset:34816
	ds_read_b128 v[192:195], v161 offset:35840
	ds_read_b128 v[210:213], v161 offset:36864
	ds_read_b128 v[214:217], v161 offset:37888
	ds_read_b128 v[218:221], v161 offset:38912
	ds_read_b128 v[222:225], v161 offset:39936
	global_load_lds_dwordx4 v[230:231], off
	v_lshl_add_u64 v[230:231], s[4:5], 0, v[138:139]
	s_mov_b32 m0, s17
	s_nop 0
	global_load_lds_dwordx4 v[230:231], off
	s_waitcnt vmcnt(8)
	s_waitcnt lgkmcnt(0)
	s_setprio 1
	s_barrier
	v_mfma_f32_16x16x32_bf16 v[124:127], v[128:131], v[180:183], v[124:127]
	v_mfma_f32_16x16x32_bf16 v[120:123], v[146:149], v[180:183], v[120:123]
	v_mfma_f32_16x16x32_bf16 v[112:115], v[128:131], v[188:191], v[112:115]
	v_mfma_f32_16x16x32_bf16 v[108:111], v[146:149], v[188:191], v[108:111]
	v_mfma_f32_16x16x32_bf16 v[100:103], v[128:131], v[210:213], v[100:103]
	v_mfma_f32_16x16x32_bf16 v[92:95], v[146:149], v[210:213], v[92:95]
	v_mfma_f32_16x16x32_bf16 v[84:87], v[128:131], v[218:221], v[84:87]
	v_mfma_f32_16x16x32_bf16 v[76:79], v[146:149], v[218:221], v[76:79]
	v_mfma_f32_16x16x32_bf16 v[124:127], v[132:135], v[184:187], v[124:127]
	v_mfma_f32_16x16x32_bf16 v[120:123], v[150:153], v[184:187], v[120:123]
	v_mfma_f32_16x16x32_bf16 v[112:115], v[132:135], v[192:195], v[112:115]
	v_mfma_f32_16x16x32_bf16 v[108:111], v[150:153], v[192:195], v[108:111]
	v_mfma_f32_16x16x32_bf16 v[100:103], v[132:135], v[214:217], v[100:103]
	v_mfma_f32_16x16x32_bf16 v[92:95], v[150:153], v[214:217], v[92:95]
	v_mfma_f32_16x16x32_bf16 v[84:87], v[132:135], v[222:225], v[84:87]
	v_mfma_f32_16x16x32_bf16 v[76:79], v[150:153], v[222:225], v[76:79]
	s_setprio 0
	s_setprio 1
	v_mfma_f32_16x16x32_bf16 v[116:119], v[154:157], v[180:183], v[116:119]
	v_mfma_f32_16x16x32_bf16 v[104:107], v[166:169], v[180:183], v[104:107]
	v_mfma_f32_16x16x32_bf16 v[96:99], v[154:157], v[188:191], v[96:99]
	v_mfma_f32_16x16x32_bf16 v[88:91], v[166:169], v[188:191], v[88:91]
	v_mfma_f32_16x16x32_bf16 v[80:83], v[154:157], v[210:213], v[80:83]
	v_mfma_f32_16x16x32_bf16 v[72:75], v[166:169], v[210:213], v[72:75]
	v_mfma_f32_16x16x32_bf16 v[68:71], v[154:157], v[218:221], v[68:71]
	v_mfma_f32_16x16x32_bf16 v[64:67], v[166:169], v[218:221], v[64:67]
	v_mfma_f32_16x16x32_bf16 v[116:119], v[162:165], v[184:187], v[116:119]
	v_mfma_f32_16x16x32_bf16 v[104:107], v[170:173], v[184:187], v[104:107]
	v_mfma_f32_16x16x32_bf16 v[96:99], v[162:165], v[192:195], v[96:99]
	v_mfma_f32_16x16x32_bf16 v[88:91], v[170:173], v[192:195], v[88:91]
	v_mfma_f32_16x16x32_bf16 v[80:83], v[162:165], v[214:217], v[80:83]
	v_mfma_f32_16x16x32_bf16 v[72:75], v[170:173], v[214:217], v[72:75]
	v_mfma_f32_16x16x32_bf16 v[68:71], v[162:165], v[222:225], v[68:71]
	v_mfma_f32_16x16x32_bf16 v[64:67], v[170:173], v[222:225], v[64:67]
	s_barrier
; #define PG8_STAGE(bufoff, gbase, voff) do { _Pragma("unroll") for (int _i = 0; _i < 2; ++_i) \
;         __builtin_amdgcn_global_load_lds((const unsigned*)((const char*)(gbase) + (voff)[_i]), (LAS unsigned*)(lds + (bufoff) + ldsw + _i * 8192), 16, 0, 0); } while (0)
; #define PG8_LDA(dst, b, h) do { _Pragma("unroll") for (int m = 0; m < 4; ++m) _Pragma("unroll") for (int k = 0; k < 2; ++k) dst[m][k] = *(const LAS bf16x8*)(lds + PG8_SA(b, h) + aoff + m * 2048 + k * 1024); } while (0)
; #define PG8_MMA(ai, bj, At, Bt) do { __builtin_amdgcn_s_setprio(1); _Pragma("unroll") for (int m = 0; m < 4; ++m) _Pragma("unroll") for (int n = 0; n < 2; ++n) _Pragma("unroll") for (int k = 0; k < 2; ++k) \
;         acc[ai][bj][m][n] = __builtin_amdgcn_mfma_f32_16x16x32_bf16(Bt[n][k], At[m][k], acc[ai][bj][m][n], 0, 0, 0); __builtin_amdgcn_s_setprio(0); } while (0)
; #define PG8_WAIT_V(n) asm volatile("s_waitcnt vmcnt(" #n ")" ::: "memory")
; #define PG8_WAIT_L(n) asm volatile("s_waitcnt lgkmcnt(" #n ")" ::: "memory")
; #define PG8_BAR __builtin_amdgcn_s_barrier()
; #define PG8_SCHED __builtin_amdgcn_sched_barrier(0)
; template <class Epi>
; __device__ __forceinline__ void gemm_phase(LAS unsigned char* lds, const GemmD g, const Epi& E, int G, int c) {
;     ...
;             PG8_LDA(At, 1, 1); PG8_STAGE(PG8_SB(1, 0), b3, voffB); PG8_STAGE(PG8_SB(1, 1), b3 + hstepB, voffB); PG8_STAGE(PG8_SA(1, 0), a3, voffA);
;             PG8_WAIT_V(8); PG8_WAIT_L(0); PG8_BAR; PG8_MMA(1, 0, At, B0); PG8_MMA(1, 1, At, B1); PG8_BAR; PG8_SCHED;
;         }
;         if (wr == 0) PG8_BAR;
	s_setprio 0
	s_add_i32 s4, s38, s9
	v_lshl_add_u64 v[174:175], v[174:175], 0, s[48:49]
	s_mov_b32 m0, s4
	ds_read_b128 v[180:183], v161 offset:49152
	ds_read_b128 v[184:187], v161 offset:50176
	ds_read_b128 v[188:191], v161 offset:51200
	ds_read_b128 v[192:195], v161 offset:52224
	ds_read_b128 v[210:213], v161 offset:53248
	ds_read_b128 v[214:217], v161 offset:54272
	ds_read_b128 v[218:221], v161 offset:55296
	ds_read_b128 v[222:225], v161 offset:56320
	global_load_lds_dwordx4 v[174:175], off
	s_add_i32 m0, s4, 0x2000
	s_add_u32 s4, s76, 0x80080
	v_lshl_add_u64 v[174:175], v[198:199], 0, s[48:49]
	s_addc_u32 s5, s77, 0
	s_add_i32 s38, s39, s9
	global_load_lds_dwordx4 v[174:175], off
	v_lshl_add_u64 v[174:175], s[4:5], 0, v[178:179]
	s_mov_b32 m0, s38
	s_nop 0
	global_load_lds_dwordx4 v[174:175], off
	v_lshl_add_u64 v[174:175], s[4:5], 0, v[136:137]
	s_add_i32 m0, s38, 0x2000
	s_nop 0
	global_load_lds_dwordx4 v[174:175], off
	v_lshl_add_u64 v[174:175], v[226:227], 0, s[48:49]
	s_mov_b32 m0, s19
	s_nop 0
	global_load_lds_dwordx4 v[174:175], off
	v_lshl_add_u64 v[174:175], v[228:229], 0, s[48:49]
	s_mov_b32 m0, s22
	s_nop 0
	global_load_lds_dwordx4 v[174:175], off
	s_waitcnt vmcnt(8)
	s_waitcnt lgkmcnt(0)
	s_setprio 1
	s_barrier
	v_mfma_f32_16x16x32_bf16 v[60:63], v[128:131], v[180:183], v[60:63]
	v_mfma_f32_16x16x32_bf16 v[56:59], v[146:149], v[180:183], v[56:59]
	v_mfma_f32_16x16x32_bf16 v[52:55], v[128:131], v[188:191], v[52:55]
	v_mfma_f32_16x16x32_bf16 v[44:47], v[146:149], v[188:191], v[44:47]
	v_mfma_f32_16x16x32_bf16 v[36:39], v[128:131], v[210:213], v[36:39]
	v_mfma_f32_16x16x32_bf16 v[28:31], v[146:149], v[210:213], v[28:31]
	v_mfma_f32_16x16x32_bf16 v[20:23], v[128:131], v[218:221], v[20:23]
	v_mfma_f32_16x16x32_bf16 v[12:15], v[146:149], v[218:221], v[12:15]
	v_mfma_f32_16x16x32_bf16 v[60:63], v[132:135], v[184:187], v[60:63]
	v_mfma_f32_16x16x32_bf16 v[56:59], v[150:153], v[184:187], v[56:59]
	v_mfma_f32_16x16x32_bf16 v[52:55], v[132:135], v[192:195], v[52:55]
	v_mfma_f32_16x16x32_bf16 v[44:47], v[150:153], v[192:195], v[44:47]
	v_mfma_f32_16x16x32_bf16 v[36:39], v[132:135], v[214:217], v[36:39]
	v_mfma_f32_16x16x32_bf16 v[28:31], v[150:153], v[214:217], v[28:31]
	v_mfma_f32_16x16x32_bf16 v[20:23], v[132:135], v[222:225], v[20:23]
	v_mfma_f32_16x16x32_bf16 v[12:15], v[150:153], v[222:225], v[12:15]
	s_setprio 0
	s_setprio 1
	v_mfma_f32_16x16x32_bf16 v[48:51], v[154:157], v[180:183], v[48:51]
	v_mfma_f32_16x16x32_bf16 v[40:43], v[166:169], v[180:183], v[40:43]
	v_mfma_f32_16x16x32_bf16 v[32:35], v[154:157], v[188:191], v[32:35]
	v_mfma_f32_16x16x32_bf16 v[24:27], v[166:169], v[188:191], v[24:27]
	v_mfma_f32_16x16x32_bf16 v[16:19], v[154:157], v[210:213], v[16:19]
	v_mfma_f32_16x16x32_bf16 v[8:11], v[166:169], v[210:213], v[8:11]
	v_mfma_f32_16x16x32_bf16 v[4:7], v[154:157], v[218:221], v[4:7]
	v_mfma_f32_16x16x32_bf16 v[0:3], v[166:169], v[218:221], v[0:3]
	v_mfma_f32_16x16x32_bf16 v[48:51], v[162:165], v[184:187], v[48:51]
	v_mfma_f32_16x16x32_bf16 v[40:43], v[170:173], v[184:187], v[40:43]
	v_mfma_f32_16x16x32_bf16 v[32:35], v[162:165], v[192:195], v[32:35]
	v_mfma_f32_16x16x32_bf16 v[24:27], v[170:173], v[192:195], v[24:27]
	v_mfma_f32_16x16x32_bf16 v[16:19], v[162:165], v[214:217], v[16:19]
	v_mfma_f32_16x16x32_bf16 v[8:11], v[170:173], v[214:217], v[8:11]
	v_mfma_f32_16x16x32_bf16 v[4:7], v[162:165], v[222:225], v[4:7]
	v_mfma_f32_16x16x32_bf16 v[0:3], v[170:173], v[222:225], v[0:3]
	s_barrier
	s_setprio 0
	s_add_i32 s36, s36, 2
	s_add_u32 s42, s42, 0x100
	s_addc_u32 s43, s43, 0
	s_add_u32 s33, s33, 0x100
	s_addc_u32 s35, s35, 0
	s_cmp_gt_u32 s36, 29
	s_cbranch_scc0 .LBB0_486
	s_and_b64 vcc, exec, s[46:47]
	s_cbranch_vccz .LBB0_489
	s_barrier
